# GEMM mainloop s_setprio flips removed; nt on P5 residual and P4 input streams; EpiFinal loads hoisted; local-barrier flag also requires gridDim 256
# speedup vs baseline: 1.0380x; 1.0124x over previous
.LBB0_217:
	s_or_b64 exec, exec, s[4:5]
	s_cmpk_lt_i32 s2, 0x300
	s_cselect_b64 s[6:7], -1, 0
	s_mov_b64 s[4:5], s[0:1]
	s_waitcnt vmcnt(14)
	v_mov_b32_e32 v8, v192
	s_waitcnt lgkmcnt(0)
	s_barrier
	s_waitcnt vmcnt(0)
	s_load_dwordx2 s[98:99], s[0:1], 0x80
	v_and_b32_e32 v0, 7, v192
	v_lshlrev_b32_e32 v0, 8, v0
	s_waitcnt lgkmcnt(0)
	global_load_dword v1, v0, s[98:99] sc1
	global_load_dword v2, v0, s[98:99] offset:2048 sc1
	s_waitcnt vmcnt(0)
	v_add_u32_e32 v1, v1, v2
	v_cmp_ne_u32_e32 vcc, 17, v1
	s_nop 3
	s_cmp_eq_u64 vcc, 0
	s_cselect_b32 s99, 1, 0
	s_cmpk_lg_i32 s52, 0x100
	s_cselect_b32 s99, 0, s99
	s_ashr_i32 s47, s52, 31
	s_ashr_i32 s76, s2, 31
	v_writelane_b32 v250, s6, 0
	v_readfirstlane_b32 s13, v8
	s_and_b64 vcc, exec, s[6:7]
	v_writelane_b32 v250, s7, 1
	s_cbranch_vccz .LBB0_233
	v_lshlrev_b32_e32 v0, 4, v8
	v_add_u32_e32 v1, 0x2000, v0
	v_ashrrev_i32_e32 v2, 31, v1
	v_lshrrev_b32_e32 v2, 22, v2
	v_add_u32_e32 v2, v1, v2
	v_ashrrev_i32_e32 v9, 10, v2
	v_mul_i32_i24_e32 v2, 0x400, v9
	v_sub_u32_e32 v1, v1, v2
	v_lshrrev_b32_e32 v2, 4, v1
	v_bitop3_b32 v1, v2, v1, 32 bitop3:0x6c
	v_ashrrev_i32_e32 v2, 31, v1
	v_lshrrev_b32_e32 v2, 26, v2
	v_add_u32_e32 v2, v1, v2
	v_lshlrev_b32_e32 v3, 3, v9
	s_waitcnt vmcnt(13)
	v_ashrrev_i32_e32 v10, 6, v2
	v_and_b32_e32 v3, -16, v3
	v_add_u32_e32 v3, v10, v3
	v_and_b32_e32 v4, 3, v10
	s_mov_b32 s6, 0xfffe0
	v_lshrrev_b32_e32 v5, 2, v3
	v_lshlrev_b32_e32 v6, 1, v3
	v_and_b32_e32 v2, 0xc0, v2
	v_and_or_b32 v4, v3, s6, v4
	v_and_b32_e32 v5, 4, v5
	v_and_b32_e32 v6, 24, v6
	v_sub_u32_e32 v1, v1, v2
	v_mov_b32_e32 v2, 1
	v_or3_b32 v4, v4, v5, v6
	v_lshlrev_b32_e32 v5, 5, v9
	v_ashrrev_i16_sdwa v1, v2, sext(v1) dst_sel:DWORD dst_unused:UNUSED_PAD src0_sel:DWORD src1_sel:BYTE_0
	v_and_b32_e32 v5, 32, v5
	v_bfe_i32 v11, v1, 0, 16
	v_add_lshl_u32 v1, v5, v11, 1
	v_lshl_add_u32 v128, v4, 12, v1
	v_lshl_add_u32 v130, v3, 12, v1
	v_bfe_i32 v1, v8, 27, 1
	v_lshrrev_b32_e32 v1, 22, v1
	v_add_u32_e32 v1, v0, v1
	v_and_b32_e32 v1, 0xfffffc00, v1
	s_load_dwordx2 s[4:5], s[4:5], 0x80
	v_sub_u32_e32 v0, v0, v1
	v_lshrrev_b32_e32 v1, 4, v0
	v_ashrrev_i32_e32 v3, 31, v8
	v_bitop3_b32 v0, v1, v0, 32 bitop3:0x6c
	v_lshrrev_b32_e32 v3, 26, v3
	v_ashrrev_i32_e32 v1, 31, v0
	v_add_u32_e32 v3, v8, v3
	v_lshrrev_b32_e32 v1, 26, v1
	v_ashrrev_i32_e32 v13, 6, v3
	s_waitcnt lgkmcnt(0)
	s_add_u32 s30, s4, 0xc600000
	v_add_u32_e32 v1, v0, v1
	v_lshlrev_b32_e32 v3, 3, v13
	s_addc_u32 s31, s5, 0
	v_ashrrev_i32_e32 v12, 6, v1
	v_and_b32_e32 v3, -16, v3
	s_add_u32 s34, s4, 0x100000
	v_add_u32_e32 v3, v12, v3
	v_and_b32_e32 v4, 3, v12
	s_addc_u32 s35, s5, 0
	v_and_or_b32 v4, v3, s6, v4
	s_lshr_b32 s6, s76, 29
	s_add_i32 s6, s2, s6
	s_ashr_i32 s10, s13, 6
	s_ashr_i32 s7, s6, 3
	s_and_b32 s6, s6, -8
	s_ashr_i32 s14, s13, 8
	s_lshl_b32 s36, s10, 10
	s_sub_i32 s6, s2, s6
	s_cmp_lt_i32 s6, 0
	s_movk_i32 s37, 0x61
	s_cselect_b32 s8, s37, 0x60
	s_mul_i32 s6, s6, s8
	s_add_i32 s6, s6, s7
	s_mul_hi_i32 s7, s6, 0x2aaaaaab
	s_lshr_b32 s8, s7, 31
	s_ashr_i32 s7, s7, 4
	s_add_i32 s7, s7, s8
	s_lshl_b32 s8, s7, 2
	s_mulk_i32 s7, 0x60
	s_sub_i32 s6, s6, s7
	s_bfe_i32 s7, s6, 0x80000
	s_bfe_u32 s7, s7, 0x2000d
	s_add_i32 s7, s6, s7
	s_bfe_i32 s9, s7, 0x80000
	s_and_b32 s7, s7, 0xfc
	s_sub_i32 s6, s6, s7
	s_sext_i32_i16 s9, s9
	s_sext_i32_i8 s6, s6
	v_lshrrev_b32_e32 v5, 2, v3
	v_lshlrev_b32_e32 v6, 1, v3
	v_and_b32_e32 v1, 0xc0, v1
	s_lshr_b32 s12, s9, 2
	s_add_i32 s22, s8, s6
	v_and_b32_e32 v5, 4, v5
	v_and_b32_e32 v6, 24, v6
	v_sub_u32_e32 v0, v0, v1
	s_ashr_i32 s23, s22, 31
	s_bfe_i64 s[8:9], s[12:13], 0x100000
	v_or3_b32 v4, v4, v5, v6
	v_lshlrev_b32_e32 v5, 5, v13
	v_ashrrev_i16_sdwa v0, v2, sext(v0) dst_sel:DWORD dst_unused:UNUSED_PAD src0_sel:DWORD src1_sel:BYTE_0
	s_lshl_b64 s[6:7], s[22:23], 20
	s_lshl_b64 s[8:9], s[8:9], 20
	v_and_b32_e32 v5, 32, v5
	s_waitcnt vmcnt(12)
	v_bfe_i32 v14, v0, 0, 16
	s_add_u32 s26, s34, s8
	v_add_lshl_u32 v0, v5, v14, 1
	s_addc_u32 s27, s35, s9
	s_add_i32 s23, s36, 0
	v_lshl_add_u32 v132, v4, 12, v0
	s_add_i32 m0, s23, 0x10000
	v_lshl_add_u32 v134, v3, 12, v0
	global_load_lds_dwordx4 v132, s[26:27]
	s_add_i32 m0, s23, 0x12000
	s_add_u32 s8, s26, 0x80000
	global_load_lds_dwordx4 v128, s[26:27]
	s_addc_u32 s9, s27, 0
	s_add_i32 m0, s23, 0x14000
	v_mov_b32_e32 v133, 0
	global_load_lds_dwordx4 v132, s[8:9]
	s_add_i32 m0, s23, 0x16000
	s_add_u32 s24, s30, s6
	s_addc_u32 s25, s31, s7
	s_add_i32 s38, s23, 0x2000
	global_load_lds_dwordx4 v128, s[8:9]
	s_mov_b32 m0, s23
	s_add_u32 s6, s24, 0x80000
	global_load_lds_dwordx4 v134, s[24:25]
	s_mov_b32 m0, s38
	s_addc_u32 s7, s25, 0
	s_add_i32 s39, s23, 0x4000
	global_load_lds_dwordx4 v130, s[24:25]
	s_mov_b32 m0, s39
	s_add_i32 s40, s23, 0x6000
	global_load_lds_dwordx4 v134, s[6:7]
	s_mov_b32 m0, s40
	v_mov_b32_e32 v129, v133
	global_load_lds_dwordx4 v130, s[6:7]
	v_mov_b32_e32 v135, v133
	v_mov_b32_e32 v131, v133
	s_cmp_eq_u32 s14, 1
	s_mov_b32 s41, 0
	v_lshl_add_u64 v[6:7], s[26:27], 0, v[132:133]
	v_lshl_add_u64 v[4:5], s[26:27], 0, v[128:129]
	v_lshl_add_u64 v[0:1], s[24:25], 0, v[134:135]
	s_cselect_b64 s[6:7], -1, 0
	s_cmp_lg_u32 s14, 1
	v_lshl_add_u64 v[2:3], s[24:25], 0, v[130:131]
	s_cbranch_scc1 .LBB0_220
	s_barrier

.LBB0_226:
	ds_read_b128 v[144:147], v151
	ds_read_b128 v[154:157], v151 offset:1024
	ds_read_b128 v[158:161], v151 offset:2048
	ds_read_b128 v[162:165], v151 offset:3072
	ds_read_b128 v[166:169], v152
	ds_read_b128 v[170:173], v152 offset:1024
	ds_read_b128 v[174:177], v152 offset:2048
	ds_read_b128 v[178:181], v152 offset:3072
	s_add_u32 s26, s24, 0xfff80080
	s_addc_u32 s27, s25, -1
	s_cmp_eq_u32 s60, 28
	s_cselect_b32 s29, s17, s27
	s_cselect_b32 s28, s54, s26
	s_cselect_b32 s27, s15, s59
	s_cselect_b32 s26, s55, s58
	v_lshl_add_u64 v[190:191], s[24:25], 0, v[136:137]
	s_add_i32 m0, s23, 0xc000
	ds_read_b128 v[182:185], v153
	ds_read_b128 v[186:189], v153 offset:1024
	ds_read_b128 v[194:197], v153 offset:2048
	ds_read_b128 v[198:201], v153 offset:3072
	ds_read_b128 v[202:205], v153 offset:4096
	ds_read_b128 v[206:209], v153 offset:5120
	ds_read_b128 v[210:213], v153 offset:6144
	ds_read_b128 v[214:217], v153 offset:7168
	global_load_lds_dwordx4 v[190:191], off
	v_lshl_add_u64 v[190:191], s[24:25], 0, v[138:139]
	s_add_i32 m0, s23, 0xe000
	s_nop 0
	global_load_lds_dwordx4 v[190:191], off
	s_waitcnt vmcnt(8)
	s_waitcnt lgkmcnt(0)
	s_barrier
	s_waitcnt lgkmcnt(0)
	v_mfma_f32_16x16x32_bf16 v[124:127], v[144:147], v[182:185], v[124:127]
	v_mfma_f32_16x16x32_bf16 v[120:123], v[158:161], v[182:185], v[120:123]
	v_mfma_f32_16x16x32_bf16 v[116:119], v[144:147], v[194:197], v[116:119]
	v_mfma_f32_16x16x32_bf16 v[108:111], v[158:161], v[194:197], v[108:111]
	v_mfma_f32_16x16x32_bf16 v[100:103], v[144:147], v[202:205], v[100:103]
	v_mfma_f32_16x16x32_bf16 v[92:95], v[158:161], v[202:205], v[92:95]
	v_mfma_f32_16x16x32_bf16 v[84:87], v[144:147], v[210:213], v[84:87]
	v_mfma_f32_16x16x32_bf16 v[76:79], v[158:161], v[210:213], v[76:79]
	v_mfma_f32_16x16x32_bf16 v[124:127], v[154:157], v[186:189], v[124:127]
	v_mfma_f32_16x16x32_bf16 v[120:123], v[162:165], v[186:189], v[120:123]
	v_mfma_f32_16x16x32_bf16 v[116:119], v[154:157], v[198:201], v[116:119]
	v_mfma_f32_16x16x32_bf16 v[108:111], v[162:165], v[198:201], v[108:111]
	v_mfma_f32_16x16x32_bf16 v[100:103], v[154:157], v[206:209], v[100:103]
	v_mfma_f32_16x16x32_bf16 v[92:95], v[162:165], v[206:209], v[92:95]
	v_mfma_f32_16x16x32_bf16 v[84:87], v[154:157], v[214:217], v[84:87]
	v_mfma_f32_16x16x32_bf16 v[76:79], v[162:165], v[214:217], v[76:79]
	v_mfma_f32_16x16x32_bf16 v[112:115], v[166:169], v[182:185], v[112:115]
	v_mfma_f32_16x16x32_bf16 v[104:107], v[174:177], v[182:185], v[104:107]
	v_mfma_f32_16x16x32_bf16 v[96:99], v[166:169], v[194:197], v[96:99]
	v_mfma_f32_16x16x32_bf16 v[88:91], v[174:177], v[194:197], v[88:91]
	v_mfma_f32_16x16x32_bf16 v[80:83], v[166:169], v[202:205], v[80:83]
	v_mfma_f32_16x16x32_bf16 v[72:75], v[174:177], v[202:205], v[72:75]
	v_mfma_f32_16x16x32_bf16 v[68:71], v[166:169], v[210:213], v[68:71]
	v_mfma_f32_16x16x32_bf16 v[64:67], v[174:177], v[210:213], v[64:67]
	v_mfma_f32_16x16x32_bf16 v[112:115], v[170:173], v[186:189], v[112:115]
	v_mfma_f32_16x16x32_bf16 v[104:107], v[178:181], v[186:189], v[104:107]
	v_mfma_f32_16x16x32_bf16 v[96:99], v[170:173], v[198:201], v[96:99]
	v_mfma_f32_16x16x32_bf16 v[88:91], v[178:181], v[198:201], v[88:91]
	v_mfma_f32_16x16x32_bf16 v[80:83], v[170:173], v[206:209], v[80:83]
	v_mfma_f32_16x16x32_bf16 v[72:75], v[178:181], v[206:209], v[72:75]
	v_mfma_f32_16x16x32_bf16 v[68:71], v[170:173], v[214:217], v[68:71]
	v_mfma_f32_16x16x32_bf16 v[64:67], v[178:181], v[214:217], v[64:67]
	s_barrier
	s_add_i32 s33, s48, s36
	v_lshl_add_u64 v[190:191], s[26:27], 0, v[132:133]
	s_mov_b32 m0, s33
	ds_read_b128 v[182:185], v153 offset:16384
	ds_read_b128 v[186:189], v153 offset:17408
	ds_read_b128 v[194:197], v153 offset:18432
	ds_read_b128 v[198:201], v153 offset:19456
	ds_read_b128 v[202:205], v153 offset:20480
	ds_read_b128 v[206:209], v153 offset:21504
	ds_read_b128 v[210:213], v153 offset:22528
	ds_read_b128 v[214:217], v153 offset:23552
	global_load_lds_dwordx4 v[190:191], off
	s_add_i32 m0, s33, 0x2000
	s_add_u32 s62, s26, 0x80000
	v_lshl_add_u64 v[218:219], s[26:27], 0, v[128:129]
	s_addc_u32 s63, s27, 0
	s_add_i32 s33, s49, s36
	global_load_lds_dwordx4 v[218:219], off
	v_lshl_add_u64 v[220:221], s[62:63], 0, v[132:133]
	s_mov_b32 m0, s33
	v_lshl_add_u64 v[222:223], s[28:29], 0, v[130:131]
	global_load_lds_dwordx4 v[220:221], off
	v_lshl_add_u64 v[220:221], s[62:63], 0, v[128:129]
	s_add_i32 m0, s33, 0x2000
	s_nop 0
	global_load_lds_dwordx4 v[220:221], off
	v_lshl_add_u64 v[220:221], s[28:29], 0, v[134:135]
	s_mov_b32 m0, s23
	s_nop 0
	global_load_lds_dwordx4 v[220:221], off
	s_mov_b32 m0, s38
	s_nop 0
	global_load_lds_dwordx4 v[222:223], off
	s_waitcnt vmcnt(8)
	s_waitcnt lgkmcnt(0)
	s_barrier
	s_waitcnt lgkmcnt(0)
	v_mfma_f32_16x16x32_bf16 v[60:63], v[144:147], v[182:185], v[60:63]
	v_mfma_f32_16x16x32_bf16 v[56:59], v[158:161], v[182:185], v[56:59]
	v_mfma_f32_16x16x32_bf16 v[52:55], v[144:147], v[194:197], v[52:55]
	v_mfma_f32_16x16x32_bf16 v[44:47], v[158:161], v[194:197], v[44:47]
	v_mfma_f32_16x16x32_bf16 v[36:39], v[144:147], v[202:205], v[36:39]
	v_mfma_f32_16x16x32_bf16 v[28:31], v[158:161], v[202:205], v[28:31]
	v_mfma_f32_16x16x32_bf16 v[20:23], v[144:147], v[210:213], v[20:23]
	v_mfma_f32_16x16x32_bf16 v[12:15], v[158:161], v[210:213], v[12:15]
	v_mfma_f32_16x16x32_bf16 v[60:63], v[154:157], v[186:189], v[60:63]
	v_mfma_f32_16x16x32_bf16 v[56:59], v[162:165], v[186:189], v[56:59]
	v_mfma_f32_16x16x32_bf16 v[52:55], v[154:157], v[198:201], v[52:55]
	v_mfma_f32_16x16x32_bf16 v[44:47], v[162:165], v[198:201], v[44:47]
	v_mfma_f32_16x16x32_bf16 v[36:39], v[154:157], v[206:209], v[36:39]
	v_mfma_f32_16x16x32_bf16 v[28:31], v[162:165], v[206:209], v[28:31]
	v_mfma_f32_16x16x32_bf16 v[20:23], v[154:157], v[214:217], v[20:23]
	v_mfma_f32_16x16x32_bf16 v[12:15], v[162:165], v[214:217], v[12:15]
	v_mfma_f32_16x16x32_bf16 v[48:51], v[166:169], v[182:185], v[48:51]
	v_mfma_f32_16x16x32_bf16 v[40:43], v[174:177], v[182:185], v[40:43]
	v_mfma_f32_16x16x32_bf16 v[32:35], v[166:169], v[194:197], v[32:35]
	v_mfma_f32_16x16x32_bf16 v[24:27], v[174:177], v[194:197], v[24:27]
	v_mfma_f32_16x16x32_bf16 v[16:19], v[166:169], v[202:205], v[16:19]
	v_mfma_f32_16x16x32_bf16 v[8:11], v[174:177], v[202:205], v[8:11]
	v_mfma_f32_16x16x32_bf16 v[4:7], v[166:169], v[210:213], v[4:7]
	v_mfma_f32_16x16x32_bf16 v[0:3], v[174:177], v[210:213], v[0:3]
	v_mfma_f32_16x16x32_bf16 v[48:51], v[170:173], v[186:189], v[48:51]
	v_mfma_f32_16x16x32_bf16 v[40:43], v[178:181], v[186:189], v[40:43]
	v_mfma_f32_16x16x32_bf16 v[32:35], v[170:173], v[198:201], v[32:35]
	v_mfma_f32_16x16x32_bf16 v[24:27], v[178:181], v[198:201], v[24:27]
	v_mfma_f32_16x16x32_bf16 v[16:19], v[170:173], v[206:209], v[16:19]
	v_mfma_f32_16x16x32_bf16 v[8:11], v[178:181], v[206:209], v[8:11]
	v_mfma_f32_16x16x32_bf16 v[4:7], v[170:173], v[214:217], v[4:7]
	v_mfma_f32_16x16x32_bf16 v[0:3], v[178:181], v[214:217], v[0:3]
	s_barrier
	s_add_i32 s33, 0, 0x18000
	s_add_i32 s56, 0, 0x1c000
	v_add_u32_e32 v162, s33, v149
	v_add_u32_e32 v178, s56, v149
	ds_read_b128 v[144:147], v162
	ds_read_b128 v[154:157], v162 offset:1024
	ds_read_b128 v[158:161], v162 offset:2048
	ds_read_b128 v[162:165], v162 offset:3072
	ds_read_b128 v[166:169], v178
	ds_read_b128 v[170:173], v178 offset:1024
	ds_read_b128 v[174:177], v178 offset:2048
	ds_read_b128 v[178:181], v178 offset:3072
	s_add_u32 s28, s28, 0x80000
	s_addc_u32 s29, s29, 0
	s_mov_b32 m0, s39
	v_lshl_add_u64 v[224:225], s[28:29], 0, v[134:135]
	ds_read_b128 v[182:185], v153 offset:32768
	ds_read_b128 v[186:189], v153 offset:33792
	ds_read_b128 v[194:197], v153 offset:34816
	ds_read_b128 v[198:201], v153 offset:35840
	ds_read_b128 v[202:205], v153 offset:36864
	ds_read_b128 v[206:209], v153 offset:37888
	ds_read_b128 v[210:213], v153 offset:38912
	ds_read_b128 v[214:217], v153 offset:39936
	global_load_lds_dwordx4 v[224:225], off
	v_lshl_add_u64 v[224:225], s[28:29], 0, v[130:131]
	s_mov_b32 m0, s40
	s_nop 0
	global_load_lds_dwordx4 v[224:225], off
	s_waitcnt vmcnt(8)
	s_waitcnt lgkmcnt(0)
	s_barrier
	s_waitcnt lgkmcnt(0)
	v_mfma_f32_16x16x32_bf16 v[124:127], v[144:147], v[182:185], v[124:127]
	v_mfma_f32_16x16x32_bf16 v[120:123], v[158:161], v[182:185], v[120:123]
	v_mfma_f32_16x16x32_bf16 v[116:119], v[144:147], v[194:197], v[116:119]
	v_mfma_f32_16x16x32_bf16 v[108:111], v[158:161], v[194:197], v[108:111]
	v_mfma_f32_16x16x32_bf16 v[100:103], v[144:147], v[202:205], v[100:103]
	v_mfma_f32_16x16x32_bf16 v[92:95], v[158:161], v[202:205], v[92:95]
	v_mfma_f32_16x16x32_bf16 v[84:87], v[144:147], v[210:213], v[84:87]
	v_mfma_f32_16x16x32_bf16 v[76:79], v[158:161], v[210:213], v[76:79]
	v_mfma_f32_16x16x32_bf16 v[124:127], v[154:157], v[186:189], v[124:127]
	v_mfma_f32_16x16x32_bf16 v[120:123], v[162:165], v[186:189], v[120:123]
	v_mfma_f32_16x16x32_bf16 v[116:119], v[154:157], v[198:201], v[116:119]
	v_mfma_f32_16x16x32_bf16 v[108:111], v[162:165], v[198:201], v[108:111]
	v_mfma_f32_16x16x32_bf16 v[100:103], v[154:157], v[206:209], v[100:103]
	v_mfma_f32_16x16x32_bf16 v[92:95], v[162:165], v[206:209], v[92:95]
	v_mfma_f32_16x16x32_bf16 v[84:87], v[154:157], v[214:217], v[84:87]
	v_mfma_f32_16x16x32_bf16 v[76:79], v[162:165], v[214:217], v[76:79]
	v_mfma_f32_16x16x32_bf16 v[112:115], v[166:169], v[182:185], v[112:115]
	v_mfma_f32_16x16x32_bf16 v[104:107], v[174:177], v[182:185], v[104:107]
	v_mfma_f32_16x16x32_bf16 v[96:99], v[166:169], v[194:197], v[96:99]
	v_mfma_f32_16x16x32_bf16 v[88:91], v[174:177], v[194:197], v[88:91]
	v_mfma_f32_16x16x32_bf16 v[80:83], v[166:169], v[202:205], v[80:83]
	v_mfma_f32_16x16x32_bf16 v[72:75], v[174:177], v[202:205], v[72:75]
	v_mfma_f32_16x16x32_bf16 v[68:71], v[166:169], v[210:213], v[68:71]
	v_mfma_f32_16x16x32_bf16 v[64:67], v[174:177], v[210:213], v[64:67]
	v_mfma_f32_16x16x32_bf16 v[112:115], v[170:173], v[186:189], v[112:115]
	v_mfma_f32_16x16x32_bf16 v[104:107], v[178:181], v[186:189], v[104:107]
	v_mfma_f32_16x16x32_bf16 v[96:99], v[170:173], v[198:201], v[96:99]
	v_mfma_f32_16x16x32_bf16 v[88:91], v[178:181], v[198:201], v[88:91]
	v_mfma_f32_16x16x32_bf16 v[80:83], v[170:173], v[206:209], v[80:83]
	v_mfma_f32_16x16x32_bf16 v[72:75], v[178:181], v[206:209], v[72:75]
	v_mfma_f32_16x16x32_bf16 v[68:71], v[170:173], v[214:217], v[68:71]
	v_mfma_f32_16x16x32_bf16 v[64:67], v[178:181], v[214:217], v[64:67]
	s_barrier
	s_add_i32 s28, s33, s36
	v_lshl_add_u64 v[190:191], v[190:191], 0, s[10:11]
	s_mov_b32 m0, s28
	ds_read_b128 v[182:185], v153 offset:49152
	ds_read_b128 v[186:189], v153 offset:50176
	ds_read_b128 v[194:197], v153 offset:51200
	ds_read_b128 v[198:201], v153 offset:52224
	ds_read_b128 v[202:205], v153 offset:53248
	ds_read_b128 v[206:209], v153 offset:54272
	ds_read_b128 v[210:213], v153 offset:55296
	ds_read_b128 v[214:217], v153 offset:56320
	global_load_lds_dwordx4 v[190:191], off
	s_add_i32 m0, s28, 0x2000
	s_add_u32 s26, s26, 0x80080
	v_lshl_add_u64 v[190:191], v[218:219], 0, s[10:11]
	s_addc_u32 s27, s27, 0
	s_add_i32 s28, s56, s36
	global_load_lds_dwordx4 v[190:191], off
	v_lshl_add_u64 v[190:191], s[26:27], 0, v[132:133]
	s_mov_b32 m0, s28
	s_nop 0
	global_load_lds_dwordx4 v[190:191], off
	v_lshl_add_u64 v[190:191], s[26:27], 0, v[128:129]
	s_add_i32 m0, s28, 0x2000
	s_nop 0
	global_load_lds_dwordx4 v[190:191], off
	v_lshl_add_u64 v[190:191], v[220:221], 0, s[10:11]
	s_mov_b32 m0, s42
	s_nop 0
	global_load_lds_dwordx4 v[190:191], off
	v_lshl_add_u64 v[190:191], v[222:223], 0, s[10:11]
	s_mov_b32 m0, s43
	s_nop 0
	global_load_lds_dwordx4 v[190:191], off
	s_waitcnt vmcnt(8)
	s_waitcnt lgkmcnt(0)
	s_barrier
	s_waitcnt lgkmcnt(0)
	v_mfma_f32_16x16x32_bf16 v[60:63], v[144:147], v[182:185], v[60:63]
	v_mfma_f32_16x16x32_bf16 v[56:59], v[158:161], v[182:185], v[56:59]
	v_mfma_f32_16x16x32_bf16 v[52:55], v[144:147], v[194:197], v[52:55]
	v_mfma_f32_16x16x32_bf16 v[44:47], v[158:161], v[194:197], v[44:47]
	v_mfma_f32_16x16x32_bf16 v[36:39], v[144:147], v[202:205], v[36:39]
	v_mfma_f32_16x16x32_bf16 v[28:31], v[158:161], v[202:205], v[28:31]
	v_mfma_f32_16x16x32_bf16 v[20:23], v[144:147], v[210:213], v[20:23]
	v_mfma_f32_16x16x32_bf16 v[12:15], v[158:161], v[210:213], v[12:15]
	v_mfma_f32_16x16x32_bf16 v[60:63], v[154:157], v[186:189], v[60:63]
	v_mfma_f32_16x16x32_bf16 v[56:59], v[162:165], v[186:189], v[56:59]
	v_mfma_f32_16x16x32_bf16 v[52:55], v[154:157], v[198:201], v[52:55]
	v_mfma_f32_16x16x32_bf16 v[44:47], v[162:165], v[198:201], v[44:47]
	v_mfma_f32_16x16x32_bf16 v[36:39], v[154:157], v[206:209], v[36:39]
	v_mfma_f32_16x16x32_bf16 v[28:31], v[162:165], v[206:209], v[28:31]
	v_mfma_f32_16x16x32_bf16 v[20:23], v[154:157], v[214:217], v[20:23]
	v_mfma_f32_16x16x32_bf16 v[12:15], v[162:165], v[214:217], v[12:15]
	v_mfma_f32_16x16x32_bf16 v[48:51], v[166:169], v[182:185], v[48:51]
	v_mfma_f32_16x16x32_bf16 v[40:43], v[174:177], v[182:185], v[40:43]
	v_mfma_f32_16x16x32_bf16 v[32:35], v[166:169], v[194:197], v[32:35]
	v_mfma_f32_16x16x32_bf16 v[24:27], v[174:177], v[194:197], v[24:27]
	v_mfma_f32_16x16x32_bf16 v[16:19], v[166:169], v[202:205], v[16:19]
	v_mfma_f32_16x16x32_bf16 v[8:11], v[174:177], v[202:205], v[8:11]
	v_mfma_f32_16x16x32_bf16 v[4:7], v[166:169], v[210:213], v[4:7]
	v_mfma_f32_16x16x32_bf16 v[0:3], v[174:177], v[210:213], v[0:3]
	v_mfma_f32_16x16x32_bf16 v[48:51], v[170:173], v[186:189], v[48:51]
	v_mfma_f32_16x16x32_bf16 v[40:43], v[178:181], v[186:189], v[40:43]
	v_mfma_f32_16x16x32_bf16 v[32:35], v[170:173], v[198:201], v[32:35]
	v_mfma_f32_16x16x32_bf16 v[24:27], v[178:181], v[198:201], v[24:27]
	v_mfma_f32_16x16x32_bf16 v[16:19], v[170:173], v[206:209], v[16:19]
	v_mfma_f32_16x16x32_bf16 v[8:11], v[178:181], v[206:209], v[8:11]
	v_mfma_f32_16x16x32_bf16 v[4:7], v[170:173], v[214:217], v[4:7]
	v_mfma_f32_16x16x32_bf16 v[0:3], v[178:181], v[214:217], v[0:3]
	s_barrier
	s_add_i32 s60, s60, 2
	s_add_u32 s24, s24, 0x100
	s_addc_u32 s25, s25, 0
	s_add_u32 s58, s58, 0x100
	s_addc_u32 s59, s59, 0
	s_cmp_gt_u32 s60, 29
	s_cbranch_scc0 .LBB0_226
	s_and_b64 vcc, exec, s[12:13]
	s_cbranch_vccz .LBB0_229
	s_barrier

.LBB0_515:
	s_or_b64 exec, exec, s[4:5]
	s_waitcnt lgkmcnt(0)
	v_mov_b32_e32 v0, v192
	s_barrier
	s_mov_b64 s[6:7], s[0:1]
	v_readfirstlane_b32 s4, v0
	s_ashr_i32 s17, s4, 6
	s_add_i32 s16, s17, s3
	s_mov_b64 s[4:5], s[0:1]
	s_cmpk_gt_i32 s16, 0x7fff
	s_cbranch_scc1 .LBB0_518
	s_load_dwordx2 s[6:7], s[6:7], 0x80
	v_and_b32_e32 v18, 63, v0
	s_load_dwordx2 s[4:5], s[4:5], 0x30
	v_mov_b32_e32 v17, 0
	v_lshlrev_b32_e32 v16, 4, v18
	s_waitcnt lgkmcnt(0)
	s_add_u32 s8, s6, 0x19800000
	s_addc_u32 s9, s7, 0
	s_add_u32 s10, s6, 0xe600000
	s_addc_u32 s11, s7, 0
	s_add_u32 s12, s6, 0xc600000
	s_addc_u32 s13, s7, 0
	s_ashr_i32 s6, s16, 2
	s_ashr_i32 s7, s6, 31
	s_mul_i32 s19, s6, 0x3000
	s_mul_hi_i32 s18, s6, 0x3000
	s_add_u32 s19, s10, s19
	s_addc_u32 s20, s11, s18
	s_lshl_b32 s21, s17, 9
	s_lshl_b32 s17, s17, 10
	s_and_b32 s22, s17, 0xc00
	s_add_u32 s18, s19, s22
	s_addc_u32 s19, s20, 0
	s_lshl_b64 s[6:7], s[6:7], 12
	s_add_u32 s6, s8, s6
	s_addc_u32 s7, s9, s7
	v_lshl_add_u64 v[0:1], s[18:19], 0, v[16:17]
	s_movk_i32 s17, 0x2000
	s_add_u32 s6, s6, s22
	v_add_co_u32_e32 v0, vcc, s17, v0
	s_addc_u32 s7, s7, 0
	s_nop 0
	v_addc_co_u32_e32 v1, vcc, 0, v1, vcc
	global_load_dwordx4 v[12:15], v16, s[6:7] nt
	v_lshlrev_b32_e32 v16, 5, v18
	global_load_dwordx4 v[8:11], v[0:1], off nt
	s_nop 0
	global_load_dwordx4 v[0:3], v16, s[4:5]
	global_load_dwordx4 v[4:7], v16, s[4:5] offset:16
	v_mbcnt_lo_u32_b32 v16, -1, 0
	v_mbcnt_hi_u32_b32 v16, -1, v16
	v_and_b32_e32 v19, 64, v16
	v_add_u32_e32 v19, 64, v19
	v_xor_b32_e32 v20, 1, v16
	v_cmp_lt_i32_e32 vcc, v20, v19
	s_lshl_b32 s4, s2, 12
	s_add_i32 s18, s4, s21
	v_cndmask_b32_e32 v20, v16, v20, vcc
	v_lshlrev_b32_e32 v26, 2, v20
	v_xor_b32_e32 v20, 2, v16
	v_cmp_lt_i32_e32 vcc, v20, v19
	s_lshl_b32 s19, s52, 12
	s_waitcnt vmcnt(8)
	v_mov_b32_e32 v32, 0x358637bd
	v_cndmask_b32_e32 v20, v16, v20, vcc
	v_lshlrev_b32_e32 v27, 2, v20
	v_xor_b32_e32 v20, 4, v16
	v_cmp_lt_i32_e32 vcc, v20, v19
	s_mov_b32 s20, 0xf800000
	v_mov_b32_e32 v33, 0x260
	v_cndmask_b32_e32 v20, v16, v20, vcc
	v_lshlrev_b32_e32 v28, 2, v20
	v_xor_b32_e32 v20, 8, v16
	v_cmp_lt_i32_e32 vcc, v20, v19
	s_nop 1
	v_cndmask_b32_e32 v20, v16, v20, vcc
	v_lshlrev_b32_e32 v29, 2, v20
	v_xor_b32_e32 v20, 16, v16
	v_cmp_lt_i32_e32 vcc, v20, v19
	s_nop 1
	v_cndmask_b32_e32 v20, v16, v20, vcc
	v_lshlrev_b32_e32 v30, 2, v20
	v_xor_b32_e32 v20, 32, v16
	v_cmp_lt_i32_e32 vcc, v20, v19
	s_nop 1
	v_cndmask_b32_e32 v16, v16, v20, vcc
	v_lshlrev_b32_e32 v31, 2, v16
	v_lshlrev_b32_e32 v16, 4, v18
.LBB0_517:
	s_ashr_i32 s6, s16, 2
	s_add_i32 s7, s16, s46
	s_cmp_lt_i32 s7, 0x8000
	s_cselect_b64 s[4:5], -1, 0
	s_waitcnt vmcnt(3)
	v_lshlrev_b32_e32 v21, 16, v15
	s_waitcnt vmcnt(2)
	v_lshlrev_b32_e32 v20, 16, v11
	v_and_b32_e32 v19, 0xffff0000, v15
	v_and_b32_e32 v18, 0xffff0000, v11
	v_lshlrev_b32_e32 v22, 16, v10
	v_and_b32_e32 v11, 0xffff0000, v14
	v_lshlrev_b32_e32 v15, 16, v13
	v_and_b32_e32 v24, 0xffff0000, v9
	v_lshlrev_b32_e32 v43, 16, v12
	s_and_b64 s[4:5], s[4:5], exec
	v_lshlrev_b32_e32 v23, 16, v14
	v_lshlrev_b32_e32 v14, 16, v9
	v_and_b32_e32 v25, 0xffff0000, v13
	v_and_b32_e32 v9, 0xffff0000, v12
	v_mul_f32_e32 v37, 0xbfb8aa3b, v22
	v_mov_b32_e32 v34, v19
	v_mov_b32_e32 v35, v11
	v_mul_f32_e32 v40, 0xbfb8aa3b, v24
	v_mul_f32_e32 v45, v15, v15
	v_mul_f32_e32 v46, v43, v43
	s_cselect_b32 s21, s7, s16
	v_mov_b32_e32 v12, v21
	v_mov_b32_e32 v13, v23
	v_exp_f32_e32 v37, v37
	v_pk_mul_f32 v[34:35], v[34:35], v[34:35]
	v_exp_f32_e32 v40, v40
	v_fmac_f32_e32 v45, v25, v25
	v_fmac_f32_e32 v46, v9, v9
	s_ashr_i32 s22, s21, 2
	v_and_b32_e32 v10, 0xffff0000, v10
	v_pk_fma_f32 v[12:13], v[12:13], v[12:13], v[34:35]
	v_add_f32_e32 v34, v46, v45
	s_ashr_i32 s23, s22, 31
	v_lshlrev_b32_e32 v42, 16, v8
	v_and_b32_e32 v8, 0xffff0000, v8
	v_mul_f32_e32 v36, 0xbfb8aa3b, v20
	v_mul_f32_e32 v38, 0xbfb8aa3b, v10
	v_mul_f32_e32 v39, 0xbfb8aa3b, v14
	v_add_f32_e32 v13, v13, v34
	s_mov_b32 s16, s7
	s_mul_hi_i32 s7, s22, 0x3000
	s_mul_i32 s24, s22, 0x3000
	s_lshl_b64 s[22:23], s[22:23], 12
	v_mul_f32_e32 v44, 0xbfb8aa3b, v8
	v_exp_f32_e32 v36, v36
	v_exp_f32_e32 v38, v38
	v_exp_f32_e32 v39, v39
	v_add_f32_e32 v13, v12, v13
	s_add_u32 s22, s8, s22
	v_exp_f32_e32 v44, v44
	v_add_f32_e32 v34, 1.0, v37
	v_add_f32_e32 v37, 1.0, v40
	ds_bpermute_b32 v40, v26, v13
	s_addc_u32 s23, s9, s23
	s_lshl_b32 s21, s21, 10
	s_and_b32 s21, s21, 0xc00
	v_mul_f32_e32 v41, 0xbfb8aa3b, v42
	s_add_u32 s22, s22, s21
	v_exp_f32_e32 v41, v41
	v_add_f32_e32 v12, 1.0, v36
	v_add_f32_e32 v35, 1.0, v38
	v_add_f32_e32 v36, 1.0, v39
	s_addc_u32 s23, s23, 0
	v_add_f32_e32 v39, 1.0, v44
	v_rcp_f32_e32 v44, v34
	v_rcp_f32_e32 v46, v35
	v_rcp_f32_e32 v48, v36
	v_rcp_f32_e32 v50, v37
	global_load_dwordx4 v[34:37], v16, s[22:23] nt
	s_add_u32 s22, s10, s24
	s_waitcnt lgkmcnt(0)
	v_add_f32_e32 v13, v13, v40
	s_addc_u32 s7, s11, s7
	ds_bpermute_b32 v40, v27, v13
	s_add_u32 s22, s22, s21
	v_add_f32_e32 v38, 1.0, v41
	s_addc_u32 s23, s7, 0
	v_rcp_f32_e32 v52, v38
	v_rcp_f32_e32 v54, v39
	v_lshl_add_u64 v[38:39], s[22:23], 0, v[16:17]
	v_add_co_u32_e32 v38, vcc, s17, v38
	s_waitcnt lgkmcnt(0)
	v_add_f32_e32 v13, v13, v40
	v_addc_co_u32_e32 v39, vcc, 0, v39, vcc
	global_load_dwordx4 v[38:41], v[38:39], off nt
	ds_bpermute_b32 v45, v28, v13
	v_mul_f32_e32 v47, 0xbfb8aa3b, v18
	v_exp_f32_e32 v47, v47
	s_ashr_i32 s7, s6, 31
	s_lshl_b64 s[6:7], s[6:7], 12
	s_waitcnt lgkmcnt(0)
	v_add_f32_e32 v13, v13, v45
	ds_bpermute_b32 v45, v29, v13
	s_add_u32 s6, s12, s6
	s_addc_u32 s7, s13, s7
	s_and_b32 s21, s18, 0x600
	v_add_f32_e32 v56, 1.0, v47
	s_waitcnt lgkmcnt(0)
	v_add_f32_e32 v13, v13, v45
	ds_bpermute_b32 v45, v30, v13
	s_lshl_b32 s21, s21, 1
	s_add_u32 s22, s6, s21
	s_addc_u32 s23, s7, 0
	v_rcp_f32_e32 v12, v12
	s_waitcnt lgkmcnt(0)
	v_add_f32_e32 v13, v13, v45
	ds_bpermute_b32 v45, v31, v13
	s_add_i32 s18, s18, s19
	s_waitcnt lgkmcnt(0)
	v_add_f32_e32 v13, v13, v45
	v_fmamk_f32 v13, v13, 0x3b000000, v32
	v_mul_f32_e32 v45, 0x4f800000, v13
	v_cmp_gt_f32_e32 vcc, s20, v13
	s_nop 1
	v_cndmask_b32_e32 v13, v13, v45, vcc
	v_sqrt_f32_e32 v45, v13
	s_nop 0
	v_add_u32_e32 v47, -1, v45
	v_add_u32_e32 v49, 1, v45
	v_fma_f32 v51, -v47, v45, v13
	v_fma_f32 v53, -v49, v45, v13
	v_cmp_ge_f32_e64 s[6:7], 0, v51
	s_nop 1
	v_cndmask_b32_e64 v45, v45, v47, s[6:7]
	v_cmp_lt_f32_e64 s[6:7], 0, v53
	s_nop 1
	v_cndmask_b32_e64 v45, v45, v49, s[6:7]
	v_mul_f32_e32 v47, 0x37800000, v45
	v_cndmask_b32_e32 v45, v45, v47, vcc
	v_cmp_class_f32_e32 vcc, v13, v33
	s_nop 1
	v_cndmask_b32_e32 v13, v45, v13, vcc
	v_div_scale_f32 v45, s[6:7], v13, v13, 1.0
	v_rcp_f32_e32 v49, v45
	v_div_scale_f32 v47, vcc, 1.0, v13, 1.0
	v_fma_f32 v51, -v45, v49, 1.0
	v_fmac_f32_e32 v49, v51, v49
	v_mul_f32_e32 v51, v47, v49
	v_fma_f32 v53, -v45, v51, v47
	v_fmac_f32_e32 v51, v53, v49
	v_fma_f32 v45, -v45, v51, v47
	v_div_fmas_f32 v45, v45, v49, v51
	v_div_fixup_f32 v53, v45, v13, 1.0
	v_pk_mul_f32 v[42:43], v[52:53], v[42:43]
	v_rcp_f32_e32 v52, v56
	v_mov_b32_e32 v47, v53
	v_mov_b32_e32 v13, v53
	v_mov_b32_e32 v55, v53
	v_mov_b32_e32 v49, v53
	v_pk_mul_f32 v[10:11], v[46:47], v[10:11]
	v_pk_mul_f32 v[12:13], v[12:13], v[20:21]
	v_mov_b32_e32 v51, v53
	v_mov_b32_e32 v45, v53
	v_pk_mul_f32 v[8:9], v[54:55], v[8:9]
	v_pk_mul_f32 v[14:15], v[48:49], v[14:15]
	s_waitcnt vmcnt(2)
	v_mul_f32_e32 v11, v5, v11
	v_mul_f32_e32 v13, v6, v13
	v_pk_mul_f32 v[24:25], v[50:51], v[24:25]
	v_pk_mul_f32 v[22:23], v[44:45], v[22:23]
	v_mul_f32_e32 v9, v1, v9
	v_mul_f32_e32 v15, v2, v15
	v_mul_f32_e32 v10, v10, v11
	v_mul_f32_e32 v11, v12, v13
	v_pk_mul_f32 v[12:13], v[52:53], v[18:19]
	v_mul_f32_e32 v43, v0, v43
	v_mul_f32_e32 v21, v3, v25
	v_mul_f32_e32 v23, v4, v23
	v_mul_f32_e32 v8, v8, v9
	v_mul_f32_e32 v9, v14, v15
	v_mul_f32_e32 v13, v7, v13
	v_mul_f32_e32 v20, v42, v43
	v_mul_f32_e32 v14, v24, v21
	v_mul_f32_e32 v15, v22, v23
	v_cvt_pk_bf16_f32 v8, v20, v8
	v_cvt_pk_bf16_f32 v9, v9, v14
	v_cvt_pk_bf16_f32 v10, v15, v10
	v_mul_f32_e32 v12, v12, v13
	v_cvt_pk_bf16_f32 v11, v11, v12
	global_store_dwordx4 v16, v[8:11], s[22:23]
	s_waitcnt vmcnt(2)
	v_mov_b64_e32 v[12:13], v[34:35]
	v_mov_b64_e32 v[14:15], v[36:37]
	s_waitcnt vmcnt(1)
	v_mov_b64_e32 v[8:9], v[38:39]
	v_mov_b64_e32 v[10:11], v[40:41]
	s_mov_b64 vcc, s[4:5]
	s_cbranch_vccnz .LBB0_517

.LBB0_589:
	ds_read_b128 v[144:147], v153
	ds_read_b128 v[158:161], v153 offset:1024
	ds_read_b128 v[162:165], v153 offset:2048
	ds_read_b128 v[166:169], v153 offset:3072
	ds_read_b128 v[170:173], v154
	ds_read_b128 v[174:177], v154 offset:1024
	ds_read_b128 v[178:181], v154 offset:2048
	ds_read_b128 v[182:185], v154 offset:3072
	s_add_u32 s33, s48, 0xfff80080
	s_addc_u32 s50, s49, -1
	s_cmp_eq_u32 s77, 28
	s_cselect_b32 s59, s35, s50
	s_cselect_b32 s58, s41, s33
	s_cselect_b32 s51, s31, s75
	s_cselect_b32 s50, s73, s74
	v_lshl_add_u64 v[148:149], s[48:49], 0, v[136:137]
	s_add_i32 m0, s43, 0xc000
	ds_read_b128 v[186:189], v155
	ds_read_b128 v[194:197], v155 offset:1024
	ds_read_b128 v[198:201], v155 offset:2048
	ds_read_b128 v[202:205], v155 offset:3072
	ds_read_b128 v[206:209], v155 offset:4096
	ds_read_b128 v[210:213], v155 offset:5120
	ds_read_b128 v[214:217], v155 offset:6144
	ds_read_b128 v[218:221], v155 offset:7168
	global_load_lds_dwordx4 v[148:149], off
	v_lshl_add_u64 v[148:149], s[48:49], 0, v[138:139]
	s_add_i32 m0, s43, 0xe000
	s_nop 0
	global_load_lds_dwordx4 v[148:149], off
	s_waitcnt vmcnt(8)
	s_waitcnt lgkmcnt(0)
	s_barrier
	s_waitcnt lgkmcnt(0)
	v_mfma_f32_16x16x32_bf16 v[124:127], v[144:147], v[186:189], v[124:127]
	v_mfma_f32_16x16x32_bf16 v[120:123], v[162:165], v[186:189], v[120:123]
	v_mfma_f32_16x16x32_bf16 v[108:111], v[144:147], v[198:201], v[108:111]
	v_mfma_f32_16x16x32_bf16 v[104:107], v[162:165], v[198:201], v[104:107]
	v_mfma_f32_16x16x32_bf16 v[92:95], v[144:147], v[206:209], v[92:95]
	v_mfma_f32_16x16x32_bf16 v[88:91], v[162:165], v[206:209], v[88:91]
	v_mfma_f32_16x16x32_bf16 v[76:79], v[144:147], v[214:217], v[76:79]
	v_mfma_f32_16x16x32_bf16 v[72:75], v[162:165], v[214:217], v[72:75]
	v_mfma_f32_16x16x32_bf16 v[124:127], v[158:161], v[194:197], v[124:127]
	v_mfma_f32_16x16x32_bf16 v[120:123], v[166:169], v[194:197], v[120:123]
	v_mfma_f32_16x16x32_bf16 v[108:111], v[158:161], v[202:205], v[108:111]
	v_mfma_f32_16x16x32_bf16 v[104:107], v[166:169], v[202:205], v[104:107]
	v_mfma_f32_16x16x32_bf16 v[92:95], v[158:161], v[210:213], v[92:95]
	v_mfma_f32_16x16x32_bf16 v[88:91], v[166:169], v[210:213], v[88:91]
	v_mfma_f32_16x16x32_bf16 v[76:79], v[158:161], v[218:221], v[76:79]
	v_mfma_f32_16x16x32_bf16 v[72:75], v[166:169], v[218:221], v[72:75]
	v_mfma_f32_16x16x32_bf16 v[116:119], v[170:173], v[186:189], v[116:119]
	v_mfma_f32_16x16x32_bf16 v[112:115], v[178:181], v[186:189], v[112:115]
	v_mfma_f32_16x16x32_bf16 v[100:103], v[170:173], v[198:201], v[100:103]
	v_mfma_f32_16x16x32_bf16 v[96:99], v[178:181], v[198:201], v[96:99]
	v_mfma_f32_16x16x32_bf16 v[84:87], v[170:173], v[206:209], v[84:87]
	v_mfma_f32_16x16x32_bf16 v[80:83], v[178:181], v[206:209], v[80:83]
	v_mfma_f32_16x16x32_bf16 v[68:71], v[170:173], v[214:217], v[68:71]
	v_mfma_f32_16x16x32_bf16 v[64:67], v[178:181], v[214:217], v[64:67]
	v_mfma_f32_16x16x32_bf16 v[116:119], v[174:177], v[194:197], v[116:119]
	v_mfma_f32_16x16x32_bf16 v[112:115], v[182:185], v[194:197], v[112:115]
	v_mfma_f32_16x16x32_bf16 v[100:103], v[174:177], v[202:205], v[100:103]
	v_mfma_f32_16x16x32_bf16 v[96:99], v[182:185], v[202:205], v[96:99]
	v_mfma_f32_16x16x32_bf16 v[84:87], v[174:177], v[210:213], v[84:87]
	v_mfma_f32_16x16x32_bf16 v[80:83], v[182:185], v[210:213], v[80:83]
	v_mfma_f32_16x16x32_bf16 v[68:71], v[174:177], v[218:221], v[68:71]
	v_mfma_f32_16x16x32_bf16 v[64:67], v[182:185], v[218:221], v[64:67]
	s_barrier
	s_add_i32 s33, s71, s64
	v_lshl_add_u64 v[148:149], s[50:51], 0, v[130:131]
	s_mov_b32 m0, s33
	ds_read_b128 v[186:189], v155 offset:16384
	ds_read_b128 v[194:197], v155 offset:17408
	ds_read_b128 v[198:201], v155 offset:18432
	ds_read_b128 v[202:205], v155 offset:19456
	ds_read_b128 v[206:209], v155 offset:20480
	ds_read_b128 v[210:213], v155 offset:21504
	ds_read_b128 v[214:217], v155 offset:22528
	ds_read_b128 v[218:221], v155 offset:23552
	global_load_lds_dwordx4 v[148:149], off
	s_add_i32 m0, s33, 0x2000
	s_add_u32 s54, s50, 0x80000
	v_lshl_add_u64 v[190:191], s[50:51], 0, v[134:135]
	s_addc_u32 s55, s51, 0
	s_add_i32 s33, s72, s64
	global_load_lds_dwordx4 v[190:191], off
	v_lshl_add_u64 v[222:223], s[54:55], 0, v[130:131]
	s_mov_b32 m0, s33
	v_lshl_add_u64 v[224:225], s[58:59], 0, v[132:133]
	global_load_lds_dwordx4 v[222:223], off
	v_lshl_add_u64 v[222:223], s[54:55], 0, v[134:135]
	s_add_i32 m0, s33, 0x2000
	s_nop 0
	global_load_lds_dwordx4 v[222:223], off
	v_lshl_add_u64 v[222:223], s[58:59], 0, v[128:129]
	s_mov_b32 m0, s43
	s_nop 0
	global_load_lds_dwordx4 v[222:223], off
	s_mov_b32 m0, s65
	s_nop 0
	global_load_lds_dwordx4 v[224:225], off
	s_waitcnt vmcnt(8)
	s_waitcnt lgkmcnt(0)
	s_barrier
	s_waitcnt lgkmcnt(0)
	v_mfma_f32_16x16x32_bf16 v[60:63], v[144:147], v[186:189], v[60:63]
	v_mfma_f32_16x16x32_bf16 v[56:59], v[162:165], v[186:189], v[56:59]
	v_mfma_f32_16x16x32_bf16 v[44:47], v[144:147], v[198:201], v[44:47]
	v_mfma_f32_16x16x32_bf16 v[40:43], v[162:165], v[198:201], v[40:43]
	v_mfma_f32_16x16x32_bf16 v[28:31], v[144:147], v[206:209], v[28:31]
	v_mfma_f32_16x16x32_bf16 v[24:27], v[162:165], v[206:209], v[24:27]
	v_mfma_f32_16x16x32_bf16 v[12:15], v[144:147], v[214:217], v[12:15]
	v_mfma_f32_16x16x32_bf16 v[8:11], v[162:165], v[214:217], v[8:11]
	v_mfma_f32_16x16x32_bf16 v[60:63], v[158:161], v[194:197], v[60:63]
	v_mfma_f32_16x16x32_bf16 v[56:59], v[166:169], v[194:197], v[56:59]
	v_mfma_f32_16x16x32_bf16 v[44:47], v[158:161], v[202:205], v[44:47]
	v_mfma_f32_16x16x32_bf16 v[40:43], v[166:169], v[202:205], v[40:43]
	v_mfma_f32_16x16x32_bf16 v[28:31], v[158:161], v[210:213], v[28:31]
	v_mfma_f32_16x16x32_bf16 v[24:27], v[166:169], v[210:213], v[24:27]
	v_mfma_f32_16x16x32_bf16 v[12:15], v[158:161], v[218:221], v[12:15]
	v_mfma_f32_16x16x32_bf16 v[8:11], v[166:169], v[218:221], v[8:11]
	v_mfma_f32_16x16x32_bf16 v[52:55], v[170:173], v[186:189], v[52:55]
	v_mfma_f32_16x16x32_bf16 v[48:51], v[178:181], v[186:189], v[48:51]
	v_mfma_f32_16x16x32_bf16 v[36:39], v[170:173], v[198:201], v[36:39]
	v_mfma_f32_16x16x32_bf16 v[32:35], v[178:181], v[198:201], v[32:35]
	v_mfma_f32_16x16x32_bf16 v[20:23], v[170:173], v[206:209], v[20:23]
	v_mfma_f32_16x16x32_bf16 v[16:19], v[178:181], v[206:209], v[16:19]
	v_mfma_f32_16x16x32_bf16 v[4:7], v[170:173], v[214:217], v[4:7]
	v_mfma_f32_16x16x32_bf16 v[0:3], v[178:181], v[214:217], v[0:3]
	v_mfma_f32_16x16x32_bf16 v[52:55], v[174:177], v[194:197], v[52:55]
	v_mfma_f32_16x16x32_bf16 v[48:51], v[182:185], v[194:197], v[48:51]
	v_mfma_f32_16x16x32_bf16 v[36:39], v[174:177], v[202:205], v[36:39]
	v_mfma_f32_16x16x32_bf16 v[32:35], v[182:185], v[202:205], v[32:35]
	v_mfma_f32_16x16x32_bf16 v[20:23], v[174:177], v[210:213], v[20:23]
	v_mfma_f32_16x16x32_bf16 v[16:19], v[182:185], v[210:213], v[16:19]
	v_mfma_f32_16x16x32_bf16 v[4:7], v[174:177], v[218:221], v[4:7]
	v_mfma_f32_16x16x32_bf16 v[0:3], v[182:185], v[218:221], v[0:3]
	s_barrier
	s_add_i32 s33, 0, 0x18000
	v_add_u32_e32 v157, s33, v151
	s_add_i32 s56, 0, 0x1c000
	ds_read_b128 v[144:147], v157
	ds_read_b128 v[158:161], v157 offset:1024
	ds_read_b128 v[162:165], v157 offset:2048
	ds_read_b128 v[166:169], v157 offset:3072
	v_add_u32_e32 v157, s56, v151
	ds_read_b128 v[170:173], v157
	ds_read_b128 v[174:177], v157 offset:1024
	ds_read_b128 v[178:181], v157 offset:2048
	ds_read_b128 v[182:185], v157 offset:3072
	s_add_u32 s54, s58, 0x80000
	s_addc_u32 s55, s59, 0
	s_mov_b32 m0, s66
	v_lshl_add_u64 v[226:227], s[54:55], 0, v[128:129]
	ds_read_b128 v[186:189], v155 offset:32768
	ds_read_b128 v[194:197], v155 offset:33792
	ds_read_b128 v[198:201], v155 offset:34816
	ds_read_b128 v[202:205], v155 offset:35840
	ds_read_b128 v[206:209], v155 offset:36864
	ds_read_b128 v[210:213], v155 offset:37888
	ds_read_b128 v[214:217], v155 offset:38912
	ds_read_b128 v[218:221], v155 offset:39936
	global_load_lds_dwordx4 v[226:227], off
	v_lshl_add_u64 v[226:227], s[54:55], 0, v[132:133]
	s_mov_b32 m0, s67
	s_nop 0
	global_load_lds_dwordx4 v[226:227], off
	s_waitcnt vmcnt(8)
	s_waitcnt lgkmcnt(0)
	s_barrier
	s_waitcnt lgkmcnt(0)
	v_mfma_f32_16x16x32_bf16 v[124:127], v[144:147], v[186:189], v[124:127]
	v_mfma_f32_16x16x32_bf16 v[120:123], v[162:165], v[186:189], v[120:123]
	v_mfma_f32_16x16x32_bf16 v[108:111], v[144:147], v[198:201], v[108:111]
	v_mfma_f32_16x16x32_bf16 v[104:107], v[162:165], v[198:201], v[104:107]
	v_mfma_f32_16x16x32_bf16 v[92:95], v[144:147], v[206:209], v[92:95]
	v_mfma_f32_16x16x32_bf16 v[88:91], v[162:165], v[206:209], v[88:91]
	v_mfma_f32_16x16x32_bf16 v[76:79], v[144:147], v[214:217], v[76:79]
	v_mfma_f32_16x16x32_bf16 v[72:75], v[162:165], v[214:217], v[72:75]
	v_mfma_f32_16x16x32_bf16 v[124:127], v[158:161], v[194:197], v[124:127]
	v_mfma_f32_16x16x32_bf16 v[120:123], v[166:169], v[194:197], v[120:123]
	v_mfma_f32_16x16x32_bf16 v[108:111], v[158:161], v[202:205], v[108:111]
	v_mfma_f32_16x16x32_bf16 v[104:107], v[166:169], v[202:205], v[104:107]
	v_mfma_f32_16x16x32_bf16 v[92:95], v[158:161], v[210:213], v[92:95]
	v_mfma_f32_16x16x32_bf16 v[88:91], v[166:169], v[210:213], v[88:91]
	v_mfma_f32_16x16x32_bf16 v[76:79], v[158:161], v[218:221], v[76:79]
	v_mfma_f32_16x16x32_bf16 v[72:75], v[166:169], v[218:221], v[72:75]
	v_mfma_f32_16x16x32_bf16 v[116:119], v[170:173], v[186:189], v[116:119]
	v_mfma_f32_16x16x32_bf16 v[112:115], v[178:181], v[186:189], v[112:115]
	v_mfma_f32_16x16x32_bf16 v[100:103], v[170:173], v[198:201], v[100:103]
	v_mfma_f32_16x16x32_bf16 v[96:99], v[178:181], v[198:201], v[96:99]
	v_mfma_f32_16x16x32_bf16 v[84:87], v[170:173], v[206:209], v[84:87]
	v_mfma_f32_16x16x32_bf16 v[80:83], v[178:181], v[206:209], v[80:83]
	v_mfma_f32_16x16x32_bf16 v[68:71], v[170:173], v[214:217], v[68:71]
	v_mfma_f32_16x16x32_bf16 v[64:67], v[178:181], v[214:217], v[64:67]
	v_mfma_f32_16x16x32_bf16 v[116:119], v[174:177], v[194:197], v[116:119]
	v_mfma_f32_16x16x32_bf16 v[112:115], v[182:185], v[194:197], v[112:115]
	v_mfma_f32_16x16x32_bf16 v[100:103], v[174:177], v[202:205], v[100:103]
	v_mfma_f32_16x16x32_bf16 v[96:99], v[182:185], v[202:205], v[96:99]
	v_mfma_f32_16x16x32_bf16 v[84:87], v[174:177], v[210:213], v[84:87]
	v_mfma_f32_16x16x32_bf16 v[80:83], v[182:185], v[210:213], v[80:83]
	v_mfma_f32_16x16x32_bf16 v[68:71], v[174:177], v[218:221], v[68:71]
	v_mfma_f32_16x16x32_bf16 v[64:67], v[182:185], v[218:221], v[64:67]
	s_barrier
	s_add_i32 s33, s33, s64
	v_lshl_add_u64 v[148:149], v[148:149], 0, s[18:19]
	s_mov_b32 m0, s33
	ds_read_b128 v[186:189], v155 offset:49152
	ds_read_b128 v[194:197], v155 offset:50176
	ds_read_b128 v[198:201], v155 offset:51200
	ds_read_b128 v[202:205], v155 offset:52224
	ds_read_b128 v[206:209], v155 offset:53248
	ds_read_b128 v[210:213], v155 offset:54272
	ds_read_b128 v[214:217], v155 offset:55296
	ds_read_b128 v[218:221], v155 offset:56320
	global_load_lds_dwordx4 v[148:149], off
	s_add_i32 m0, s33, 0x2000
	s_add_u32 s50, s50, 0x80080
	v_lshl_add_u64 v[148:149], v[190:191], 0, s[18:19]
	s_addc_u32 s51, s51, 0
	s_add_i32 s33, s56, s64
	global_load_lds_dwordx4 v[148:149], off
	v_lshl_add_u64 v[148:149], s[50:51], 0, v[130:131]
	s_mov_b32 m0, s33
	s_nop 0
	global_load_lds_dwordx4 v[148:149], off
	v_lshl_add_u64 v[148:149], s[50:51], 0, v[134:135]
	s_add_i32 m0, s33, 0x2000
	s_nop 0
	global_load_lds_dwordx4 v[148:149], off
	v_lshl_add_u64 v[148:149], v[222:223], 0, s[18:19]
	s_mov_b32 m0, s69
	s_nop 0
	global_load_lds_dwordx4 v[148:149], off
	v_lshl_add_u64 v[148:149], v[224:225], 0, s[18:19]
	s_mov_b32 m0, s70
	s_nop 0
	global_load_lds_dwordx4 v[148:149], off
	s_waitcnt vmcnt(8)
	s_waitcnt lgkmcnt(0)
	s_barrier
	s_waitcnt lgkmcnt(0)
	v_mfma_f32_16x16x32_bf16 v[60:63], v[144:147], v[186:189], v[60:63]
	v_mfma_f32_16x16x32_bf16 v[56:59], v[162:165], v[186:189], v[56:59]
	v_mfma_f32_16x16x32_bf16 v[44:47], v[144:147], v[198:201], v[44:47]
	v_mfma_f32_16x16x32_bf16 v[40:43], v[162:165], v[198:201], v[40:43]
	v_mfma_f32_16x16x32_bf16 v[28:31], v[144:147], v[206:209], v[28:31]
	v_mfma_f32_16x16x32_bf16 v[24:27], v[162:165], v[206:209], v[24:27]
	v_mfma_f32_16x16x32_bf16 v[12:15], v[144:147], v[214:217], v[12:15]
	v_mfma_f32_16x16x32_bf16 v[8:11], v[162:165], v[214:217], v[8:11]
	v_mfma_f32_16x16x32_bf16 v[60:63], v[158:161], v[194:197], v[60:63]
	v_mfma_f32_16x16x32_bf16 v[56:59], v[166:169], v[194:197], v[56:59]
	v_mfma_f32_16x16x32_bf16 v[44:47], v[158:161], v[202:205], v[44:47]
	v_mfma_f32_16x16x32_bf16 v[40:43], v[166:169], v[202:205], v[40:43]
	v_mfma_f32_16x16x32_bf16 v[28:31], v[158:161], v[210:213], v[28:31]
	v_mfma_f32_16x16x32_bf16 v[24:27], v[166:169], v[210:213], v[24:27]
	v_mfma_f32_16x16x32_bf16 v[12:15], v[158:161], v[218:221], v[12:15]
	v_mfma_f32_16x16x32_bf16 v[8:11], v[166:169], v[218:221], v[8:11]
	v_mfma_f32_16x16x32_bf16 v[52:55], v[170:173], v[186:189], v[52:55]
	v_mfma_f32_16x16x32_bf16 v[48:51], v[178:181], v[186:189], v[48:51]
	v_mfma_f32_16x16x32_bf16 v[36:39], v[170:173], v[198:201], v[36:39]
	v_mfma_f32_16x16x32_bf16 v[32:35], v[178:181], v[198:201], v[32:35]
	v_mfma_f32_16x16x32_bf16 v[20:23], v[170:173], v[206:209], v[20:23]
	v_mfma_f32_16x16x32_bf16 v[16:19], v[178:181], v[206:209], v[16:19]
	v_mfma_f32_16x16x32_bf16 v[4:7], v[170:173], v[214:217], v[4:7]
	v_mfma_f32_16x16x32_bf16 v[0:3], v[178:181], v[214:217], v[0:3]
	v_mfma_f32_16x16x32_bf16 v[52:55], v[174:177], v[194:197], v[52:55]
	v_mfma_f32_16x16x32_bf16 v[48:51], v[182:185], v[194:197], v[48:51]
	v_mfma_f32_16x16x32_bf16 v[36:39], v[174:177], v[202:205], v[36:39]
	v_mfma_f32_16x16x32_bf16 v[32:35], v[182:185], v[202:205], v[32:35]
	v_mfma_f32_16x16x32_bf16 v[20:23], v[174:177], v[210:213], v[20:23]
	v_mfma_f32_16x16x32_bf16 v[16:19], v[182:185], v[210:213], v[16:19]
	v_mfma_f32_16x16x32_bf16 v[4:7], v[174:177], v[218:221], v[4:7]
	v_mfma_f32_16x16x32_bf16 v[0:3], v[182:185], v[218:221], v[0:3]
	s_barrier
	s_add_i32 s77, s77, 2
	s_add_u32 s48, s48, 0x100
	s_addc_u32 s49, s49, 0
	s_add_u32 s74, s74, 0x100
	s_addc_u32 s75, s75, 0
	s_cmp_gt_u32 s77, 29
	s_cbranch_scc0 .LBB0_589
	s_and_b64 vcc, exec, s[20:21]
	s_cbranch_vccz .LBB0_592
	s_barrier
.LBB0_592:
	v_lshl_add_u32 v148, s40, 8, v150
	v_lshl_or_b32 v146, s42, 8, v152
	v_ashrrev_i32_e32 v149, 31, v148
	v_ashrrev_i32_e32 v147, 31, v146
	v_lshlrev_b64 v[144:145], 11, v[148:149]
	v_lshl_add_u64 v[144:145], v[144:145], 0, v[146:147]
	v_lshl_add_u64 v[166:167], v[144:145], 2, s[10:11]
	global_load_dwordx4 v[158:161], v[166:167], off nt
	global_load_dwordx4 v[162:165], v[166:167], off offset:16 nt
	v_lshl_add_u64 v[168:169], v[144:145], 1, s[14:15]
	v_xor_b32_e32 v157, 32, v156
	s_waitcnt vmcnt(0)
	v_pk_add_f32 v[126:127], v[126:127], v[160:161]
	v_pk_add_f32 v[170:171], v[124:125], v[158:159]
	v_pk_add_f32 v[164:165], v[122:123], v[164:165]
	v_pk_add_f32 v[162:163], v[120:121], v[162:163]
	v_cvt_pk_bf16_f32 v120, v170, v171
	v_cvt_pk_bf16_f32 v121, v126, v127
	v_mul_f32_e32 v127, v127, v127
	v_cvt_pk_bf16_f32 v122, v162, v163
	v_cvt_pk_bf16_f32 v123, v164, v165
	global_store_dwordx4 v[168:169], v[120:123], off
	global_load_dwordx4 v[122:125], v[166:167], off offset:512 nt
	s_nop 0
	global_load_dwordx4 v[158:161], v[166:167], off offset:528 nt
	v_mul_f32_e32 v166, v171, v171
	v_mul_f32_e32 v163, v163, v163
	v_fmac_f32_e32 v166, v170, v170
	v_fmac_f32_e32 v127, v126, v126
	v_mul_f32_e32 v165, v165, v165
	v_fmac_f32_e32 v163, v162, v162
	v_add_f32_e32 v126, v166, v127
	v_fmac_f32_e32 v165, v164, v164
	v_add_f32_e32 v126, v126, v163
	v_add_f32_e32 v162, v165, v126
	v_and_b32_e32 v121, 64, v156
	v_xor_b32_e32 v120, 16, v156
	v_add_u32_e32 v121, 64, v121
	v_cmp_lt_i32_e32 vcc, v120, v121
	s_waitcnt vmcnt(1)
	v_pk_add_f32 v[118:119], v[118:119], v[124:125]
	v_pk_add_f32 v[116:117], v[116:117], v[122:123]
	s_waitcnt vmcnt(0)
	v_pk_add_f32 v[126:127], v[114:115], v[160:161]
	v_pk_add_f32 v[112:113], v[112:113], v[158:159]
	v_mul_f32_e32 v114, v117, v117
	v_mul_f32_e32 v115, v119, v119
	v_mul_f32_e32 v122, v113, v113
	v_fmac_f32_e32 v114, v116, v116
	v_fmac_f32_e32 v115, v118, v118
	v_mul_f32_e32 v123, v127, v127
	v_fmac_f32_e32 v122, v112, v112
	v_add_f32_e32 v114, v114, v115
	v_fmac_f32_e32 v123, v126, v126
	v_add_f32_e32 v114, v114, v122
	v_cndmask_b32_e32 v120, v156, v120, vcc
	v_add_f32_e32 v114, v123, v114
	v_lshlrev_b32_e32 v120, 2, v120
	v_add_f32_e32 v114, v162, v114
	ds_bpermute_b32 v115, v120, v114
	v_cmp_lt_i32_e32 vcc, v157, v121
	v_cvt_pk_bf16_f32 v122, v116, v117
	v_cvt_pk_bf16_f32 v123, v118, v119
	v_cvt_pk_bf16_f32 v124, v112, v113
	s_waitcnt lgkmcnt(0)
	v_add_f32_e32 v115, v114, v115
	v_lshl_add_u64 v[112:113], v[148:149], 2, s[16:17]
	v_cndmask_b32_e32 v121, v156, v157, vcc
	v_lshlrev_b32_e32 v114, 2, v121
	ds_bpermute_b32 v116, v114, v115
	v_cvt_pk_bf16_f32 v125, v126, v127
	global_store_dwordx4 v[168:169], v[122:125], off offset:256
	s_and_saveexec_b64 s[40:41], s[6:7]
	s_cbranch_execz .LBB0_594
	s_waitcnt lgkmcnt(0)
	v_add_f32_e32 v115, v115, v116
	global_atomic_add_f32 v[112:113], v115, off
.LBB0_594:
	s_or_b64 exec, exec, s[40:41]
	s_waitcnt lgkmcnt(0)
	v_or_b32_e32 v116, 16, v148
	v_ashrrev_i32_e32 v117, 31, v116
	v_lshlrev_b64 v[116:117], 11, v[116:117]
	v_lshl_add_u64 v[126:127], v[116:117], 0, v[146:147]
	v_lshl_add_u64 v[158:159], v[126:127], 2, s[10:11]
	global_load_dwordx4 v[116:119], v[158:159], off nt
	global_load_dwordx4 v[122:125], v[158:159], off offset:16 nt
	v_lshl_add_u64 v[126:127], v[126:127], 1, s[14:15]
	s_waitcnt vmcnt(1)
	v_pk_add_f32 v[118:119], v[110:111], v[118:119]
	v_pk_add_f32 v[116:117], v[108:109], v[116:117]
	s_waitcnt vmcnt(0)
	v_pk_add_f32 v[124:125], v[106:107], v[124:125]
	v_pk_add_f32 v[122:123], v[104:105], v[122:123]
	v_cvt_pk_bf16_f32 v104, v116, v117
	v_cvt_pk_bf16_f32 v105, v118, v119
	v_mul_f32_e32 v115, v117, v117
	v_cvt_pk_bf16_f32 v106, v122, v123
	v_cvt_pk_bf16_f32 v107, v124, v125
	global_store_dwordx4 v[126:127], v[104:107], off
	global_load_dwordx4 v[104:107], v[158:159], off offset:512 nt
	s_nop 0
	global_load_dwordx4 v[108:111], v[158:159], off offset:528 nt
	v_mul_f32_e32 v117, v119, v119
	v_mul_f32_e32 v119, v123, v123
	v_fmac_f32_e32 v115, v116, v116
	v_fmac_f32_e32 v117, v118, v118
	v_mul_f32_e32 v121, v125, v125
	v_fmac_f32_e32 v119, v122, v122
	v_add_f32_e32 v115, v115, v117
	v_fmac_f32_e32 v121, v124, v124
	v_add_f32_e32 v115, v115, v119
	v_add_f32_e32 v115, v121, v115
	s_waitcnt vmcnt(1)
	v_pk_add_f32 v[102:103], v[102:103], v[106:107]
	v_pk_add_f32 v[100:101], v[100:101], v[104:105]
	s_waitcnt vmcnt(0)
	v_pk_add_f32 v[106:107], v[96:97], v[108:109]
	v_mul_f32_e32 v96, v101, v101
	v_mul_f32_e32 v97, v103, v103
	v_pk_add_f32 v[104:105], v[98:99], v[110:111]
	v_mul_f32_e32 v98, v107, v107
	v_fmac_f32_e32 v96, v100, v100
	v_fmac_f32_e32 v97, v102, v102
	v_mul_f32_e32 v99, v105, v105
	v_fmac_f32_e32 v98, v106, v106
	v_add_f32_e32 v96, v96, v97
	v_add_f32_e32 v96, v96, v98
	v_fmac_f32_e32 v99, v104, v104
	v_add_f32_e32 v96, v99, v96
	v_add_f32_e32 v96, v115, v96
	ds_bpermute_b32 v97, v120, v96
	v_cvt_pk_bf16_f32 v98, v100, v101
	v_cvt_pk_bf16_f32 v99, v102, v103
	v_cvt_pk_bf16_f32 v100, v106, v107
	v_cvt_pk_bf16_f32 v101, v104, v105
	s_waitcnt lgkmcnt(0)
	v_add_f32_e32 v96, v96, v97
	ds_bpermute_b32 v97, v114, v96
	global_store_dwordx4 v[126:127], v[98:101], off offset:256
	s_and_saveexec_b64 s[40:41], s[6:7]
	s_cbranch_execz .LBB0_596
	s_waitcnt lgkmcnt(0)
	v_add_f32_e32 v96, v96, v97
	global_atomic_add_f32 v[112:113], v96, off offset:64
.LBB0_596:
	s_or_b64 exec, exec, s[40:41]
	v_or_b32_e32 v96, 32, v148
	s_waitcnt lgkmcnt(0)
	v_ashrrev_i32_e32 v97, 31, v96
	v_lshlrev_b64 v[96:97], 11, v[96:97]
	v_lshl_add_u64 v[104:105], v[96:97], 0, v[146:147]
	v_lshl_add_u64 v[106:107], v[104:105], 2, s[10:11]
	global_load_dwordx4 v[96:99], v[106:107], off nt
	global_load_dwordx4 v[100:103], v[106:107], off offset:16 nt
	v_lshl_add_u64 v[104:105], v[104:105], 1, s[14:15]
	s_waitcnt vmcnt(1)
	v_pk_add_f32 v[98:99], v[94:95], v[98:99]
	v_pk_add_f32 v[96:97], v[92:93], v[96:97]
	s_waitcnt vmcnt(0)
	v_pk_add_f32 v[102:103], v[90:91], v[102:103]
	v_pk_add_f32 v[100:101], v[88:89], v[100:101]
	v_cvt_pk_bf16_f32 v88, v96, v97
	v_cvt_pk_bf16_f32 v89, v98, v99
	v_mul_f32_e32 v97, v97, v97
	v_cvt_pk_bf16_f32 v90, v100, v101
	v_cvt_pk_bf16_f32 v91, v102, v103
	global_store_dwordx4 v[104:105], v[88:91], off
	global_load_dwordx4 v[88:91], v[106:107], off offset:512 nt
	s_nop 0
	global_load_dwordx4 v[92:95], v[106:107], off offset:528 nt
	v_mul_f32_e32 v99, v99, v99
	v_mul_f32_e32 v101, v101, v101
	v_fmac_f32_e32 v97, v96, v96
	v_fmac_f32_e32 v99, v98, v98
	v_mul_f32_e32 v103, v103, v103
	v_fmac_f32_e32 v101, v100, v100
	v_add_f32_e32 v96, v97, v99
	v_fmac_f32_e32 v103, v102, v102
	v_add_f32_e32 v96, v96, v101
	v_add_f32_e32 v96, v103, v96
	s_waitcnt vmcnt(1)
	v_pk_add_f32 v[86:87], v[86:87], v[90:91]
	v_pk_add_f32 v[84:85], v[84:85], v[88:89]
	s_waitcnt vmcnt(0)
	v_pk_add_f32 v[90:91], v[80:81], v[92:93]
	v_mul_f32_e32 v80, v85, v85
	v_mul_f32_e32 v81, v87, v87
	v_pk_add_f32 v[88:89], v[82:83], v[94:95]
	v_mul_f32_e32 v82, v91, v91
	v_fmac_f32_e32 v80, v84, v84
	v_fmac_f32_e32 v81, v86, v86
	v_mul_f32_e32 v83, v89, v89
	v_fmac_f32_e32 v82, v90, v90
	v_add_f32_e32 v80, v80, v81
	v_add_f32_e32 v80, v80, v82
	v_fmac_f32_e32 v83, v88, v88
	v_add_f32_e32 v80, v83, v80
	v_add_f32_e32 v80, v96, v80
	ds_bpermute_b32 v81, v120, v80
	v_cvt_pk_bf16_f32 v82, v84, v85
	v_cvt_pk_bf16_f32 v83, v86, v87
	v_cvt_pk_bf16_f32 v84, v90, v91
	v_cvt_pk_bf16_f32 v85, v88, v89
	s_waitcnt lgkmcnt(0)
	v_add_f32_e32 v80, v80, v81
	ds_bpermute_b32 v81, v114, v80
	global_store_dwordx4 v[104:105], v[82:85], off offset:256
	s_and_saveexec_b64 s[40:41], s[6:7]
	s_cbranch_execz .LBB0_598
	s_waitcnt lgkmcnt(0)
	v_add_f32_e32 v80, v80, v81
	global_atomic_add_f32 v[112:113], v80, off offset:128
.LBB0_598:
	s_or_b64 exec, exec, s[40:41]
	v_or_b32_e32 v80, 48, v148
	s_waitcnt lgkmcnt(0)
	v_ashrrev_i32_e32 v81, 31, v80
	v_lshlrev_b64 v[80:81], 11, v[80:81]
	v_lshl_add_u64 v[88:89], v[80:81], 0, v[146:147]
	v_lshl_add_u64 v[90:91], v[88:89], 2, s[10:11]
	global_load_dwordx4 v[80:83], v[90:91], off nt
	global_load_dwordx4 v[84:87], v[90:91], off offset:16 nt
	v_lshl_add_u64 v[88:89], v[88:89], 1, s[14:15]
	s_waitcnt vmcnt(1)
	v_pk_add_f32 v[82:83], v[78:79], v[82:83]
	v_pk_add_f32 v[80:81], v[76:77], v[80:81]
	s_waitcnt vmcnt(0)
	v_pk_add_f32 v[86:87], v[74:75], v[86:87]
	v_pk_add_f32 v[84:85], v[72:73], v[84:85]
	v_cvt_pk_bf16_f32 v72, v80, v81
	v_cvt_pk_bf16_f32 v73, v82, v83
	v_mul_f32_e32 v81, v81, v81
	v_cvt_pk_bf16_f32 v74, v84, v85
	v_cvt_pk_bf16_f32 v75, v86, v87
	global_store_dwordx4 v[88:89], v[72:75], off
	global_load_dwordx4 v[72:75], v[90:91], off offset:512 nt
	s_nop 0
	global_load_dwordx4 v[76:79], v[90:91], off offset:528 nt
	v_mul_f32_e32 v83, v83, v83
	v_mul_f32_e32 v85, v85, v85
	v_fmac_f32_e32 v81, v80, v80
	v_fmac_f32_e32 v83, v82, v82
	v_mul_f32_e32 v87, v87, v87
	v_fmac_f32_e32 v85, v84, v84
	v_add_f32_e32 v80, v81, v83
	v_fmac_f32_e32 v87, v86, v86
	v_add_f32_e32 v80, v80, v85
	v_add_f32_e32 v80, v87, v80
	s_waitcnt vmcnt(1)
	v_pk_add_f32 v[70:71], v[70:71], v[74:75]
	v_pk_add_f32 v[68:69], v[68:69], v[72:73]
	s_waitcnt vmcnt(0)
	v_pk_add_f32 v[74:75], v[64:65], v[76:77]
	v_mul_f32_e32 v64, v69, v69
	v_mul_f32_e32 v65, v71, v71
	v_pk_add_f32 v[72:73], v[66:67], v[78:79]
	v_mul_f32_e32 v66, v75, v75
	v_fmac_f32_e32 v64, v68, v68
	v_fmac_f32_e32 v65, v70, v70
	v_mul_f32_e32 v67, v73, v73
	v_fmac_f32_e32 v66, v74, v74
	v_add_f32_e32 v64, v64, v65
	v_add_f32_e32 v64, v64, v66
	v_fmac_f32_e32 v67, v72, v72
	v_add_f32_e32 v64, v67, v64
	v_add_f32_e32 v64, v80, v64
	ds_bpermute_b32 v65, v120, v64
	v_cvt_pk_bf16_f32 v66, v68, v69
	v_cvt_pk_bf16_f32 v67, v70, v71
	v_cvt_pk_bf16_f32 v68, v74, v75
	v_cvt_pk_bf16_f32 v69, v72, v73
	s_waitcnt lgkmcnt(0)
	v_add_f32_e32 v64, v64, v65
	ds_bpermute_b32 v65, v114, v64
	global_store_dwordx4 v[88:89], v[66:69], off offset:256
	s_and_saveexec_b64 s[40:41], s[6:7]
	s_cbranch_execz .LBB0_600
	s_waitcnt lgkmcnt(0)
	v_add_f32_e32 v64, v64, v65
	global_atomic_add_f32 v[112:113], v64, off offset:192
.LBB0_600:
	s_or_b64 exec, exec, s[40:41]
	v_lshl_add_u64 v[72:73], v[144:145], 0, s[22:23]
	v_lshl_add_u64 v[74:75], v[72:73], 2, s[10:11]
	s_waitcnt lgkmcnt(0)
	global_load_dwordx4 v[64:67], v[74:75], off nt
	global_load_dwordx4 v[68:71], v[74:75], off offset:16 nt
	v_lshl_add_u64 v[72:73], v[72:73], 1, s[14:15]
	s_waitcnt vmcnt(1)
	v_pk_add_f32 v[66:67], v[62:63], v[66:67]
	v_pk_add_f32 v[64:65], v[60:61], v[64:65]
	s_waitcnt vmcnt(0)
	v_pk_add_f32 v[70:71], v[58:59], v[70:71]
	v_pk_add_f32 v[68:69], v[56:57], v[68:69]
	v_cvt_pk_bf16_f32 v56, v64, v65
	v_cvt_pk_bf16_f32 v57, v66, v67
	v_mul_f32_e32 v65, v65, v65
	v_cvt_pk_bf16_f32 v58, v68, v69
	v_cvt_pk_bf16_f32 v59, v70, v71
	global_store_dwordx4 v[72:73], v[56:59], off
	global_load_dwordx4 v[56:59], v[74:75], off offset:512 nt
	s_nop 0
	global_load_dwordx4 v[60:63], v[74:75], off offset:528 nt
	v_mul_f32_e32 v67, v67, v67
	v_mul_f32_e32 v69, v69, v69
	v_fmac_f32_e32 v65, v64, v64
	v_fmac_f32_e32 v67, v66, v66
	v_mul_f32_e32 v71, v71, v71
	v_fmac_f32_e32 v69, v68, v68
	v_add_f32_e32 v64, v65, v67
	v_fmac_f32_e32 v71, v70, v70
	v_add_f32_e32 v64, v64, v69
	v_add_f32_e32 v64, v71, v64
	s_waitcnt vmcnt(1)
	v_pk_add_f32 v[54:55], v[54:55], v[58:59]
	v_pk_add_f32 v[52:53], v[52:53], v[56:57]
	s_waitcnt vmcnt(0)
	v_pk_add_f32 v[58:59], v[48:49], v[60:61]
	v_mul_f32_e32 v48, v53, v53
	v_mul_f32_e32 v49, v55, v55
	v_pk_add_f32 v[56:57], v[50:51], v[62:63]
	v_mul_f32_e32 v50, v59, v59
	v_fmac_f32_e32 v48, v52, v52
	v_fmac_f32_e32 v49, v54, v54
	v_mul_f32_e32 v51, v57, v57
	v_fmac_f32_e32 v50, v58, v58
	v_add_f32_e32 v48, v48, v49
	v_add_f32_e32 v48, v48, v50
	v_fmac_f32_e32 v51, v56, v56
	v_add_f32_e32 v48, v51, v48
	v_add_f32_e32 v48, v64, v48
	ds_bpermute_b32 v49, v120, v48
	v_cvt_pk_bf16_f32 v50, v52, v53
	v_cvt_pk_bf16_f32 v51, v54, v55
	v_cvt_pk_bf16_f32 v52, v58, v59
	v_cvt_pk_bf16_f32 v53, v56, v57
	s_waitcnt lgkmcnt(0)
	v_add_f32_e32 v48, v48, v49
	ds_bpermute_b32 v49, v114, v48
	global_store_dwordx4 v[72:73], v[50:53], off offset:256
	s_and_saveexec_b64 s[40:41], s[6:7]
	s_cbranch_execz .LBB0_602
	s_waitcnt lgkmcnt(0)
	v_add_f32_e32 v48, v48, v49
	global_atomic_add_f32 v[112:113], v48, off offset:512
.LBB0_602:
	s_or_b64 exec, exec, s[40:41]
	v_lshl_add_u64 v[56:57], v[144:145], 0, s[24:25]
	v_lshl_add_u64 v[58:59], v[56:57], 2, s[10:11]
	s_waitcnt lgkmcnt(0)
	global_load_dwordx4 v[48:51], v[58:59], off nt
	global_load_dwordx4 v[52:55], v[58:59], off offset:16 nt
	v_lshl_add_u64 v[56:57], v[56:57], 1, s[14:15]
	s_waitcnt vmcnt(1)
	v_pk_add_f32 v[50:51], v[46:47], v[50:51]
	v_pk_add_f32 v[48:49], v[44:45], v[48:49]
	s_waitcnt vmcnt(0)
	v_pk_add_f32 v[54:55], v[42:43], v[54:55]
	v_pk_add_f32 v[52:53], v[40:41], v[52:53]
	v_cvt_pk_bf16_f32 v40, v48, v49
	v_cvt_pk_bf16_f32 v41, v50, v51
	v_mul_f32_e32 v49, v49, v49
	v_cvt_pk_bf16_f32 v42, v52, v53
	v_cvt_pk_bf16_f32 v43, v54, v55
	global_store_dwordx4 v[56:57], v[40:43], off
	global_load_dwordx4 v[40:43], v[58:59], off offset:512 nt
	s_nop 0
	global_load_dwordx4 v[44:47], v[58:59], off offset:528 nt
	v_mul_f32_e32 v51, v51, v51
	v_mul_f32_e32 v53, v53, v53
	v_fmac_f32_e32 v49, v48, v48
	v_fmac_f32_e32 v51, v50, v50
	v_mul_f32_e32 v55, v55, v55
	v_fmac_f32_e32 v53, v52, v52
	v_add_f32_e32 v48, v49, v51
	v_fmac_f32_e32 v55, v54, v54
	v_add_f32_e32 v48, v48, v53
	v_add_f32_e32 v48, v55, v48
	s_waitcnt vmcnt(1)
	v_pk_add_f32 v[38:39], v[38:39], v[42:43]
	v_pk_add_f32 v[36:37], v[36:37], v[40:41]
	s_waitcnt vmcnt(0)
	v_pk_add_f32 v[42:43], v[32:33], v[44:45]
	v_mul_f32_e32 v32, v37, v37
	v_mul_f32_e32 v33, v39, v39
	v_pk_add_f32 v[40:41], v[34:35], v[46:47]
	v_mul_f32_e32 v34, v43, v43
	v_fmac_f32_e32 v32, v36, v36
	v_fmac_f32_e32 v33, v38, v38
	v_mul_f32_e32 v35, v41, v41
	v_fmac_f32_e32 v34, v42, v42
	v_add_f32_e32 v32, v32, v33
	v_add_f32_e32 v32, v32, v34
	v_fmac_f32_e32 v35, v40, v40
	v_add_f32_e32 v32, v35, v32
	v_add_f32_e32 v32, v48, v32
	ds_bpermute_b32 v33, v120, v32
	v_cvt_pk_bf16_f32 v34, v36, v37
	v_cvt_pk_bf16_f32 v35, v38, v39
	v_cvt_pk_bf16_f32 v36, v42, v43
	v_cvt_pk_bf16_f32 v37, v40, v41
	s_waitcnt lgkmcnt(0)
	v_add_f32_e32 v32, v32, v33
	ds_bpermute_b32 v33, v114, v32
	global_store_dwordx4 v[56:57], v[34:37], off offset:256
	s_and_saveexec_b64 s[40:41], s[6:7]
	s_cbranch_execz .LBB0_604
	s_waitcnt lgkmcnt(0)
	v_add_f32_e32 v32, v32, v33
	global_atomic_add_f32 v[112:113], v32, off offset:576
.LBB0_604:
	s_or_b64 exec, exec, s[40:41]
	v_lshl_add_u64 v[40:41], v[144:145], 0, s[26:27]
	v_lshl_add_u64 v[42:43], v[40:41], 2, s[10:11]
	s_waitcnt lgkmcnt(0)
	global_load_dwordx4 v[32:35], v[42:43], off nt
	global_load_dwordx4 v[36:39], v[42:43], off offset:16 nt
	v_lshl_add_u64 v[40:41], v[40:41], 1, s[14:15]
	s_waitcnt vmcnt(1)
	v_pk_add_f32 v[34:35], v[30:31], v[34:35]
	v_pk_add_f32 v[32:33], v[28:29], v[32:33]
	s_waitcnt vmcnt(0)
	v_pk_add_f32 v[38:39], v[26:27], v[38:39]
	v_pk_add_f32 v[36:37], v[24:25], v[36:37]
	v_cvt_pk_bf16_f32 v24, v32, v33
	v_cvt_pk_bf16_f32 v25, v34, v35
	v_mul_f32_e32 v33, v33, v33
	v_cvt_pk_bf16_f32 v26, v36, v37
	v_cvt_pk_bf16_f32 v27, v38, v39
	global_store_dwordx4 v[40:41], v[24:27], off
	global_load_dwordx4 v[24:27], v[42:43], off offset:512 nt
	s_nop 0
	global_load_dwordx4 v[28:31], v[42:43], off offset:528 nt
	v_mul_f32_e32 v35, v35, v35
	v_mul_f32_e32 v37, v37, v37
	v_fmac_f32_e32 v33, v32, v32
	v_fmac_f32_e32 v35, v34, v34
	v_mul_f32_e32 v39, v39, v39
	v_fmac_f32_e32 v37, v36, v36
	v_add_f32_e32 v32, v33, v35
	v_fmac_f32_e32 v39, v38, v38
	v_add_f32_e32 v32, v32, v37
	v_add_f32_e32 v32, v39, v32
	s_waitcnt vmcnt(1)
	v_pk_add_f32 v[22:23], v[22:23], v[26:27]
	v_pk_add_f32 v[20:21], v[20:21], v[24:25]
	s_waitcnt vmcnt(0)
	v_pk_add_f32 v[26:27], v[16:17], v[28:29]
	v_mul_f32_e32 v16, v21, v21
	v_mul_f32_e32 v17, v23, v23
	v_pk_add_f32 v[24:25], v[18:19], v[30:31]
	v_mul_f32_e32 v18, v27, v27
	v_fmac_f32_e32 v16, v20, v20
	v_fmac_f32_e32 v17, v22, v22
	v_mul_f32_e32 v19, v25, v25
	v_fmac_f32_e32 v18, v26, v26
	v_add_f32_e32 v16, v16, v17
	v_add_f32_e32 v16, v16, v18
	v_fmac_f32_e32 v19, v24, v24
	v_add_f32_e32 v16, v19, v16
	v_add_f32_e32 v16, v32, v16
	ds_bpermute_b32 v17, v120, v16
	v_cvt_pk_bf16_f32 v18, v20, v21
	v_cvt_pk_bf16_f32 v19, v22, v23
	v_cvt_pk_bf16_f32 v20, v26, v27
	v_cvt_pk_bf16_f32 v21, v24, v25
	s_waitcnt lgkmcnt(0)
	v_add_f32_e32 v16, v16, v17
	ds_bpermute_b32 v17, v114, v16
	global_store_dwordx4 v[40:41], v[18:21], off offset:256
	s_and_saveexec_b64 s[40:41], s[6:7]
	s_cbranch_execz .LBB0_606
	s_waitcnt lgkmcnt(0)
	v_add_f32_e32 v16, v16, v17
	global_atomic_add_f32 v[112:113], v16, off offset:640
.LBB0_606:
	s_or_b64 exec, exec, s[40:41]
	v_lshl_add_u64 v[24:25], v[144:145], 0, s[28:29]
	v_lshl_add_u64 v[26:27], v[24:25], 2, s[10:11]
	s_waitcnt lgkmcnt(0)
	global_load_dwordx4 v[16:19], v[26:27], off nt
	global_load_dwordx4 v[20:23], v[26:27], off offset:16 nt
	v_lshl_add_u64 v[24:25], v[24:25], 1, s[14:15]
	s_waitcnt vmcnt(1)
	v_pk_add_f32 v[18:19], v[14:15], v[18:19]
	v_pk_add_f32 v[16:17], v[12:13], v[16:17]
	s_waitcnt vmcnt(0)
	v_pk_add_f32 v[22:23], v[10:11], v[22:23]
	v_pk_add_f32 v[20:21], v[8:9], v[20:21]
	v_cvt_pk_bf16_f32 v8, v16, v17
	v_cvt_pk_bf16_f32 v9, v18, v19
	v_mul_f32_e32 v17, v17, v17
	v_cvt_pk_bf16_f32 v10, v20, v21
	v_cvt_pk_bf16_f32 v11, v22, v23
	global_store_dwordx4 v[24:25], v[8:11], off
	global_load_dwordx4 v[8:11], v[26:27], off offset:512 nt
	s_nop 0
	global_load_dwordx4 v[12:15], v[26:27], off offset:528 nt
	v_mul_f32_e32 v19, v19, v19
	v_mul_f32_e32 v21, v21, v21
	v_fmac_f32_e32 v17, v16, v16
	v_fmac_f32_e32 v19, v18, v18
	v_mul_f32_e32 v23, v23, v23
	v_fmac_f32_e32 v21, v20, v20
	v_add_f32_e32 v16, v17, v19
	v_fmac_f32_e32 v23, v22, v22
	v_add_f32_e32 v16, v16, v21
	v_add_f32_e32 v16, v23, v16
	s_waitcnt vmcnt(1)
	v_pk_add_f32 v[6:7], v[6:7], v[10:11]
	v_pk_add_f32 v[4:5], v[4:5], v[8:9]
	s_waitcnt vmcnt(0)
	v_pk_add_f32 v[10:11], v[0:1], v[12:13]
	v_mul_f32_e32 v0, v5, v5
	v_mul_f32_e32 v1, v7, v7
	v_pk_add_f32 v[8:9], v[2:3], v[14:15]
	v_mul_f32_e32 v2, v11, v11
	v_fmac_f32_e32 v0, v4, v4
	v_fmac_f32_e32 v1, v6, v6
	v_mul_f32_e32 v3, v9, v9
	v_fmac_f32_e32 v2, v10, v10
	v_add_f32_e32 v0, v0, v1
	v_add_f32_e32 v0, v0, v2
	v_fmac_f32_e32 v3, v8, v8
	v_add_f32_e32 v0, v3, v0
	v_add_f32_e32 v0, v16, v0
	ds_bpermute_b32 v1, v120, v0
	v_cvt_pk_bf16_f32 v2, v4, v5
	v_cvt_pk_bf16_f32 v3, v6, v7
	v_cvt_pk_bf16_f32 v4, v10, v11
	v_cvt_pk_bf16_f32 v5, v8, v9
	s_waitcnt lgkmcnt(0)
	v_add_f32_e32 v0, v0, v1
	ds_bpermute_b32 v1, v114, v0
	global_store_dwordx4 v[24:25], v[2:5], off offset:256
	s_and_saveexec_b64 s[40:41], s[6:7]
	s_cbranch_execz .LBB0_608
	s_waitcnt lgkmcnt(0)
	v_add_f32_e32 v0, v0, v1
	global_atomic_add_f32 v[112:113], v0, off offset:704

.LBB0_673:
	ds_read_b128 v[144:147], v153
	ds_read_b128 v[158:161], v153 offset:1024
	ds_read_b128 v[162:165], v153 offset:2048
	ds_read_b128 v[166:169], v153 offset:3072
	ds_read_b128 v[170:173], v154
	ds_read_b128 v[174:177], v154 offset:1024
	ds_read_b128 v[178:181], v154 offset:2048
	ds_read_b128 v[182:185], v154 offset:3072
	s_add_u32 s33, s30, 0xfff80080
	s_addc_u32 s34, s31, -1
	s_cmp_eq_u32 s69, 28
	s_cselect_b32 s37, s25, s34
	s_cselect_b32 s36, s65, s33
	s_cselect_b32 s35, s23, s68
	s_cselect_b32 s34, s66, s67
	v_lshl_add_u64 v[148:149], s[30:31], 0, v[136:137]
	s_add_i32 m0, s48, 0xc000
	ds_read_b128 v[186:189], v155
	ds_read_b128 v[194:197], v155 offset:1024
	ds_read_b128 v[198:201], v155 offset:2048
	ds_read_b128 v[202:205], v155 offset:3072
	ds_read_b128 v[206:209], v155 offset:4096
	ds_read_b128 v[210:213], v155 offset:5120
	ds_read_b128 v[214:217], v155 offset:6144
	ds_read_b128 v[218:221], v155 offset:7168
	global_load_lds_dwordx4 v[148:149], off
	v_lshl_add_u64 v[148:149], s[30:31], 0, v[138:139]
	s_add_i32 m0, s48, 0xe000
	s_nop 0
	global_load_lds_dwordx4 v[148:149], off
	s_waitcnt vmcnt(8)
	s_waitcnt lgkmcnt(0)
	s_barrier
	s_waitcnt lgkmcnt(0)
	v_mfma_f32_16x16x32_bf16 v[116:119], v[144:147], v[186:189], v[116:119]
	v_mfma_f32_16x16x32_bf16 v[112:115], v[162:165], v[186:189], v[112:115]
	v_mfma_f32_16x16x32_bf16 v[100:103], v[144:147], v[198:201], v[100:103]
	v_mfma_f32_16x16x32_bf16 v[96:99], v[162:165], v[198:201], v[96:99]
	v_mfma_f32_16x16x32_bf16 v[84:87], v[144:147], v[206:209], v[84:87]
	v_mfma_f32_16x16x32_bf16 v[80:83], v[162:165], v[206:209], v[80:83]
	v_mfma_f32_16x16x32_bf16 v[68:71], v[144:147], v[214:217], v[68:71]
	v_mfma_f32_16x16x32_bf16 v[64:67], v[162:165], v[214:217], v[64:67]
	v_mfma_f32_16x16x32_bf16 v[116:119], v[158:161], v[194:197], v[116:119]
	v_mfma_f32_16x16x32_bf16 v[112:115], v[166:169], v[194:197], v[112:115]
	v_mfma_f32_16x16x32_bf16 v[100:103], v[158:161], v[202:205], v[100:103]
	v_mfma_f32_16x16x32_bf16 v[96:99], v[166:169], v[202:205], v[96:99]
	v_mfma_f32_16x16x32_bf16 v[84:87], v[158:161], v[210:213], v[84:87]
	v_mfma_f32_16x16x32_bf16 v[80:83], v[166:169], v[210:213], v[80:83]
	v_mfma_f32_16x16x32_bf16 v[68:71], v[158:161], v[218:221], v[68:71]
	v_mfma_f32_16x16x32_bf16 v[64:67], v[166:169], v[218:221], v[64:67]
	v_mfma_f32_16x16x32_bf16 v[124:127], v[170:173], v[186:189], v[124:127]
	v_mfma_f32_16x16x32_bf16 v[120:123], v[178:181], v[186:189], v[120:123]
	v_mfma_f32_16x16x32_bf16 v[108:111], v[170:173], v[198:201], v[108:111]
	v_mfma_f32_16x16x32_bf16 v[104:107], v[178:181], v[198:201], v[104:107]
	v_mfma_f32_16x16x32_bf16 v[92:95], v[170:173], v[206:209], v[92:95]
	v_mfma_f32_16x16x32_bf16 v[88:91], v[178:181], v[206:209], v[88:91]
	v_mfma_f32_16x16x32_bf16 v[76:79], v[170:173], v[214:217], v[76:79]
	v_mfma_f32_16x16x32_bf16 v[72:75], v[178:181], v[214:217], v[72:75]
	v_mfma_f32_16x16x32_bf16 v[124:127], v[174:177], v[194:197], v[124:127]
	v_mfma_f32_16x16x32_bf16 v[120:123], v[182:185], v[194:197], v[120:123]
	v_mfma_f32_16x16x32_bf16 v[108:111], v[174:177], v[202:205], v[108:111]
	v_mfma_f32_16x16x32_bf16 v[104:107], v[182:185], v[202:205], v[104:107]
	v_mfma_f32_16x16x32_bf16 v[92:95], v[174:177], v[210:213], v[92:95]
	v_mfma_f32_16x16x32_bf16 v[88:91], v[182:185], v[210:213], v[88:91]
	v_mfma_f32_16x16x32_bf16 v[76:79], v[174:177], v[218:221], v[76:79]
	v_mfma_f32_16x16x32_bf16 v[72:75], v[182:185], v[218:221], v[72:75]
	s_barrier
	s_add_i32 s33, s61, s42
	v_lshl_add_u64 v[148:149], s[34:35], 0, v[132:133]
	s_mov_b32 m0, s33
	ds_read_b128 v[186:189], v155 offset:16384
	ds_read_b128 v[194:197], v155 offset:17408
	ds_read_b128 v[198:201], v155 offset:18432
	ds_read_b128 v[202:205], v155 offset:19456
	ds_read_b128 v[206:209], v155 offset:20480
	ds_read_b128 v[210:213], v155 offset:21504
	ds_read_b128 v[214:217], v155 offset:22528
	ds_read_b128 v[218:221], v155 offset:23552
	global_load_lds_dwordx4 v[148:149], off
	s_add_i32 m0, s33, 0x2000
	s_add_u32 s54, s34, 0x80000
	v_lshl_add_u64 v[190:191], s[34:35], 0, v[128:129]
	s_addc_u32 s55, s35, 0
	s_add_i32 s33, s62, s42
	global_load_lds_dwordx4 v[190:191], off
	v_lshl_add_u64 v[222:223], s[54:55], 0, v[132:133]
	s_mov_b32 m0, s33
	v_lshl_add_u64 v[224:225], s[36:37], 0, v[130:131]
	global_load_lds_dwordx4 v[222:223], off
	v_lshl_add_u64 v[222:223], s[54:55], 0, v[128:129]
	s_add_i32 m0, s33, 0x2000
	s_nop 0
	global_load_lds_dwordx4 v[222:223], off
	v_lshl_add_u64 v[222:223], s[36:37], 0, v[134:135]
	s_mov_b32 m0, s48
	s_nop 0
	global_load_lds_dwordx4 v[222:223], off
	s_mov_b32 m0, s49
	s_nop 0
	global_load_lds_dwordx4 v[224:225], off
	s_waitcnt vmcnt(8)
	s_waitcnt lgkmcnt(0)
	s_barrier
	s_waitcnt lgkmcnt(0)
	v_mfma_f32_16x16x32_bf16 v[52:55], v[144:147], v[186:189], v[52:55]
	v_mfma_f32_16x16x32_bf16 v[48:51], v[162:165], v[186:189], v[48:51]
	v_mfma_f32_16x16x32_bf16 v[36:39], v[144:147], v[198:201], v[36:39]
	v_mfma_f32_16x16x32_bf16 v[32:35], v[162:165], v[198:201], v[32:35]
	v_mfma_f32_16x16x32_bf16 v[20:23], v[144:147], v[206:209], v[20:23]
	v_mfma_f32_16x16x32_bf16 v[16:19], v[162:165], v[206:209], v[16:19]
	v_mfma_f32_16x16x32_bf16 v[4:7], v[144:147], v[214:217], v[4:7]
	v_mfma_f32_16x16x32_bf16 v[0:3], v[162:165], v[214:217], v[0:3]
	v_mfma_f32_16x16x32_bf16 v[52:55], v[158:161], v[194:197], v[52:55]
	v_mfma_f32_16x16x32_bf16 v[48:51], v[166:169], v[194:197], v[48:51]
	v_mfma_f32_16x16x32_bf16 v[36:39], v[158:161], v[202:205], v[36:39]
	v_mfma_f32_16x16x32_bf16 v[32:35], v[166:169], v[202:205], v[32:35]
	v_mfma_f32_16x16x32_bf16 v[20:23], v[158:161], v[210:213], v[20:23]
	v_mfma_f32_16x16x32_bf16 v[16:19], v[166:169], v[210:213], v[16:19]
	v_mfma_f32_16x16x32_bf16 v[4:7], v[158:161], v[218:221], v[4:7]
	v_mfma_f32_16x16x32_bf16 v[0:3], v[166:169], v[218:221], v[0:3]
	v_mfma_f32_16x16x32_bf16 v[60:63], v[170:173], v[186:189], v[60:63]
	v_mfma_f32_16x16x32_bf16 v[56:59], v[178:181], v[186:189], v[56:59]
	v_mfma_f32_16x16x32_bf16 v[44:47], v[170:173], v[198:201], v[44:47]
	v_mfma_f32_16x16x32_bf16 v[40:43], v[178:181], v[198:201], v[40:43]
	v_mfma_f32_16x16x32_bf16 v[28:31], v[170:173], v[206:209], v[28:31]
	v_mfma_f32_16x16x32_bf16 v[24:27], v[178:181], v[206:209], v[24:27]
	v_mfma_f32_16x16x32_bf16 v[12:15], v[170:173], v[214:217], v[12:15]
	v_mfma_f32_16x16x32_bf16 v[8:11], v[178:181], v[214:217], v[8:11]
	v_mfma_f32_16x16x32_bf16 v[60:63], v[174:177], v[194:197], v[60:63]
	v_mfma_f32_16x16x32_bf16 v[56:59], v[182:185], v[194:197], v[56:59]
	v_mfma_f32_16x16x32_bf16 v[44:47], v[174:177], v[202:205], v[44:47]
	v_mfma_f32_16x16x32_bf16 v[40:43], v[182:185], v[202:205], v[40:43]
	v_mfma_f32_16x16x32_bf16 v[28:31], v[174:177], v[210:213], v[28:31]
	v_mfma_f32_16x16x32_bf16 v[24:27], v[182:185], v[210:213], v[24:27]
	v_mfma_f32_16x16x32_bf16 v[12:15], v[174:177], v[218:221], v[12:15]
	v_mfma_f32_16x16x32_bf16 v[8:11], v[182:185], v[218:221], v[8:11]
	s_barrier
	s_add_i32 s33, 0, 0x18000
	s_add_i32 s54, 0, 0x1c000
	v_add_u32_e32 v166, s33, v151
	v_add_u32_e32 v182, s54, v151
	ds_read_b128 v[144:147], v166
	ds_read_b128 v[158:161], v166 offset:1024
	ds_read_b128 v[162:165], v166 offset:2048
	ds_read_b128 v[166:169], v166 offset:3072
	ds_read_b128 v[170:173], v182
	ds_read_b128 v[174:177], v182 offset:1024
	ds_read_b128 v[178:181], v182 offset:2048
	ds_read_b128 v[182:185], v182 offset:3072
	s_add_u32 s36, s36, 0x80000
	s_addc_u32 s37, s37, 0
	s_mov_b32 m0, s50
	v_lshl_add_u64 v[226:227], s[36:37], 0, v[134:135]
	ds_read_b128 v[186:189], v155 offset:32768
	ds_read_b128 v[194:197], v155 offset:33792
	ds_read_b128 v[198:201], v155 offset:34816
	ds_read_b128 v[202:205], v155 offset:35840
	ds_read_b128 v[206:209], v155 offset:36864
	ds_read_b128 v[210:213], v155 offset:37888
	ds_read_b128 v[214:217], v155 offset:38912
	ds_read_b128 v[218:221], v155 offset:39936
	global_load_lds_dwordx4 v[226:227], off
	v_lshl_add_u64 v[226:227], s[36:37], 0, v[130:131]
	s_mov_b32 m0, s51
	s_nop 0
	global_load_lds_dwordx4 v[226:227], off
	s_waitcnt vmcnt(8)
	s_waitcnt lgkmcnt(0)
	s_barrier
	s_waitcnt lgkmcnt(0)
	v_mfma_f32_16x16x32_bf16 v[116:119], v[144:147], v[186:189], v[116:119]
	v_mfma_f32_16x16x32_bf16 v[112:115], v[162:165], v[186:189], v[112:115]
	v_mfma_f32_16x16x32_bf16 v[100:103], v[144:147], v[198:201], v[100:103]
	v_mfma_f32_16x16x32_bf16 v[96:99], v[162:165], v[198:201], v[96:99]
	v_mfma_f32_16x16x32_bf16 v[84:87], v[144:147], v[206:209], v[84:87]
	v_mfma_f32_16x16x32_bf16 v[80:83], v[162:165], v[206:209], v[80:83]
	v_mfma_f32_16x16x32_bf16 v[68:71], v[144:147], v[214:217], v[68:71]
	v_mfma_f32_16x16x32_bf16 v[64:67], v[162:165], v[214:217], v[64:67]
	v_mfma_f32_16x16x32_bf16 v[116:119], v[158:161], v[194:197], v[116:119]
	v_mfma_f32_16x16x32_bf16 v[112:115], v[166:169], v[194:197], v[112:115]
	v_mfma_f32_16x16x32_bf16 v[100:103], v[158:161], v[202:205], v[100:103]
	v_mfma_f32_16x16x32_bf16 v[96:99], v[166:169], v[202:205], v[96:99]
	v_mfma_f32_16x16x32_bf16 v[84:87], v[158:161], v[210:213], v[84:87]
	v_mfma_f32_16x16x32_bf16 v[80:83], v[166:169], v[210:213], v[80:83]
	v_mfma_f32_16x16x32_bf16 v[68:71], v[158:161], v[218:221], v[68:71]
	v_mfma_f32_16x16x32_bf16 v[64:67], v[166:169], v[218:221], v[64:67]
	v_mfma_f32_16x16x32_bf16 v[124:127], v[170:173], v[186:189], v[124:127]
	v_mfma_f32_16x16x32_bf16 v[120:123], v[178:181], v[186:189], v[120:123]
	v_mfma_f32_16x16x32_bf16 v[108:111], v[170:173], v[198:201], v[108:111]
	v_mfma_f32_16x16x32_bf16 v[104:107], v[178:181], v[198:201], v[104:107]
	v_mfma_f32_16x16x32_bf16 v[92:95], v[170:173], v[206:209], v[92:95]
	v_mfma_f32_16x16x32_bf16 v[88:91], v[178:181], v[206:209], v[88:91]
	v_mfma_f32_16x16x32_bf16 v[76:79], v[170:173], v[214:217], v[76:79]
	v_mfma_f32_16x16x32_bf16 v[72:75], v[178:181], v[214:217], v[72:75]
	v_mfma_f32_16x16x32_bf16 v[124:127], v[174:177], v[194:197], v[124:127]
	v_mfma_f32_16x16x32_bf16 v[120:123], v[182:185], v[194:197], v[120:123]
	v_mfma_f32_16x16x32_bf16 v[108:111], v[174:177], v[202:205], v[108:111]
	v_mfma_f32_16x16x32_bf16 v[104:107], v[182:185], v[202:205], v[104:107]
	v_mfma_f32_16x16x32_bf16 v[92:95], v[174:177], v[210:213], v[92:95]
	v_mfma_f32_16x16x32_bf16 v[88:91], v[182:185], v[210:213], v[88:91]
	v_mfma_f32_16x16x32_bf16 v[76:79], v[174:177], v[218:221], v[76:79]
	v_mfma_f32_16x16x32_bf16 v[72:75], v[182:185], v[218:221], v[72:75]
	s_barrier
	s_add_i32 s33, s33, s42
	v_lshl_add_u64 v[148:149], v[148:149], 0, s[18:19]
	s_mov_b32 m0, s33
	ds_read_b128 v[186:189], v155 offset:49152
	ds_read_b128 v[194:197], v155 offset:50176
	ds_read_b128 v[198:201], v155 offset:51200
	ds_read_b128 v[202:205], v155 offset:52224
	ds_read_b128 v[206:209], v155 offset:53248
	ds_read_b128 v[210:213], v155 offset:54272
	ds_read_b128 v[214:217], v155 offset:55296
	ds_read_b128 v[218:221], v155 offset:56320
	global_load_lds_dwordx4 v[148:149], off
	s_add_i32 m0, s33, 0x2000
	s_add_u32 s34, s34, 0x80080
	v_lshl_add_u64 v[148:149], v[190:191], 0, s[18:19]
	s_addc_u32 s35, s35, 0
	s_add_i32 s33, s54, s42
	global_load_lds_dwordx4 v[148:149], off
	v_lshl_add_u64 v[148:149], s[34:35], 0, v[132:133]
	s_mov_b32 m0, s33
	s_nop 0
	global_load_lds_dwordx4 v[148:149], off
	v_lshl_add_u64 v[148:149], s[34:35], 0, v[128:129]
	s_add_i32 m0, s33, 0x2000
	s_nop 0
	global_load_lds_dwordx4 v[148:149], off
	v_lshl_add_u64 v[148:149], v[222:223], 0, s[18:19]
	s_mov_b32 m0, s59
	s_nop 0
	global_load_lds_dwordx4 v[148:149], off
	v_lshl_add_u64 v[148:149], v[224:225], 0, s[18:19]
	s_mov_b32 m0, s60
	s_nop 0
	global_load_lds_dwordx4 v[148:149], off
	s_waitcnt vmcnt(8)
	s_waitcnt lgkmcnt(0)
	s_barrier
	s_waitcnt lgkmcnt(0)
	v_mfma_f32_16x16x32_bf16 v[52:55], v[144:147], v[186:189], v[52:55]
	v_mfma_f32_16x16x32_bf16 v[48:51], v[162:165], v[186:189], v[48:51]
	v_mfma_f32_16x16x32_bf16 v[36:39], v[144:147], v[198:201], v[36:39]
	v_mfma_f32_16x16x32_bf16 v[32:35], v[162:165], v[198:201], v[32:35]
	v_mfma_f32_16x16x32_bf16 v[20:23], v[144:147], v[206:209], v[20:23]
	v_mfma_f32_16x16x32_bf16 v[16:19], v[162:165], v[206:209], v[16:19]
	v_mfma_f32_16x16x32_bf16 v[4:7], v[144:147], v[214:217], v[4:7]
	v_mfma_f32_16x16x32_bf16 v[0:3], v[162:165], v[214:217], v[0:3]
	v_mfma_f32_16x16x32_bf16 v[52:55], v[158:161], v[194:197], v[52:55]
	v_mfma_f32_16x16x32_bf16 v[48:51], v[166:169], v[194:197], v[48:51]
	v_mfma_f32_16x16x32_bf16 v[36:39], v[158:161], v[202:205], v[36:39]
	v_mfma_f32_16x16x32_bf16 v[32:35], v[166:169], v[202:205], v[32:35]
	v_mfma_f32_16x16x32_bf16 v[20:23], v[158:161], v[210:213], v[20:23]
	v_mfma_f32_16x16x32_bf16 v[16:19], v[166:169], v[210:213], v[16:19]
	v_mfma_f32_16x16x32_bf16 v[4:7], v[158:161], v[218:221], v[4:7]
	v_mfma_f32_16x16x32_bf16 v[0:3], v[166:169], v[218:221], v[0:3]
	v_mfma_f32_16x16x32_bf16 v[60:63], v[170:173], v[186:189], v[60:63]
	v_mfma_f32_16x16x32_bf16 v[56:59], v[178:181], v[186:189], v[56:59]
	v_mfma_f32_16x16x32_bf16 v[44:47], v[170:173], v[198:201], v[44:47]
	v_mfma_f32_16x16x32_bf16 v[40:43], v[178:181], v[198:201], v[40:43]
	v_mfma_f32_16x16x32_bf16 v[28:31], v[170:173], v[206:209], v[28:31]
	v_mfma_f32_16x16x32_bf16 v[24:27], v[178:181], v[206:209], v[24:27]
	v_mfma_f32_16x16x32_bf16 v[12:15], v[170:173], v[214:217], v[12:15]
	v_mfma_f32_16x16x32_bf16 v[8:11], v[178:181], v[214:217], v[8:11]
	v_mfma_f32_16x16x32_bf16 v[60:63], v[174:177], v[194:197], v[60:63]
	v_mfma_f32_16x16x32_bf16 v[56:59], v[182:185], v[194:197], v[56:59]
	v_mfma_f32_16x16x32_bf16 v[44:47], v[174:177], v[202:205], v[44:47]
	v_mfma_f32_16x16x32_bf16 v[40:43], v[182:185], v[202:205], v[40:43]
	v_mfma_f32_16x16x32_bf16 v[28:31], v[174:177], v[210:213], v[28:31]
	v_mfma_f32_16x16x32_bf16 v[24:27], v[182:185], v[210:213], v[24:27]
	v_mfma_f32_16x16x32_bf16 v[12:15], v[174:177], v[218:221], v[12:15]
	v_mfma_f32_16x16x32_bf16 v[8:11], v[182:185], v[218:221], v[8:11]
	s_barrier
	s_add_i32 s69, s69, 2
	s_add_u32 s30, s30, 0x100
	s_addc_u32 s31, s31, 0
	s_add_u32 s67, s67, 0x100
	s_addc_u32 s68, s68, 0
	s_cmp_gt_u32 s69, 29
	s_cbranch_scc0 .LBB0_673
	v_lshl_add_u32 v144, s8, 8, v150
	v_ashrrev_i32_e32 v145, 31, v144
	v_lshl_add_u64 v[148:149], v[144:145], 2, s[16:17]
	global_load_dword v172, v[148:149], off
	global_load_dword v173, v[148:149], off offset:64
	global_load_dword v174, v[148:149], off offset:128
	global_load_dword v175, v[148:149], off offset:192
	global_load_dword v176, v[148:149], off offset:512
	global_load_dword v177, v[148:149], off offset:576
	global_load_dword v178, v[148:149], off offset:640
	global_load_dword v179, v[148:149], off offset:704
	s_and_b64 vcc, exec, s[20:21]
	s_cbranch_vccz .LBB0_676
	s_barrier

.LBB0_1187:
	ds_read_b128 v[152:155], v161
	ds_read_b128 v[166:169], v161 offset:1024
	ds_read_b128 v[170:173], v161 offset:2048
	ds_read_b128 v[174:177], v161 offset:3072
	ds_read_b128 v[178:181], v162
	ds_read_b128 v[182:185], v162 offset:1024
	ds_read_b128 v[186:189], v162 offset:2048
	ds_read_b128 v[194:197], v162 offset:3072
	s_add_u32 s30, s28, 0x100
	s_addc_u32 s31, s29, 0
	s_cmpk_eq_i32 s68, 0x54
	s_cselect_b32 s37, s11, s31
	s_cselect_b32 s36, s10, s30
	s_cselect_b32 s35, s27, s67
	s_cselect_b32 s34, s26, s66
	v_lshl_add_u64 v[156:157], s[28:29], 0, v[136:137]
	s_add_i32 m0, s43, 0xc000
	ds_read_b128 v[198:201], v163
	ds_read_b128 v[202:205], v163 offset:1024
	ds_read_b128 v[206:209], v163 offset:2048
	ds_read_b128 v[210:213], v163 offset:3072
	ds_read_b128 v[214:217], v163 offset:4096
	ds_read_b128 v[218:221], v163 offset:5120
	ds_read_b128 v[222:225], v163 offset:6144
	ds_read_b128 v[226:229], v163 offset:7168
	global_load_lds_dwordx4 v[156:157], off
	v_lshl_add_u64 v[156:157], s[28:29], 0, v[138:139]
	s_add_i32 m0, s43, 0xe000
	s_nop 0
	global_load_lds_dwordx4 v[156:157], off
	s_waitcnt vmcnt(8)
	s_waitcnt lgkmcnt(0)
	s_barrier
	s_waitcnt lgkmcnt(0)
	v_mfma_f32_16x16x32_bf16 v[124:127], v[152:155], v[198:201], v[124:127]
	v_mfma_f32_16x16x32_bf16 v[120:123], v[170:173], v[198:201], v[120:123]
	v_mfma_f32_16x16x32_bf16 v[108:111], v[152:155], v[206:209], v[108:111]
	v_mfma_f32_16x16x32_bf16 v[104:107], v[170:173], v[206:209], v[104:107]
	v_mfma_f32_16x16x32_bf16 v[92:95], v[152:155], v[214:217], v[92:95]
	v_mfma_f32_16x16x32_bf16 v[88:91], v[170:173], v[214:217], v[88:91]
	v_mfma_f32_16x16x32_bf16 v[76:79], v[152:155], v[222:225], v[76:79]
	v_mfma_f32_16x16x32_bf16 v[72:75], v[170:173], v[222:225], v[72:75]
	v_mfma_f32_16x16x32_bf16 v[124:127], v[166:169], v[202:205], v[124:127]
	v_mfma_f32_16x16x32_bf16 v[120:123], v[174:177], v[202:205], v[120:123]
	v_mfma_f32_16x16x32_bf16 v[108:111], v[166:169], v[210:213], v[108:111]
	v_mfma_f32_16x16x32_bf16 v[104:107], v[174:177], v[210:213], v[104:107]
	v_mfma_f32_16x16x32_bf16 v[92:95], v[166:169], v[218:221], v[92:95]
	v_mfma_f32_16x16x32_bf16 v[88:91], v[174:177], v[218:221], v[88:91]
	v_mfma_f32_16x16x32_bf16 v[76:79], v[166:169], v[226:229], v[76:79]
	v_mfma_f32_16x16x32_bf16 v[72:75], v[174:177], v[226:229], v[72:75]
	v_mfma_f32_16x16x32_bf16 v[116:119], v[178:181], v[198:201], v[116:119]
	v_mfma_f32_16x16x32_bf16 v[112:115], v[186:189], v[198:201], v[112:115]
	v_mfma_f32_16x16x32_bf16 v[100:103], v[178:181], v[206:209], v[100:103]
	v_mfma_f32_16x16x32_bf16 v[96:99], v[186:189], v[206:209], v[96:99]
	v_mfma_f32_16x16x32_bf16 v[84:87], v[178:181], v[214:217], v[84:87]
	v_mfma_f32_16x16x32_bf16 v[80:83], v[186:189], v[214:217], v[80:83]
	v_mfma_f32_16x16x32_bf16 v[68:71], v[178:181], v[222:225], v[68:71]
	v_mfma_f32_16x16x32_bf16 v[64:67], v[186:189], v[222:225], v[64:67]
	v_mfma_f32_16x16x32_bf16 v[116:119], v[182:185], v[202:205], v[116:119]
	v_mfma_f32_16x16x32_bf16 v[112:115], v[194:197], v[202:205], v[112:115]
	v_mfma_f32_16x16x32_bf16 v[100:103], v[182:185], v[210:213], v[100:103]
	v_mfma_f32_16x16x32_bf16 v[96:99], v[194:197], v[210:213], v[96:99]
	v_mfma_f32_16x16x32_bf16 v[84:87], v[182:185], v[218:221], v[84:87]
	v_mfma_f32_16x16x32_bf16 v[80:83], v[194:197], v[218:221], v[80:83]
	v_mfma_f32_16x16x32_bf16 v[68:71], v[182:185], v[226:229], v[68:71]
	v_mfma_f32_16x16x32_bf16 v[64:67], v[194:197], v[226:229], v[64:67]
	s_barrier
	s_add_i32 s28, s60, s42
	v_lshl_add_u64 v[156:157], s[34:35], 0, v[130:131]
	s_mov_b32 m0, s28
	ds_read_b128 v[198:201], v163 offset:16384
	ds_read_b128 v[202:205], v163 offset:17408
	ds_read_b128 v[206:209], v163 offset:18432
	ds_read_b128 v[210:213], v163 offset:19456
	ds_read_b128 v[214:217], v163 offset:20480
	ds_read_b128 v[218:221], v163 offset:21504
	ds_read_b128 v[222:225], v163 offset:22528
	ds_read_b128 v[226:229], v163 offset:23552
	global_load_lds_dwordx4 v[156:157], off
	s_add_i32 m0, s28, 0x2000
	s_add_u32 s28, s34, 0x160000
	v_lshl_add_u64 v[190:191], s[34:35], 0, v[134:135]
	s_addc_u32 s29, s35, 0
	s_add_i32 s33, s61, s42
	global_load_lds_dwordx4 v[190:191], off
	v_lshl_add_u64 v[230:231], s[28:29], 0, v[130:131]
	s_mov_b32 m0, s33
	v_lshl_add_u64 v[232:233], s[36:37], 0, v[132:133]
	global_load_lds_dwordx4 v[230:231], off
	v_lshl_add_u64 v[230:231], s[28:29], 0, v[134:135]
	s_add_i32 m0, s33, 0x2000
	s_nop 0
	global_load_lds_dwordx4 v[230:231], off
	v_lshl_add_u64 v[230:231], s[36:37], 0, v[128:129]
	s_mov_b32 m0, s43
	s_nop 0
	global_load_lds_dwordx4 v[230:231], off
	s_mov_b32 m0, s48
	s_nop 0
	global_load_lds_dwordx4 v[232:233], off
	s_waitcnt vmcnt(8)
	s_waitcnt lgkmcnt(0)
	s_barrier
	s_waitcnt lgkmcnt(0)
	v_mfma_f32_16x16x32_bf16 v[60:63], v[152:155], v[198:201], v[60:63]
	v_mfma_f32_16x16x32_bf16 v[56:59], v[170:173], v[198:201], v[56:59]
	v_mfma_f32_16x16x32_bf16 v[44:47], v[152:155], v[206:209], v[44:47]
	v_mfma_f32_16x16x32_bf16 v[40:43], v[170:173], v[206:209], v[40:43]
	v_mfma_f32_16x16x32_bf16 v[28:31], v[152:155], v[214:217], v[28:31]
	v_mfma_f32_16x16x32_bf16 v[24:27], v[170:173], v[214:217], v[24:27]
	v_mfma_f32_16x16x32_bf16 v[12:15], v[152:155], v[222:225], v[12:15]
	v_mfma_f32_16x16x32_bf16 v[8:11], v[170:173], v[222:225], v[8:11]
	v_mfma_f32_16x16x32_bf16 v[60:63], v[166:169], v[202:205], v[60:63]
	v_mfma_f32_16x16x32_bf16 v[56:59], v[174:177], v[202:205], v[56:59]
	v_mfma_f32_16x16x32_bf16 v[44:47], v[166:169], v[210:213], v[44:47]
	v_mfma_f32_16x16x32_bf16 v[40:43], v[174:177], v[210:213], v[40:43]
	v_mfma_f32_16x16x32_bf16 v[28:31], v[166:169], v[218:221], v[28:31]
	v_mfma_f32_16x16x32_bf16 v[24:27], v[174:177], v[218:221], v[24:27]
	v_mfma_f32_16x16x32_bf16 v[12:15], v[166:169], v[226:229], v[12:15]
	v_mfma_f32_16x16x32_bf16 v[8:11], v[174:177], v[226:229], v[8:11]
	v_mfma_f32_16x16x32_bf16 v[52:55], v[178:181], v[198:201], v[52:55]
	v_mfma_f32_16x16x32_bf16 v[48:51], v[186:189], v[198:201], v[48:51]
	v_mfma_f32_16x16x32_bf16 v[36:39], v[178:181], v[206:209], v[36:39]
	v_mfma_f32_16x16x32_bf16 v[32:35], v[186:189], v[206:209], v[32:35]
	v_mfma_f32_16x16x32_bf16 v[20:23], v[178:181], v[214:217], v[20:23]
	v_mfma_f32_16x16x32_bf16 v[16:19], v[186:189], v[214:217], v[16:19]
	v_mfma_f32_16x16x32_bf16 v[4:7], v[178:181], v[222:225], v[4:7]
	v_mfma_f32_16x16x32_bf16 v[0:3], v[186:189], v[222:225], v[0:3]
	v_mfma_f32_16x16x32_bf16 v[52:55], v[182:185], v[202:205], v[52:55]
	v_mfma_f32_16x16x32_bf16 v[48:51], v[194:197], v[202:205], v[48:51]
	v_mfma_f32_16x16x32_bf16 v[36:39], v[182:185], v[210:213], v[36:39]
	v_mfma_f32_16x16x32_bf16 v[32:35], v[194:197], v[210:213], v[32:35]
	v_mfma_f32_16x16x32_bf16 v[20:23], v[182:185], v[218:221], v[20:23]
	v_mfma_f32_16x16x32_bf16 v[16:19], v[194:197], v[218:221], v[16:19]
	v_mfma_f32_16x16x32_bf16 v[4:7], v[182:185], v[226:229], v[4:7]
	v_mfma_f32_16x16x32_bf16 v[0:3], v[194:197], v[226:229], v[0:3]
	s_barrier
	s_add_i32 s33, 0, 0x18000
	v_add_u32_e32 v165, s33, v159
	s_add_i32 s54, 0, 0x1c000
	ds_read_b128 v[152:155], v165
	ds_read_b128 v[166:169], v165 offset:1024
	ds_read_b128 v[170:173], v165 offset:2048
	ds_read_b128 v[174:177], v165 offset:3072
	v_add_u32_e32 v165, s54, v159
	ds_read_b128 v[178:181], v165
	ds_read_b128 v[182:185], v165 offset:1024
	ds_read_b128 v[186:189], v165 offset:2048
	ds_read_b128 v[194:197], v165 offset:3072
	s_add_u32 s28, s36, 0x160000
	s_addc_u32 s29, s37, 0
	s_mov_b32 m0, s49
	v_lshl_add_u64 v[234:235], s[28:29], 0, v[128:129]
	ds_read_b128 v[198:201], v163 offset:32768
	ds_read_b128 v[202:205], v163 offset:33792
	ds_read_b128 v[206:209], v163 offset:34816
	ds_read_b128 v[210:213], v163 offset:35840
	ds_read_b128 v[214:217], v163 offset:36864
	ds_read_b128 v[218:221], v163 offset:37888
	ds_read_b128 v[222:225], v163 offset:38912
	ds_read_b128 v[226:229], v163 offset:39936
	global_load_lds_dwordx4 v[234:235], off
	v_lshl_add_u64 v[234:235], s[28:29], 0, v[132:133]
	s_mov_b32 m0, s50
	s_nop 0
	global_load_lds_dwordx4 v[234:235], off
	s_waitcnt vmcnt(8)
	s_waitcnt lgkmcnt(0)
	s_barrier
	s_waitcnt lgkmcnt(0)
	v_mfma_f32_16x16x32_bf16 v[124:127], v[152:155], v[198:201], v[124:127]
	v_mfma_f32_16x16x32_bf16 v[120:123], v[170:173], v[198:201], v[120:123]
	v_mfma_f32_16x16x32_bf16 v[108:111], v[152:155], v[206:209], v[108:111]
	v_mfma_f32_16x16x32_bf16 v[104:107], v[170:173], v[206:209], v[104:107]
	v_mfma_f32_16x16x32_bf16 v[92:95], v[152:155], v[214:217], v[92:95]
	v_mfma_f32_16x16x32_bf16 v[88:91], v[170:173], v[214:217], v[88:91]
	v_mfma_f32_16x16x32_bf16 v[76:79], v[152:155], v[222:225], v[76:79]
	v_mfma_f32_16x16x32_bf16 v[72:75], v[170:173], v[222:225], v[72:75]
	v_mfma_f32_16x16x32_bf16 v[124:127], v[166:169], v[202:205], v[124:127]
	v_mfma_f32_16x16x32_bf16 v[120:123], v[174:177], v[202:205], v[120:123]
	v_mfma_f32_16x16x32_bf16 v[108:111], v[166:169], v[210:213], v[108:111]
	v_mfma_f32_16x16x32_bf16 v[104:107], v[174:177], v[210:213], v[104:107]
	v_mfma_f32_16x16x32_bf16 v[92:95], v[166:169], v[218:221], v[92:95]
	v_mfma_f32_16x16x32_bf16 v[88:91], v[174:177], v[218:221], v[88:91]
	v_mfma_f32_16x16x32_bf16 v[76:79], v[166:169], v[226:229], v[76:79]
	v_mfma_f32_16x16x32_bf16 v[72:75], v[174:177], v[226:229], v[72:75]
	v_mfma_f32_16x16x32_bf16 v[116:119], v[178:181], v[198:201], v[116:119]
	v_mfma_f32_16x16x32_bf16 v[112:115], v[186:189], v[198:201], v[112:115]
	v_mfma_f32_16x16x32_bf16 v[100:103], v[178:181], v[206:209], v[100:103]
	v_mfma_f32_16x16x32_bf16 v[96:99], v[186:189], v[206:209], v[96:99]
	v_mfma_f32_16x16x32_bf16 v[84:87], v[178:181], v[214:217], v[84:87]
	v_mfma_f32_16x16x32_bf16 v[80:83], v[186:189], v[214:217], v[80:83]
	v_mfma_f32_16x16x32_bf16 v[68:71], v[178:181], v[222:225], v[68:71]
	v_mfma_f32_16x16x32_bf16 v[64:67], v[186:189], v[222:225], v[64:67]
	v_mfma_f32_16x16x32_bf16 v[116:119], v[182:185], v[202:205], v[116:119]
	v_mfma_f32_16x16x32_bf16 v[112:115], v[194:197], v[202:205], v[112:115]
	v_mfma_f32_16x16x32_bf16 v[100:103], v[182:185], v[210:213], v[100:103]
	v_mfma_f32_16x16x32_bf16 v[96:99], v[194:197], v[210:213], v[96:99]
	v_mfma_f32_16x16x32_bf16 v[84:87], v[182:185], v[218:221], v[84:87]
	v_mfma_f32_16x16x32_bf16 v[80:83], v[194:197], v[218:221], v[80:83]
	v_mfma_f32_16x16x32_bf16 v[68:71], v[182:185], v[226:229], v[68:71]
	v_mfma_f32_16x16x32_bf16 v[64:67], v[194:197], v[226:229], v[64:67]
	s_barrier
	s_add_i32 s28, s33, s42
	v_lshl_add_u64 v[156:157], v[156:157], 0, s[22:23]
	s_mov_b32 m0, s28
	ds_read_b128 v[198:201], v163 offset:49152
	ds_read_b128 v[202:205], v163 offset:50176
	ds_read_b128 v[206:209], v163 offset:51200
	ds_read_b128 v[210:213], v163 offset:52224
	ds_read_b128 v[214:217], v163 offset:53248
	ds_read_b128 v[218:221], v163 offset:54272
	ds_read_b128 v[222:225], v163 offset:55296
	ds_read_b128 v[226:229], v163 offset:56320
	global_load_lds_dwordx4 v[156:157], off
	s_add_i32 m0, s28, 0x2000
	s_add_u32 s28, s34, 0x160080
	v_lshl_add_u64 v[156:157], v[190:191], 0, s[22:23]
	s_addc_u32 s29, s35, 0
	s_add_i32 s33, s54, s42
	global_load_lds_dwordx4 v[156:157], off
	v_lshl_add_u64 v[156:157], s[28:29], 0, v[130:131]
	s_mov_b32 m0, s33
	s_nop 0
	global_load_lds_dwordx4 v[156:157], off
	v_lshl_add_u64 v[156:157], s[28:29], 0, v[134:135]
	s_add_i32 m0, s33, 0x2000
	s_nop 0
	global_load_lds_dwordx4 v[156:157], off
	v_lshl_add_u64 v[156:157], v[230:231], 0, s[22:23]
	s_mov_b32 m0, s58
	s_nop 0
	global_load_lds_dwordx4 v[156:157], off
	v_lshl_add_u64 v[156:157], v[232:233], 0, s[22:23]
	s_mov_b32 m0, s59
	s_nop 0
	global_load_lds_dwordx4 v[156:157], off
	s_waitcnt vmcnt(8)
	s_waitcnt lgkmcnt(0)
	s_barrier
	s_waitcnt lgkmcnt(0)
	v_mfma_f32_16x16x32_bf16 v[60:63], v[152:155], v[198:201], v[60:63]
	v_mfma_f32_16x16x32_bf16 v[56:59], v[170:173], v[198:201], v[56:59]
	v_mfma_f32_16x16x32_bf16 v[44:47], v[152:155], v[206:209], v[44:47]
	v_mfma_f32_16x16x32_bf16 v[40:43], v[170:173], v[206:209], v[40:43]
	v_mfma_f32_16x16x32_bf16 v[28:31], v[152:155], v[214:217], v[28:31]
	v_mfma_f32_16x16x32_bf16 v[24:27], v[170:173], v[214:217], v[24:27]
	v_mfma_f32_16x16x32_bf16 v[12:15], v[152:155], v[222:225], v[12:15]
	v_mfma_f32_16x16x32_bf16 v[8:11], v[170:173], v[222:225], v[8:11]
	v_mfma_f32_16x16x32_bf16 v[60:63], v[166:169], v[202:205], v[60:63]
	v_mfma_f32_16x16x32_bf16 v[56:59], v[174:177], v[202:205], v[56:59]
	v_mfma_f32_16x16x32_bf16 v[44:47], v[166:169], v[210:213], v[44:47]
	v_mfma_f32_16x16x32_bf16 v[40:43], v[174:177], v[210:213], v[40:43]
	v_mfma_f32_16x16x32_bf16 v[28:31], v[166:169], v[218:221], v[28:31]
	v_mfma_f32_16x16x32_bf16 v[24:27], v[174:177], v[218:221], v[24:27]
	v_mfma_f32_16x16x32_bf16 v[12:15], v[166:169], v[226:229], v[12:15]
	v_mfma_f32_16x16x32_bf16 v[8:11], v[174:177], v[226:229], v[8:11]
	v_mfma_f32_16x16x32_bf16 v[52:55], v[178:181], v[198:201], v[52:55]
	v_mfma_f32_16x16x32_bf16 v[48:51], v[186:189], v[198:201], v[48:51]
	v_mfma_f32_16x16x32_bf16 v[36:39], v[178:181], v[206:209], v[36:39]
	v_mfma_f32_16x16x32_bf16 v[32:35], v[186:189], v[206:209], v[32:35]
	v_mfma_f32_16x16x32_bf16 v[20:23], v[178:181], v[214:217], v[20:23]
	v_mfma_f32_16x16x32_bf16 v[16:19], v[186:189], v[214:217], v[16:19]
	v_mfma_f32_16x16x32_bf16 v[4:7], v[178:181], v[222:225], v[4:7]
	v_mfma_f32_16x16x32_bf16 v[0:3], v[186:189], v[222:225], v[0:3]
	v_mfma_f32_16x16x32_bf16 v[52:55], v[182:185], v[202:205], v[52:55]
	v_mfma_f32_16x16x32_bf16 v[48:51], v[194:197], v[202:205], v[48:51]
	v_mfma_f32_16x16x32_bf16 v[36:39], v[182:185], v[210:213], v[36:39]
	v_mfma_f32_16x16x32_bf16 v[32:35], v[194:197], v[210:213], v[32:35]
	v_mfma_f32_16x16x32_bf16 v[20:23], v[182:185], v[218:221], v[20:23]
	v_mfma_f32_16x16x32_bf16 v[16:19], v[194:197], v[218:221], v[16:19]
	v_mfma_f32_16x16x32_bf16 v[4:7], v[182:185], v[226:229], v[4:7]
	v_mfma_f32_16x16x32_bf16 v[0:3], v[194:197], v[226:229], v[0:3]
	s_barrier
	s_add_i32 s68, s68, 2
	s_add_u32 s66, s66, 0x100
	s_addc_u32 s67, s67, 0
	s_cmpk_gt_u32 s68, 0x55
	s_mov_b64 s[28:29], s[30:31]
	s_cbranch_scc0 .LBB0_1187
	v_lshl_add_u32 v156, s64, 8, v158
	v_lshl_or_b32 v154, s65, 8, v160
	v_ashrrev_i32_e32 v157, 31, v156
	v_ashrrev_i32_e32 v155, 31, v154
	v_lshlrev_b64 v[152:153], 11, v[156:157]
	v_lshl_add_u64 v[152:153], v[152:153], 0, v[154:155]
	v_lshlrev_b64 v[170:171], 1, v[152:153]
	v_lshl_add_u64 v[172:173], s[16:17], 0, v[170:171]
	global_load_dwordx4 v[180:183], v[172:173], off
	global_load_dwordx4 v[184:187], v[172:173], off offset:256
	v_add_co_u32_e32 v252, vcc, 0x10000, v172
	s_nop 1
	v_addc_co_u32_e32 v253, vcc, 0, v173, vcc
	global_load_dwordx4 v[188:191], v[252:253], off
	global_load_dwordx4 v[194:197], v[252:253], off offset:256
	v_add_co_u32_e32 v254, vcc, 0x20000, v172
	s_nop 1
	v_addc_co_u32_e32 v255, vcc, 0, v173, vcc
	global_load_dwordx4 v[198:201], v[254:255], off
	global_load_dwordx4 v[202:205], v[254:255], off offset:256
	v_add_co_u32_e32 v252, vcc, 0x30000, v172
	s_nop 1
	v_addc_co_u32_e32 v253, vcc, 0, v173, vcc
	global_load_dwordx4 v[206:209], v[252:253], off
	global_load_dwordx4 v[210:213], v[252:253], off offset:256
	v_add_co_u32_e32 v254, vcc, 0x80000, v172
	s_nop 1
	v_addc_co_u32_e32 v255, vcc, 0, v173, vcc
	global_load_dwordx4 v[214:217], v[254:255], off
	global_load_dwordx4 v[218:221], v[254:255], off offset:256
	v_add_co_u32_e32 v252, vcc, 0x90000, v172
	s_nop 1
	v_addc_co_u32_e32 v253, vcc, 0, v173, vcc
	global_load_dwordx4 v[222:225], v[252:253], off
	global_load_dwordx4 v[226:229], v[252:253], off offset:256
	v_add_co_u32_e32 v254, vcc, 0xa0000, v172
	s_nop 1
	v_addc_co_u32_e32 v255, vcc, 0, v173, vcc
	global_load_dwordx4 v[230:233], v[254:255], off
	global_load_dwordx4 v[234:237], v[254:255], off offset:256
	v_add_co_u32_e32 v252, vcc, 0xb0000, v172
	s_nop 1
	v_addc_co_u32_e32 v253, vcc, 0, v173, vcc
	global_load_dwordx4 v[238:241], v[252:253], off
	global_load_dwordx4 v[242:245], v[252:253], off offset:256
	s_and_b64 vcc, exec, s[24:25]
	s_cbranch_vccz .LBB0_1190
	s_barrier

.LBB0_1271:
	ds_read_b128 v[144:147], v155
	ds_read_b128 v[148:151], v155 offset:1024
	ds_read_b128 v[160:163], v155 offset:2048
	ds_read_b128 v[164:167], v155 offset:3072
	ds_read_b128 v[168:171], v156
	ds_read_b128 v[172:175], v156 offset:1024
	ds_read_b128 v[176:179], v156 offset:2048
	ds_read_b128 v[180:183], v156 offset:3072
	s_add_u32 s33, s30, 0xfff80080
	s_addc_u32 s34, s31, -1
	s_cmp_eq_u32 s67, 28
	s_cselect_b32 s37, s25, s34
	s_cselect_b32 s36, s63, s33
	s_cselect_b32 s35, s23, s66
	s_cselect_b32 s34, s64, s65
	v_lshl_add_u64 v[218:219], s[30:31], 0, v[136:137]
	s_add_i32 m0, s48, 0xc000
	ds_read_b128 v[184:187], v157
	ds_read_b128 v[188:191], v157 offset:1024
	ds_read_b128 v[194:197], v157 offset:2048
	ds_read_b128 v[198:201], v157 offset:3072
	ds_read_b128 v[202:205], v157 offset:4096
	ds_read_b128 v[206:209], v157 offset:5120
	ds_read_b128 v[210:213], v157 offset:6144
	ds_read_b128 v[214:217], v157 offset:7168
	global_load_lds_dwordx4 v[218:219], off
	v_lshl_add_u64 v[218:219], s[30:31], 0, v[138:139]
	s_add_i32 m0, s48, 0xe000
	s_nop 0
	global_load_lds_dwordx4 v[218:219], off
	s_waitcnt vmcnt(8)
	s_waitcnt lgkmcnt(0)
	s_barrier
	s_waitcnt lgkmcnt(0)
	v_mfma_f32_16x16x32_bf16 v[124:127], v[144:147], v[184:187], v[124:127]
	v_mfma_f32_16x16x32_bf16 v[120:123], v[160:163], v[184:187], v[120:123]
	v_mfma_f32_16x16x32_bf16 v[108:111], v[144:147], v[194:197], v[108:111]
	v_mfma_f32_16x16x32_bf16 v[104:107], v[160:163], v[194:197], v[104:107]
	v_mfma_f32_16x16x32_bf16 v[92:95], v[144:147], v[202:205], v[92:95]
	v_mfma_f32_16x16x32_bf16 v[88:91], v[160:163], v[202:205], v[88:91]
	v_mfma_f32_16x16x32_bf16 v[76:79], v[144:147], v[210:213], v[76:79]
	v_mfma_f32_16x16x32_bf16 v[72:75], v[160:163], v[210:213], v[72:75]
	v_mfma_f32_16x16x32_bf16 v[124:127], v[148:151], v[188:191], v[124:127]
	v_mfma_f32_16x16x32_bf16 v[120:123], v[164:167], v[188:191], v[120:123]
	v_mfma_f32_16x16x32_bf16 v[108:111], v[148:151], v[198:201], v[108:111]
	v_mfma_f32_16x16x32_bf16 v[104:107], v[164:167], v[198:201], v[104:107]
	v_mfma_f32_16x16x32_bf16 v[92:95], v[148:151], v[206:209], v[92:95]
	v_mfma_f32_16x16x32_bf16 v[88:91], v[164:167], v[206:209], v[88:91]
	v_mfma_f32_16x16x32_bf16 v[76:79], v[148:151], v[214:217], v[76:79]
	v_mfma_f32_16x16x32_bf16 v[72:75], v[164:167], v[214:217], v[72:75]
	v_mfma_f32_16x16x32_bf16 v[116:119], v[168:171], v[184:187], v[116:119]
	v_mfma_f32_16x16x32_bf16 v[112:115], v[176:179], v[184:187], v[112:115]
	v_mfma_f32_16x16x32_bf16 v[100:103], v[168:171], v[194:197], v[100:103]
	v_mfma_f32_16x16x32_bf16 v[96:99], v[176:179], v[194:197], v[96:99]
	v_mfma_f32_16x16x32_bf16 v[84:87], v[168:171], v[202:205], v[84:87]
	v_mfma_f32_16x16x32_bf16 v[80:83], v[176:179], v[202:205], v[80:83]
	v_mfma_f32_16x16x32_bf16 v[68:71], v[168:171], v[210:213], v[68:71]
	v_mfma_f32_16x16x32_bf16 v[64:67], v[176:179], v[210:213], v[64:67]
	v_mfma_f32_16x16x32_bf16 v[116:119], v[172:175], v[188:191], v[116:119]
	v_mfma_f32_16x16x32_bf16 v[112:115], v[180:183], v[188:191], v[112:115]
	v_mfma_f32_16x16x32_bf16 v[100:103], v[172:175], v[198:201], v[100:103]
	v_mfma_f32_16x16x32_bf16 v[96:99], v[180:183], v[198:201], v[96:99]
	v_mfma_f32_16x16x32_bf16 v[84:87], v[172:175], v[206:209], v[84:87]
	v_mfma_f32_16x16x32_bf16 v[80:83], v[180:183], v[206:209], v[80:83]
	v_mfma_f32_16x16x32_bf16 v[68:71], v[172:175], v[214:217], v[68:71]
	v_mfma_f32_16x16x32_bf16 v[64:67], v[180:183], v[214:217], v[64:67]
	s_barrier
	s_add_i32 s33, s59, s42
	v_lshl_add_u64 v[218:219], s[34:35], 0, v[132:133]
	s_mov_b32 m0, s33
	ds_read_b128 v[184:187], v157 offset:16384
	ds_read_b128 v[188:191], v157 offset:17408
	ds_read_b128 v[194:197], v157 offset:18432
	ds_read_b128 v[198:201], v157 offset:19456
	ds_read_b128 v[202:205], v157 offset:20480
	ds_read_b128 v[206:209], v157 offset:21504
	ds_read_b128 v[210:213], v157 offset:22528
	ds_read_b128 v[214:217], v157 offset:23552
	global_load_lds_dwordx4 v[218:219], off
	s_add_i32 m0, s33, 0x2000
	s_add_u32 s54, s34, 0x80000
	v_lshl_add_u64 v[220:221], s[34:35], 0, v[128:129]
	s_addc_u32 s55, s35, 0
	s_add_i32 s33, s60, s42
	global_load_lds_dwordx4 v[220:221], off
	v_lshl_add_u64 v[222:223], s[54:55], 0, v[132:133]
	s_mov_b32 m0, s33
	v_lshl_add_u64 v[224:225], s[36:37], 0, v[130:131]
	global_load_lds_dwordx4 v[222:223], off
	v_lshl_add_u64 v[222:223], s[54:55], 0, v[128:129]
	s_add_i32 m0, s33, 0x2000
	s_nop 0
	global_load_lds_dwordx4 v[222:223], off
	v_lshl_add_u64 v[222:223], s[36:37], 0, v[134:135]
	s_mov_b32 m0, s48
	s_nop 0
	global_load_lds_dwordx4 v[222:223], off
	s_mov_b32 m0, s49
	s_nop 0
	global_load_lds_dwordx4 v[224:225], off
	s_waitcnt vmcnt(8)
	s_waitcnt lgkmcnt(0)
	s_barrier
	s_waitcnt lgkmcnt(0)
	v_mfma_f32_16x16x32_bf16 v[60:63], v[144:147], v[184:187], v[60:63]
	v_mfma_f32_16x16x32_bf16 v[56:59], v[160:163], v[184:187], v[56:59]
	v_mfma_f32_16x16x32_bf16 v[44:47], v[144:147], v[194:197], v[44:47]
	v_mfma_f32_16x16x32_bf16 v[40:43], v[160:163], v[194:197], v[40:43]
	v_mfma_f32_16x16x32_bf16 v[28:31], v[144:147], v[202:205], v[28:31]
	v_mfma_f32_16x16x32_bf16 v[24:27], v[160:163], v[202:205], v[24:27]
	v_mfma_f32_16x16x32_bf16 v[12:15], v[144:147], v[210:213], v[12:15]
	v_mfma_f32_16x16x32_bf16 v[8:11], v[160:163], v[210:213], v[8:11]
	v_mfma_f32_16x16x32_bf16 v[60:63], v[148:151], v[188:191], v[60:63]
	v_mfma_f32_16x16x32_bf16 v[56:59], v[164:167], v[188:191], v[56:59]
	v_mfma_f32_16x16x32_bf16 v[44:47], v[148:151], v[198:201], v[44:47]
	v_mfma_f32_16x16x32_bf16 v[40:43], v[164:167], v[198:201], v[40:43]
	v_mfma_f32_16x16x32_bf16 v[28:31], v[148:151], v[206:209], v[28:31]
	v_mfma_f32_16x16x32_bf16 v[24:27], v[164:167], v[206:209], v[24:27]
	v_mfma_f32_16x16x32_bf16 v[12:15], v[148:151], v[214:217], v[12:15]
	v_mfma_f32_16x16x32_bf16 v[8:11], v[164:167], v[214:217], v[8:11]
	v_mfma_f32_16x16x32_bf16 v[52:55], v[168:171], v[184:187], v[52:55]
	v_mfma_f32_16x16x32_bf16 v[48:51], v[176:179], v[184:187], v[48:51]
	v_mfma_f32_16x16x32_bf16 v[36:39], v[168:171], v[194:197], v[36:39]
	v_mfma_f32_16x16x32_bf16 v[32:35], v[176:179], v[194:197], v[32:35]
	v_mfma_f32_16x16x32_bf16 v[20:23], v[168:171], v[202:205], v[20:23]
	v_mfma_f32_16x16x32_bf16 v[16:19], v[176:179], v[202:205], v[16:19]
	v_mfma_f32_16x16x32_bf16 v[4:7], v[168:171], v[210:213], v[4:7]
	v_mfma_f32_16x16x32_bf16 v[0:3], v[176:179], v[210:213], v[0:3]
	v_mfma_f32_16x16x32_bf16 v[52:55], v[172:175], v[188:191], v[52:55]
	v_mfma_f32_16x16x32_bf16 v[48:51], v[180:183], v[188:191], v[48:51]
	v_mfma_f32_16x16x32_bf16 v[36:39], v[172:175], v[198:201], v[36:39]
	v_mfma_f32_16x16x32_bf16 v[32:35], v[180:183], v[198:201], v[32:35]
	v_mfma_f32_16x16x32_bf16 v[20:23], v[172:175], v[206:209], v[20:23]
	v_mfma_f32_16x16x32_bf16 v[16:19], v[180:183], v[206:209], v[16:19]
	v_mfma_f32_16x16x32_bf16 v[4:7], v[172:175], v[214:217], v[4:7]
	v_mfma_f32_16x16x32_bf16 v[0:3], v[180:183], v[214:217], v[0:3]
	s_barrier
	s_add_i32 s33, 0, 0x18000
	s_add_i32 s54, 0, 0x1c000
	v_add_u32_e32 v164, s33, v153
	v_add_u32_e32 v180, s54, v153
	ds_read_b128 v[144:147], v164
	ds_read_b128 v[148:151], v164 offset:1024
	ds_read_b128 v[160:163], v164 offset:2048
	ds_read_b128 v[164:167], v164 offset:3072
	ds_read_b128 v[168:171], v180
	ds_read_b128 v[172:175], v180 offset:1024
	ds_read_b128 v[176:179], v180 offset:2048
	ds_read_b128 v[180:183], v180 offset:3072
	s_add_u32 s36, s36, 0x80000
	s_addc_u32 s37, s37, 0
	s_mov_b32 m0, s50
	v_lshl_add_u64 v[226:227], s[36:37], 0, v[134:135]
	ds_read_b128 v[184:187], v157 offset:32768
	ds_read_b128 v[188:191], v157 offset:33792
	ds_read_b128 v[194:197], v157 offset:34816
	ds_read_b128 v[198:201], v157 offset:35840
	ds_read_b128 v[202:205], v157 offset:36864
	ds_read_b128 v[206:209], v157 offset:37888
	ds_read_b128 v[210:213], v157 offset:38912
	ds_read_b128 v[214:217], v157 offset:39936
	global_load_lds_dwordx4 v[226:227], off
	v_lshl_add_u64 v[226:227], s[36:37], 0, v[130:131]
	s_mov_b32 m0, s51
	s_nop 0
	global_load_lds_dwordx4 v[226:227], off
	s_waitcnt vmcnt(8)
	s_waitcnt lgkmcnt(0)
	s_barrier
	s_waitcnt lgkmcnt(0)
	v_mfma_f32_16x16x32_bf16 v[124:127], v[144:147], v[184:187], v[124:127]
	v_mfma_f32_16x16x32_bf16 v[120:123], v[160:163], v[184:187], v[120:123]
	v_mfma_f32_16x16x32_bf16 v[108:111], v[144:147], v[194:197], v[108:111]
	v_mfma_f32_16x16x32_bf16 v[104:107], v[160:163], v[194:197], v[104:107]
	v_mfma_f32_16x16x32_bf16 v[92:95], v[144:147], v[202:205], v[92:95]
	v_mfma_f32_16x16x32_bf16 v[88:91], v[160:163], v[202:205], v[88:91]
	v_mfma_f32_16x16x32_bf16 v[76:79], v[144:147], v[210:213], v[76:79]
	v_mfma_f32_16x16x32_bf16 v[72:75], v[160:163], v[210:213], v[72:75]
	v_mfma_f32_16x16x32_bf16 v[124:127], v[148:151], v[188:191], v[124:127]
	v_mfma_f32_16x16x32_bf16 v[120:123], v[164:167], v[188:191], v[120:123]
	v_mfma_f32_16x16x32_bf16 v[108:111], v[148:151], v[198:201], v[108:111]
	v_mfma_f32_16x16x32_bf16 v[104:107], v[164:167], v[198:201], v[104:107]
	v_mfma_f32_16x16x32_bf16 v[92:95], v[148:151], v[206:209], v[92:95]
	v_mfma_f32_16x16x32_bf16 v[88:91], v[164:167], v[206:209], v[88:91]
	v_mfma_f32_16x16x32_bf16 v[76:79], v[148:151], v[214:217], v[76:79]
	v_mfma_f32_16x16x32_bf16 v[72:75], v[164:167], v[214:217], v[72:75]
	v_mfma_f32_16x16x32_bf16 v[116:119], v[168:171], v[184:187], v[116:119]
	v_mfma_f32_16x16x32_bf16 v[112:115], v[176:179], v[184:187], v[112:115]
	v_mfma_f32_16x16x32_bf16 v[100:103], v[168:171], v[194:197], v[100:103]
	v_mfma_f32_16x16x32_bf16 v[96:99], v[176:179], v[194:197], v[96:99]
	v_mfma_f32_16x16x32_bf16 v[84:87], v[168:171], v[202:205], v[84:87]
	v_mfma_f32_16x16x32_bf16 v[80:83], v[176:179], v[202:205], v[80:83]
	v_mfma_f32_16x16x32_bf16 v[68:71], v[168:171], v[210:213], v[68:71]
	v_mfma_f32_16x16x32_bf16 v[64:67], v[176:179], v[210:213], v[64:67]
	v_mfma_f32_16x16x32_bf16 v[116:119], v[172:175], v[188:191], v[116:119]
	v_mfma_f32_16x16x32_bf16 v[112:115], v[180:183], v[188:191], v[112:115]
	v_mfma_f32_16x16x32_bf16 v[100:103], v[172:175], v[198:201], v[100:103]
	v_mfma_f32_16x16x32_bf16 v[96:99], v[180:183], v[198:201], v[96:99]
	v_mfma_f32_16x16x32_bf16 v[84:87], v[172:175], v[206:209], v[84:87]
	v_mfma_f32_16x16x32_bf16 v[80:83], v[180:183], v[206:209], v[80:83]
	v_mfma_f32_16x16x32_bf16 v[68:71], v[172:175], v[214:217], v[68:71]
	v_mfma_f32_16x16x32_bf16 v[64:67], v[180:183], v[214:217], v[64:67]
	s_barrier
	s_add_i32 s33, s33, s42
	v_lshl_add_u64 v[218:219], v[218:219], 0, s[18:19]
	s_mov_b32 m0, s33
	ds_read_b128 v[184:187], v157 offset:49152
	ds_read_b128 v[188:191], v157 offset:50176
	ds_read_b128 v[194:197], v157 offset:51200
	ds_read_b128 v[198:201], v157 offset:52224
	ds_read_b128 v[202:205], v157 offset:53248
	ds_read_b128 v[206:209], v157 offset:54272
	ds_read_b128 v[210:213], v157 offset:55296
	ds_read_b128 v[214:217], v157 offset:56320
	global_load_lds_dwordx4 v[218:219], off
	s_add_i32 m0, s33, 0x2000
	s_add_u32 s34, s34, 0x80080
	v_lshl_add_u64 v[218:219], v[220:221], 0, s[18:19]
	s_addc_u32 s35, s35, 0
	s_add_i32 s33, s54, s42
	global_load_lds_dwordx4 v[218:219], off
	v_lshl_add_u64 v[218:219], s[34:35], 0, v[132:133]
	s_mov_b32 m0, s33
	s_nop 0
	global_load_lds_dwordx4 v[218:219], off
	v_lshl_add_u64 v[218:219], s[34:35], 0, v[128:129]
	s_add_i32 m0, s33, 0x2000
	s_nop 0
	global_load_lds_dwordx4 v[218:219], off
	v_lshl_add_u64 v[218:219], v[222:223], 0, s[18:19]
	s_mov_b32 m0, s57
	s_nop 0
	global_load_lds_dwordx4 v[218:219], off
	v_lshl_add_u64 v[218:219], v[224:225], 0, s[18:19]
	s_mov_b32 m0, s58
	s_nop 0
	global_load_lds_dwordx4 v[218:219], off
	s_waitcnt vmcnt(8)
	s_waitcnt lgkmcnt(0)
	s_barrier
	s_waitcnt lgkmcnt(0)
	v_mfma_f32_16x16x32_bf16 v[60:63], v[144:147], v[184:187], v[60:63]
	v_mfma_f32_16x16x32_bf16 v[56:59], v[160:163], v[184:187], v[56:59]
	v_mfma_f32_16x16x32_bf16 v[44:47], v[144:147], v[194:197], v[44:47]
	v_mfma_f32_16x16x32_bf16 v[40:43], v[160:163], v[194:197], v[40:43]
	v_mfma_f32_16x16x32_bf16 v[28:31], v[144:147], v[202:205], v[28:31]
	v_mfma_f32_16x16x32_bf16 v[24:27], v[160:163], v[202:205], v[24:27]
	v_mfma_f32_16x16x32_bf16 v[12:15], v[144:147], v[210:213], v[12:15]
	v_mfma_f32_16x16x32_bf16 v[8:11], v[160:163], v[210:213], v[8:11]
	v_mfma_f32_16x16x32_bf16 v[60:63], v[148:151], v[188:191], v[60:63]
	v_mfma_f32_16x16x32_bf16 v[56:59], v[164:167], v[188:191], v[56:59]
	v_mfma_f32_16x16x32_bf16 v[44:47], v[148:151], v[198:201], v[44:47]
	v_mfma_f32_16x16x32_bf16 v[40:43], v[164:167], v[198:201], v[40:43]
	v_mfma_f32_16x16x32_bf16 v[28:31], v[148:151], v[206:209], v[28:31]
	v_mfma_f32_16x16x32_bf16 v[24:27], v[164:167], v[206:209], v[24:27]
	v_mfma_f32_16x16x32_bf16 v[12:15], v[148:151], v[214:217], v[12:15]
	v_mfma_f32_16x16x32_bf16 v[8:11], v[164:167], v[214:217], v[8:11]
	v_mfma_f32_16x16x32_bf16 v[52:55], v[168:171], v[184:187], v[52:55]
	v_mfma_f32_16x16x32_bf16 v[48:51], v[176:179], v[184:187], v[48:51]
	v_mfma_f32_16x16x32_bf16 v[36:39], v[168:171], v[194:197], v[36:39]
	v_mfma_f32_16x16x32_bf16 v[32:35], v[176:179], v[194:197], v[32:35]
	v_mfma_f32_16x16x32_bf16 v[20:23], v[168:171], v[202:205], v[20:23]
	v_mfma_f32_16x16x32_bf16 v[16:19], v[176:179], v[202:205], v[16:19]
	v_mfma_f32_16x16x32_bf16 v[4:7], v[168:171], v[210:213], v[4:7]
	v_mfma_f32_16x16x32_bf16 v[0:3], v[176:179], v[210:213], v[0:3]
	v_mfma_f32_16x16x32_bf16 v[52:55], v[172:175], v[188:191], v[52:55]
	v_mfma_f32_16x16x32_bf16 v[48:51], v[180:183], v[188:191], v[48:51]
	v_mfma_f32_16x16x32_bf16 v[36:39], v[172:175], v[198:201], v[36:39]
	v_mfma_f32_16x16x32_bf16 v[32:35], v[180:183], v[198:201], v[32:35]
	v_mfma_f32_16x16x32_bf16 v[20:23], v[172:175], v[206:209], v[20:23]
	v_mfma_f32_16x16x32_bf16 v[16:19], v[180:183], v[206:209], v[16:19]
	v_mfma_f32_16x16x32_bf16 v[4:7], v[172:175], v[214:217], v[4:7]
	v_mfma_f32_16x16x32_bf16 v[0:3], v[180:183], v[214:217], v[0:3]
	s_barrier
	s_add_i32 s67, s67, 2
	s_add_u32 s30, s30, 0x100
	s_addc_u32 s31, s31, 0
	s_add_u32 s65, s65, 0x100
	s_addc_u32 s66, s66, 0
	s_cmp_gt_u32 s67, 29
	s_cbranch_scc0 .LBB0_1271
	v_lshl_add_u32 v144, s8, 8, v152
	v_ashrrev_i32_e32 v145, 31, v144
	v_lshl_add_u64 v[150:151], v[144:145], 2, s[16:17]
	global_load_dword v172, v[150:151], off
	global_load_dword v173, v[150:151], off offset:64
	global_load_dword v174, v[150:151], off offset:128
	global_load_dword v175, v[150:151], off offset:192
	global_load_dword v176, v[150:151], off offset:512
	global_load_dword v177, v[150:151], off offset:576
	global_load_dword v178, v[150:151], off offset:640
	global_load_dword v179, v[150:151], off offset:704
	s_and_b64 vcc, exec, s[20:21]
	s_cbranch_vccz .LBB0_1274
	s_barrier

.LBB0_1420:
	ds_read_b128 v[152:155], v161
	ds_read_b128 v[166:169], v161 offset:1024
	ds_read_b128 v[170:173], v161 offset:2048
	ds_read_b128 v[174:177], v161 offset:3072
	ds_read_b128 v[178:181], v162
	ds_read_b128 v[182:185], v162 offset:1024
	ds_read_b128 v[186:189], v162 offset:2048
	ds_read_b128 v[194:197], v162 offset:3072
	s_add_u32 s33, s38, 0xfff80080
	s_addc_u32 s40, s39, -1
	s_cmp_eq_u32 s68, 28
	s_cselect_b32 s43, s27, s40
	s_cselect_b32 s42, s35, s33
	s_cselect_b32 s41, s25, s67
	s_cselect_b32 s40, s65, s66
	v_lshl_add_u64 v[156:157], s[38:39], 0, v[136:137]
	s_add_i32 m0, s37, 0xc000
	ds_read_b128 v[198:201], v163
	ds_read_b128 v[202:205], v163 offset:1024
	ds_read_b128 v[206:209], v163 offset:2048
	ds_read_b128 v[210:213], v163 offset:3072
	ds_read_b128 v[214:217], v163 offset:4096
	ds_read_b128 v[218:221], v163 offset:5120
	ds_read_b128 v[222:225], v163 offset:6144
	ds_read_b128 v[226:229], v163 offset:7168
	global_load_lds_dwordx4 v[156:157], off
	v_lshl_add_u64 v[156:157], s[38:39], 0, v[138:139]
	s_add_i32 m0, s37, 0xe000
	s_nop 0
	global_load_lds_dwordx4 v[156:157], off
	s_waitcnt vmcnt(8)
	s_waitcnt lgkmcnt(0)
	s_barrier
	s_waitcnt lgkmcnt(0)
	v_mfma_f32_16x16x32_bf16 v[124:127], v[152:155], v[198:201], v[124:127]
	v_mfma_f32_16x16x32_bf16 v[120:123], v[170:173], v[198:201], v[120:123]
	v_mfma_f32_16x16x32_bf16 v[108:111], v[152:155], v[206:209], v[108:111]
	v_mfma_f32_16x16x32_bf16 v[104:107], v[170:173], v[206:209], v[104:107]
	v_mfma_f32_16x16x32_bf16 v[92:95], v[152:155], v[214:217], v[92:95]
	v_mfma_f32_16x16x32_bf16 v[88:91], v[170:173], v[214:217], v[88:91]
	v_mfma_f32_16x16x32_bf16 v[76:79], v[152:155], v[222:225], v[76:79]
	v_mfma_f32_16x16x32_bf16 v[72:75], v[170:173], v[222:225], v[72:75]
	v_mfma_f32_16x16x32_bf16 v[124:127], v[166:169], v[202:205], v[124:127]
	v_mfma_f32_16x16x32_bf16 v[120:123], v[174:177], v[202:205], v[120:123]
	v_mfma_f32_16x16x32_bf16 v[108:111], v[166:169], v[210:213], v[108:111]
	v_mfma_f32_16x16x32_bf16 v[104:107], v[174:177], v[210:213], v[104:107]
	v_mfma_f32_16x16x32_bf16 v[92:95], v[166:169], v[218:221], v[92:95]
	v_mfma_f32_16x16x32_bf16 v[88:91], v[174:177], v[218:221], v[88:91]
	v_mfma_f32_16x16x32_bf16 v[76:79], v[166:169], v[226:229], v[76:79]
	v_mfma_f32_16x16x32_bf16 v[72:75], v[174:177], v[226:229], v[72:75]
	v_mfma_f32_16x16x32_bf16 v[116:119], v[178:181], v[198:201], v[116:119]
	v_mfma_f32_16x16x32_bf16 v[112:115], v[186:189], v[198:201], v[112:115]
	v_mfma_f32_16x16x32_bf16 v[100:103], v[178:181], v[206:209], v[100:103]
	v_mfma_f32_16x16x32_bf16 v[96:99], v[186:189], v[206:209], v[96:99]
	v_mfma_f32_16x16x32_bf16 v[84:87], v[178:181], v[214:217], v[84:87]
	v_mfma_f32_16x16x32_bf16 v[80:83], v[186:189], v[214:217], v[80:83]
	v_mfma_f32_16x16x32_bf16 v[68:71], v[178:181], v[222:225], v[68:71]
	v_mfma_f32_16x16x32_bf16 v[64:67], v[186:189], v[222:225], v[64:67]
	v_mfma_f32_16x16x32_bf16 v[116:119], v[182:185], v[202:205], v[116:119]
	v_mfma_f32_16x16x32_bf16 v[112:115], v[194:197], v[202:205], v[112:115]
	v_mfma_f32_16x16x32_bf16 v[100:103], v[182:185], v[210:213], v[100:103]
	v_mfma_f32_16x16x32_bf16 v[96:99], v[194:197], v[210:213], v[96:99]
	v_mfma_f32_16x16x32_bf16 v[84:87], v[182:185], v[218:221], v[84:87]
	v_mfma_f32_16x16x32_bf16 v[80:83], v[194:197], v[218:221], v[80:83]
	v_mfma_f32_16x16x32_bf16 v[68:71], v[182:185], v[226:229], v[68:71]
	v_mfma_f32_16x16x32_bf16 v[64:67], v[194:197], v[226:229], v[64:67]
	s_barrier
	s_add_i32 s33, s63, s56
	v_lshl_add_u64 v[156:157], s[40:41], 0, v[130:131]
	s_mov_b32 m0, s33
	ds_read_b128 v[198:201], v163 offset:16384
	ds_read_b128 v[202:205], v163 offset:17408
	ds_read_b128 v[206:209], v163 offset:18432
	ds_read_b128 v[210:213], v163 offset:19456
	ds_read_b128 v[214:217], v163 offset:20480
	ds_read_b128 v[218:221], v163 offset:21504
	ds_read_b128 v[222:225], v163 offset:22528
	ds_read_b128 v[226:229], v163 offset:23552
	global_load_lds_dwordx4 v[156:157], off
	s_add_i32 m0, s33, 0x2000
	s_add_u32 s54, s40, 0x80000
	v_lshl_add_u64 v[190:191], s[40:41], 0, v[134:135]
	s_addc_u32 s55, s41, 0
	s_add_i32 s33, s64, s56
	global_load_lds_dwordx4 v[190:191], off
	v_lshl_add_u64 v[230:231], s[54:55], 0, v[130:131]
	s_mov_b32 m0, s33
	v_lshl_add_u64 v[232:233], s[42:43], 0, v[132:133]
	global_load_lds_dwordx4 v[230:231], off
	v_lshl_add_u64 v[230:231], s[54:55], 0, v[134:135]
	s_add_i32 m0, s33, 0x2000
	s_nop 0
	global_load_lds_dwordx4 v[230:231], off
	v_lshl_add_u64 v[230:231], s[42:43], 0, v[128:129]
	s_mov_b32 m0, s37
	s_nop 0
	global_load_lds_dwordx4 v[230:231], off
	s_mov_b32 m0, s57
	s_nop 0
	global_load_lds_dwordx4 v[232:233], off
	s_waitcnt vmcnt(8)
	s_waitcnt lgkmcnt(0)
	s_barrier
	s_waitcnt lgkmcnt(0)
	v_mfma_f32_16x16x32_bf16 v[60:63], v[152:155], v[198:201], v[60:63]
	v_mfma_f32_16x16x32_bf16 v[56:59], v[170:173], v[198:201], v[56:59]
	v_mfma_f32_16x16x32_bf16 v[44:47], v[152:155], v[206:209], v[44:47]
	v_mfma_f32_16x16x32_bf16 v[40:43], v[170:173], v[206:209], v[40:43]
	v_mfma_f32_16x16x32_bf16 v[28:31], v[152:155], v[214:217], v[28:31]
	v_mfma_f32_16x16x32_bf16 v[24:27], v[170:173], v[214:217], v[24:27]
	v_mfma_f32_16x16x32_bf16 v[12:15], v[152:155], v[222:225], v[12:15]
	v_mfma_f32_16x16x32_bf16 v[8:11], v[170:173], v[222:225], v[8:11]
	v_mfma_f32_16x16x32_bf16 v[60:63], v[166:169], v[202:205], v[60:63]
	v_mfma_f32_16x16x32_bf16 v[56:59], v[174:177], v[202:205], v[56:59]
	v_mfma_f32_16x16x32_bf16 v[44:47], v[166:169], v[210:213], v[44:47]
	v_mfma_f32_16x16x32_bf16 v[40:43], v[174:177], v[210:213], v[40:43]
	v_mfma_f32_16x16x32_bf16 v[28:31], v[166:169], v[218:221], v[28:31]
	v_mfma_f32_16x16x32_bf16 v[24:27], v[174:177], v[218:221], v[24:27]
	v_mfma_f32_16x16x32_bf16 v[12:15], v[166:169], v[226:229], v[12:15]
	v_mfma_f32_16x16x32_bf16 v[8:11], v[174:177], v[226:229], v[8:11]
	v_mfma_f32_16x16x32_bf16 v[52:55], v[178:181], v[198:201], v[52:55]
	v_mfma_f32_16x16x32_bf16 v[48:51], v[186:189], v[198:201], v[48:51]
	v_mfma_f32_16x16x32_bf16 v[36:39], v[178:181], v[206:209], v[36:39]
	v_mfma_f32_16x16x32_bf16 v[32:35], v[186:189], v[206:209], v[32:35]
	v_mfma_f32_16x16x32_bf16 v[20:23], v[178:181], v[214:217], v[20:23]
	v_mfma_f32_16x16x32_bf16 v[16:19], v[186:189], v[214:217], v[16:19]
	v_mfma_f32_16x16x32_bf16 v[4:7], v[178:181], v[222:225], v[4:7]
	v_mfma_f32_16x16x32_bf16 v[0:3], v[186:189], v[222:225], v[0:3]
	v_mfma_f32_16x16x32_bf16 v[52:55], v[182:185], v[202:205], v[52:55]
	v_mfma_f32_16x16x32_bf16 v[48:51], v[194:197], v[202:205], v[48:51]
	v_mfma_f32_16x16x32_bf16 v[36:39], v[182:185], v[210:213], v[36:39]
	v_mfma_f32_16x16x32_bf16 v[32:35], v[194:197], v[210:213], v[32:35]
	v_mfma_f32_16x16x32_bf16 v[20:23], v[182:185], v[218:221], v[20:23]
	v_mfma_f32_16x16x32_bf16 v[16:19], v[194:197], v[218:221], v[16:19]
	v_mfma_f32_16x16x32_bf16 v[4:7], v[182:185], v[226:229], v[4:7]
	v_mfma_f32_16x16x32_bf16 v[0:3], v[194:197], v[226:229], v[0:3]
	s_barrier
	s_add_i32 s33, 0, 0x18000
	v_add_u32_e32 v165, s33, v159
	s_add_i32 s54, 0, 0x1c000
	ds_read_b128 v[152:155], v165
	ds_read_b128 v[166:169], v165 offset:1024
	ds_read_b128 v[170:173], v165 offset:2048
	ds_read_b128 v[174:177], v165 offset:3072
	v_add_u32_e32 v165, s54, v159
	ds_read_b128 v[178:181], v165
	ds_read_b128 v[182:185], v165 offset:1024
	ds_read_b128 v[186:189], v165 offset:2048
	ds_read_b128 v[194:197], v165 offset:3072
	s_add_u32 s42, s42, 0x80000
	s_addc_u32 s43, s43, 0
	s_mov_b32 m0, s58
	v_lshl_add_u64 v[234:235], s[42:43], 0, v[128:129]
	ds_read_b128 v[198:201], v163 offset:32768
	ds_read_b128 v[202:205], v163 offset:33792
	ds_read_b128 v[206:209], v163 offset:34816
	ds_read_b128 v[210:213], v163 offset:35840
	ds_read_b128 v[214:217], v163 offset:36864
	ds_read_b128 v[218:221], v163 offset:37888
	ds_read_b128 v[222:225], v163 offset:38912
	ds_read_b128 v[226:229], v163 offset:39936
	global_load_lds_dwordx4 v[234:235], off
	v_lshl_add_u64 v[234:235], s[42:43], 0, v[132:133]
	s_mov_b32 m0, s59
	s_nop 0
	global_load_lds_dwordx4 v[234:235], off
	s_waitcnt vmcnt(8)
	s_waitcnt lgkmcnt(0)
	s_barrier
	s_waitcnt lgkmcnt(0)
	v_mfma_f32_16x16x32_bf16 v[124:127], v[152:155], v[198:201], v[124:127]
	v_mfma_f32_16x16x32_bf16 v[120:123], v[170:173], v[198:201], v[120:123]
	v_mfma_f32_16x16x32_bf16 v[108:111], v[152:155], v[206:209], v[108:111]
	v_mfma_f32_16x16x32_bf16 v[104:107], v[170:173], v[206:209], v[104:107]
	v_mfma_f32_16x16x32_bf16 v[92:95], v[152:155], v[214:217], v[92:95]
	v_mfma_f32_16x16x32_bf16 v[88:91], v[170:173], v[214:217], v[88:91]
	v_mfma_f32_16x16x32_bf16 v[76:79], v[152:155], v[222:225], v[76:79]
	v_mfma_f32_16x16x32_bf16 v[72:75], v[170:173], v[222:225], v[72:75]
	v_mfma_f32_16x16x32_bf16 v[124:127], v[166:169], v[202:205], v[124:127]
	v_mfma_f32_16x16x32_bf16 v[120:123], v[174:177], v[202:205], v[120:123]
	v_mfma_f32_16x16x32_bf16 v[108:111], v[166:169], v[210:213], v[108:111]
	v_mfma_f32_16x16x32_bf16 v[104:107], v[174:177], v[210:213], v[104:107]
	v_mfma_f32_16x16x32_bf16 v[92:95], v[166:169], v[218:221], v[92:95]
	v_mfma_f32_16x16x32_bf16 v[88:91], v[174:177], v[218:221], v[88:91]
	v_mfma_f32_16x16x32_bf16 v[76:79], v[166:169], v[226:229], v[76:79]
	v_mfma_f32_16x16x32_bf16 v[72:75], v[174:177], v[226:229], v[72:75]
	v_mfma_f32_16x16x32_bf16 v[116:119], v[178:181], v[198:201], v[116:119]
	v_mfma_f32_16x16x32_bf16 v[112:115], v[186:189], v[198:201], v[112:115]
	v_mfma_f32_16x16x32_bf16 v[100:103], v[178:181], v[206:209], v[100:103]
	v_mfma_f32_16x16x32_bf16 v[96:99], v[186:189], v[206:209], v[96:99]
	v_mfma_f32_16x16x32_bf16 v[84:87], v[178:181], v[214:217], v[84:87]
	v_mfma_f32_16x16x32_bf16 v[80:83], v[186:189], v[214:217], v[80:83]
	v_mfma_f32_16x16x32_bf16 v[68:71], v[178:181], v[222:225], v[68:71]
	v_mfma_f32_16x16x32_bf16 v[64:67], v[186:189], v[222:225], v[64:67]
	v_mfma_f32_16x16x32_bf16 v[116:119], v[182:185], v[202:205], v[116:119]
	v_mfma_f32_16x16x32_bf16 v[112:115], v[194:197], v[202:205], v[112:115]
	v_mfma_f32_16x16x32_bf16 v[100:103], v[182:185], v[210:213], v[100:103]
	v_mfma_f32_16x16x32_bf16 v[96:99], v[194:197], v[210:213], v[96:99]
	v_mfma_f32_16x16x32_bf16 v[84:87], v[182:185], v[218:221], v[84:87]
	v_mfma_f32_16x16x32_bf16 v[80:83], v[194:197], v[218:221], v[80:83]
	v_mfma_f32_16x16x32_bf16 v[68:71], v[182:185], v[226:229], v[68:71]
	v_mfma_f32_16x16x32_bf16 v[64:67], v[194:197], v[226:229], v[64:67]
	s_barrier
	s_add_i32 s33, s33, s56
	v_lshl_add_u64 v[156:157], v[156:157], 0, s[20:21]
	s_mov_b32 m0, s33
	ds_read_b128 v[198:201], v163 offset:49152
	ds_read_b128 v[202:205], v163 offset:50176
	ds_read_b128 v[206:209], v163 offset:51200
	ds_read_b128 v[210:213], v163 offset:52224
	ds_read_b128 v[214:217], v163 offset:53248
	ds_read_b128 v[218:221], v163 offset:54272
	ds_read_b128 v[222:225], v163 offset:55296
	ds_read_b128 v[226:229], v163 offset:56320
	global_load_lds_dwordx4 v[156:157], off
	s_add_i32 m0, s33, 0x2000
	s_add_u32 s40, s40, 0x80080
	v_lshl_add_u64 v[156:157], v[190:191], 0, s[20:21]
	s_addc_u32 s41, s41, 0
	s_add_i32 s33, s54, s56
	global_load_lds_dwordx4 v[156:157], off
	v_lshl_add_u64 v[156:157], s[40:41], 0, v[130:131]
	s_mov_b32 m0, s33
	s_nop 0
	global_load_lds_dwordx4 v[156:157], off
	v_lshl_add_u64 v[156:157], s[40:41], 0, v[134:135]
	s_add_i32 m0, s33, 0x2000
	s_nop 0
	global_load_lds_dwordx4 v[156:157], off
	v_lshl_add_u64 v[156:157], v[230:231], 0, s[20:21]
	s_mov_b32 m0, s61
	s_nop 0
	global_load_lds_dwordx4 v[156:157], off
	v_lshl_add_u64 v[156:157], v[232:233], 0, s[20:21]
	s_mov_b32 m0, s62
	s_nop 0
	global_load_lds_dwordx4 v[156:157], off
	s_waitcnt vmcnt(8)
	s_waitcnt lgkmcnt(0)
	s_barrier
	s_waitcnt lgkmcnt(0)
	v_mfma_f32_16x16x32_bf16 v[60:63], v[152:155], v[198:201], v[60:63]
	v_mfma_f32_16x16x32_bf16 v[56:59], v[170:173], v[198:201], v[56:59]
	v_mfma_f32_16x16x32_bf16 v[44:47], v[152:155], v[206:209], v[44:47]
	v_mfma_f32_16x16x32_bf16 v[40:43], v[170:173], v[206:209], v[40:43]
	v_mfma_f32_16x16x32_bf16 v[28:31], v[152:155], v[214:217], v[28:31]
	v_mfma_f32_16x16x32_bf16 v[24:27], v[170:173], v[214:217], v[24:27]
	v_mfma_f32_16x16x32_bf16 v[12:15], v[152:155], v[222:225], v[12:15]
	v_mfma_f32_16x16x32_bf16 v[8:11], v[170:173], v[222:225], v[8:11]
	v_mfma_f32_16x16x32_bf16 v[60:63], v[166:169], v[202:205], v[60:63]
	v_mfma_f32_16x16x32_bf16 v[56:59], v[174:177], v[202:205], v[56:59]
	v_mfma_f32_16x16x32_bf16 v[44:47], v[166:169], v[210:213], v[44:47]
	v_mfma_f32_16x16x32_bf16 v[40:43], v[174:177], v[210:213], v[40:43]
	v_mfma_f32_16x16x32_bf16 v[28:31], v[166:169], v[218:221], v[28:31]
	v_mfma_f32_16x16x32_bf16 v[24:27], v[174:177], v[218:221], v[24:27]
	v_mfma_f32_16x16x32_bf16 v[12:15], v[166:169], v[226:229], v[12:15]
	v_mfma_f32_16x16x32_bf16 v[8:11], v[174:177], v[226:229], v[8:11]
	v_mfma_f32_16x16x32_bf16 v[52:55], v[178:181], v[198:201], v[52:55]
	v_mfma_f32_16x16x32_bf16 v[48:51], v[186:189], v[198:201], v[48:51]
	v_mfma_f32_16x16x32_bf16 v[36:39], v[178:181], v[206:209], v[36:39]
	v_mfma_f32_16x16x32_bf16 v[32:35], v[186:189], v[206:209], v[32:35]
	v_mfma_f32_16x16x32_bf16 v[20:23], v[178:181], v[214:217], v[20:23]
	v_mfma_f32_16x16x32_bf16 v[16:19], v[186:189], v[214:217], v[16:19]
	v_mfma_f32_16x16x32_bf16 v[4:7], v[178:181], v[222:225], v[4:7]
	v_mfma_f32_16x16x32_bf16 v[0:3], v[186:189], v[222:225], v[0:3]
	v_mfma_f32_16x16x32_bf16 v[52:55], v[182:185], v[202:205], v[52:55]
	v_mfma_f32_16x16x32_bf16 v[48:51], v[194:197], v[202:205], v[48:51]
	v_mfma_f32_16x16x32_bf16 v[36:39], v[182:185], v[210:213], v[36:39]
	v_mfma_f32_16x16x32_bf16 v[32:35], v[194:197], v[210:213], v[32:35]
	v_mfma_f32_16x16x32_bf16 v[20:23], v[182:185], v[218:221], v[20:23]
	v_mfma_f32_16x16x32_bf16 v[16:19], v[194:197], v[218:221], v[16:19]
	v_mfma_f32_16x16x32_bf16 v[4:7], v[182:185], v[226:229], v[4:7]
	v_mfma_f32_16x16x32_bf16 v[0:3], v[194:197], v[226:229], v[0:3]
	s_barrier
	s_add_i32 s68, s68, 2
	s_add_u32 s38, s38, 0x100
	s_addc_u32 s39, s39, 0
	s_add_u32 s66, s66, 0x100
	s_addc_u32 s67, s67, 0
	s_cmp_gt_u32 s68, 29
	s_cbranch_scc0 .LBB0_1420
	v_lshl_add_u32 v156, s34, 8, v158
	v_lshl_or_b32 v154, s36, 8, v160
	v_ashrrev_i32_e32 v157, 31, v156
	v_ashrrev_i32_e32 v155, 31, v154
	v_lshlrev_b64 v[152:153], 11, v[156:157]
	v_lshl_add_u64 v[152:153], v[152:153], 0, v[154:155]
	v_lshlrev_b64 v[170:171], 1, v[152:153]
	v_lshl_add_u64 v[172:173], s[12:13], 0, v[170:171]
	global_load_dwordx4 v[180:183], v[172:173], off
	global_load_dwordx4 v[184:187], v[172:173], off offset:256
	v_add_co_u32_e32 v252, vcc, 0x10000, v172
	s_nop 1
	v_addc_co_u32_e32 v253, vcc, 0, v173, vcc
	global_load_dwordx4 v[188:191], v[252:253], off
	global_load_dwordx4 v[194:197], v[252:253], off offset:256
	v_add_co_u32_e32 v254, vcc, 0x20000, v172
	s_nop 1
	v_addc_co_u32_e32 v255, vcc, 0, v173, vcc
	global_load_dwordx4 v[198:201], v[254:255], off
	global_load_dwordx4 v[202:205], v[254:255], off offset:256
	v_add_co_u32_e32 v252, vcc, 0x30000, v172
	s_nop 1
	v_addc_co_u32_e32 v253, vcc, 0, v173, vcc
	global_load_dwordx4 v[206:209], v[252:253], off
	global_load_dwordx4 v[210:213], v[252:253], off offset:256
	v_add_co_u32_e32 v254, vcc, 0x80000, v172
	s_nop 1
	v_addc_co_u32_e32 v255, vcc, 0, v173, vcc
	global_load_dwordx4 v[214:217], v[254:255], off
	global_load_dwordx4 v[218:221], v[254:255], off offset:256
	v_add_co_u32_e32 v252, vcc, 0x90000, v172
	s_nop 1
	v_addc_co_u32_e32 v253, vcc, 0, v173, vcc
	global_load_dwordx4 v[222:225], v[252:253], off
	global_load_dwordx4 v[226:229], v[252:253], off offset:256
	v_add_co_u32_e32 v254, vcc, 0xa0000, v172
	s_nop 1
	v_addc_co_u32_e32 v255, vcc, 0, v173, vcc
	global_load_dwordx4 v[230:233], v[254:255], off
	global_load_dwordx4 v[234:237], v[254:255], off offset:256
	v_add_co_u32_e32 v252, vcc, 0xb0000, v172
	s_nop 1
	v_addc_co_u32_e32 v253, vcc, 0, v173, vcc
	global_load_dwordx4 v[238:241], v[252:253], off
	global_load_dwordx4 v[242:245], v[252:253], off offset:256
	s_and_b64 vcc, exec, s[22:23]
	s_cbranch_vccz .LBB0_1423
	s_barrier

.LBB0_1504:
	ds_read_b128 v[144:147], v153
	ds_read_b128 v[158:161], v153 offset:1024
	ds_read_b128 v[162:165], v153 offset:2048
	ds_read_b128 v[166:169], v153 offset:3072
	ds_read_b128 v[170:173], v154
	ds_read_b128 v[174:177], v154 offset:1024
	ds_read_b128 v[178:181], v154 offset:2048
	ds_read_b128 v[182:185], v154 offset:3072
	s_add_u32 s30, s28, 0xfff80080
	s_addc_u32 s31, s29, -1
	s_cmp_eq_u32 s65, 28
	s_cselect_b32 s35, s23, s31
	s_cselect_b32 s34, s61, s30
	s_cselect_b32 s31, s21, s64
	s_cselect_b32 s30, s62, s63
	v_lshl_add_u64 v[148:149], s[28:29], 0, v[136:137]
	s_add_i32 m0, s42, 0xc000
	ds_read_b128 v[186:189], v155
	ds_read_b128 v[194:197], v155 offset:1024
	ds_read_b128 v[198:201], v155 offset:2048
	ds_read_b128 v[202:205], v155 offset:3072
	ds_read_b128 v[206:209], v155 offset:4096
	ds_read_b128 v[210:213], v155 offset:5120
	ds_read_b128 v[214:217], v155 offset:6144
	ds_read_b128 v[218:221], v155 offset:7168
	global_load_lds_dwordx4 v[148:149], off
	v_lshl_add_u64 v[148:149], s[28:29], 0, v[138:139]
	s_add_i32 m0, s42, 0xe000
	s_nop 0
	global_load_lds_dwordx4 v[148:149], off
	s_waitcnt vmcnt(8)
	s_waitcnt lgkmcnt(0)
	s_barrier
	s_waitcnt lgkmcnt(0)
	v_mfma_f32_16x16x32_bf16 v[116:119], v[144:147], v[186:189], v[116:119]
	v_mfma_f32_16x16x32_bf16 v[112:115], v[162:165], v[186:189], v[112:115]
	v_mfma_f32_16x16x32_bf16 v[100:103], v[144:147], v[198:201], v[100:103]
	v_mfma_f32_16x16x32_bf16 v[96:99], v[162:165], v[198:201], v[96:99]
	v_mfma_f32_16x16x32_bf16 v[84:87], v[144:147], v[206:209], v[84:87]
	v_mfma_f32_16x16x32_bf16 v[80:83], v[162:165], v[206:209], v[80:83]
	v_mfma_f32_16x16x32_bf16 v[68:71], v[144:147], v[214:217], v[68:71]
	v_mfma_f32_16x16x32_bf16 v[64:67], v[162:165], v[214:217], v[64:67]
	v_mfma_f32_16x16x32_bf16 v[116:119], v[158:161], v[194:197], v[116:119]
	v_mfma_f32_16x16x32_bf16 v[112:115], v[166:169], v[194:197], v[112:115]
	v_mfma_f32_16x16x32_bf16 v[100:103], v[158:161], v[202:205], v[100:103]
	v_mfma_f32_16x16x32_bf16 v[96:99], v[166:169], v[202:205], v[96:99]
	v_mfma_f32_16x16x32_bf16 v[84:87], v[158:161], v[210:213], v[84:87]
	v_mfma_f32_16x16x32_bf16 v[80:83], v[166:169], v[210:213], v[80:83]
	v_mfma_f32_16x16x32_bf16 v[68:71], v[158:161], v[218:221], v[68:71]
	v_mfma_f32_16x16x32_bf16 v[64:67], v[166:169], v[218:221], v[64:67]
	v_mfma_f32_16x16x32_bf16 v[124:127], v[170:173], v[186:189], v[124:127]
	v_mfma_f32_16x16x32_bf16 v[120:123], v[178:181], v[186:189], v[120:123]
	v_mfma_f32_16x16x32_bf16 v[108:111], v[170:173], v[198:201], v[108:111]
	v_mfma_f32_16x16x32_bf16 v[104:107], v[178:181], v[198:201], v[104:107]
	v_mfma_f32_16x16x32_bf16 v[92:95], v[170:173], v[206:209], v[92:95]
	v_mfma_f32_16x16x32_bf16 v[88:91], v[178:181], v[206:209], v[88:91]
	v_mfma_f32_16x16x32_bf16 v[76:79], v[170:173], v[214:217], v[76:79]
	v_mfma_f32_16x16x32_bf16 v[72:75], v[178:181], v[214:217], v[72:75]
	v_mfma_f32_16x16x32_bf16 v[124:127], v[174:177], v[194:197], v[124:127]
	v_mfma_f32_16x16x32_bf16 v[120:123], v[182:185], v[194:197], v[120:123]
	v_mfma_f32_16x16x32_bf16 v[108:111], v[174:177], v[202:205], v[108:111]
	v_mfma_f32_16x16x32_bf16 v[104:107], v[182:185], v[202:205], v[104:107]
	v_mfma_f32_16x16x32_bf16 v[92:95], v[174:177], v[210:213], v[92:95]
	v_mfma_f32_16x16x32_bf16 v[88:91], v[182:185], v[210:213], v[88:91]
	v_mfma_f32_16x16x32_bf16 v[76:79], v[174:177], v[218:221], v[76:79]
	v_mfma_f32_16x16x32_bf16 v[72:75], v[182:185], v[218:221], v[72:75]
	s_barrier
	s_add_i32 s33, s57, s40
	v_lshl_add_u64 v[148:149], s[30:31], 0, v[132:133]
	s_mov_b32 m0, s33
	ds_read_b128 v[186:189], v155 offset:16384
	ds_read_b128 v[194:197], v155 offset:17408
	ds_read_b128 v[198:201], v155 offset:18432
	ds_read_b128 v[202:205], v155 offset:19456
	ds_read_b128 v[206:209], v155 offset:20480
	ds_read_b128 v[210:213], v155 offset:21504
	ds_read_b128 v[214:217], v155 offset:22528
	ds_read_b128 v[218:221], v155 offset:23552
	global_load_lds_dwordx4 v[148:149], off
	s_add_i32 m0, s33, 0x2000
	s_add_u32 s54, s30, 0x80000
	v_lshl_add_u64 v[190:191], s[30:31], 0, v[128:129]
	s_addc_u32 s55, s31, 0
	s_add_i32 s33, s58, s40
	global_load_lds_dwordx4 v[190:191], off
	v_lshl_add_u64 v[222:223], s[54:55], 0, v[132:133]
	s_mov_b32 m0, s33
	v_lshl_add_u64 v[224:225], s[34:35], 0, v[130:131]
	global_load_lds_dwordx4 v[222:223], off
	v_lshl_add_u64 v[222:223], s[54:55], 0, v[128:129]
	s_add_i32 m0, s33, 0x2000
	s_nop 0
	global_load_lds_dwordx4 v[222:223], off
	v_lshl_add_u64 v[222:223], s[34:35], 0, v[134:135]
	s_mov_b32 m0, s42
	s_nop 0
	global_load_lds_dwordx4 v[222:223], off
	s_mov_b32 m0, s43
	s_nop 0
	global_load_lds_dwordx4 v[224:225], off
	s_waitcnt vmcnt(8)
	s_waitcnt lgkmcnt(0)
	s_barrier
	s_waitcnt lgkmcnt(0)
	v_mfma_f32_16x16x32_bf16 v[52:55], v[144:147], v[186:189], v[52:55]
	v_mfma_f32_16x16x32_bf16 v[48:51], v[162:165], v[186:189], v[48:51]
	v_mfma_f32_16x16x32_bf16 v[36:39], v[144:147], v[198:201], v[36:39]
	v_mfma_f32_16x16x32_bf16 v[32:35], v[162:165], v[198:201], v[32:35]
	v_mfma_f32_16x16x32_bf16 v[20:23], v[144:147], v[206:209], v[20:23]
	v_mfma_f32_16x16x32_bf16 v[16:19], v[162:165], v[206:209], v[16:19]
	v_mfma_f32_16x16x32_bf16 v[4:7], v[144:147], v[214:217], v[4:7]
	v_mfma_f32_16x16x32_bf16 v[0:3], v[162:165], v[214:217], v[0:3]
	v_mfma_f32_16x16x32_bf16 v[52:55], v[158:161], v[194:197], v[52:55]
	v_mfma_f32_16x16x32_bf16 v[48:51], v[166:169], v[194:197], v[48:51]
	v_mfma_f32_16x16x32_bf16 v[36:39], v[158:161], v[202:205], v[36:39]
	v_mfma_f32_16x16x32_bf16 v[32:35], v[166:169], v[202:205], v[32:35]
	v_mfma_f32_16x16x32_bf16 v[20:23], v[158:161], v[210:213], v[20:23]
	v_mfma_f32_16x16x32_bf16 v[16:19], v[166:169], v[210:213], v[16:19]
	v_mfma_f32_16x16x32_bf16 v[4:7], v[158:161], v[218:221], v[4:7]
	v_mfma_f32_16x16x32_bf16 v[0:3], v[166:169], v[218:221], v[0:3]
	v_mfma_f32_16x16x32_bf16 v[60:63], v[170:173], v[186:189], v[60:63]
	v_mfma_f32_16x16x32_bf16 v[56:59], v[178:181], v[186:189], v[56:59]
	v_mfma_f32_16x16x32_bf16 v[44:47], v[170:173], v[198:201], v[44:47]
	v_mfma_f32_16x16x32_bf16 v[40:43], v[178:181], v[198:201], v[40:43]
	v_mfma_f32_16x16x32_bf16 v[28:31], v[170:173], v[206:209], v[28:31]
	v_mfma_f32_16x16x32_bf16 v[24:27], v[178:181], v[206:209], v[24:27]
	v_mfma_f32_16x16x32_bf16 v[12:15], v[170:173], v[214:217], v[12:15]
	v_mfma_f32_16x16x32_bf16 v[8:11], v[178:181], v[214:217], v[8:11]
	v_mfma_f32_16x16x32_bf16 v[60:63], v[174:177], v[194:197], v[60:63]
	v_mfma_f32_16x16x32_bf16 v[56:59], v[182:185], v[194:197], v[56:59]
	v_mfma_f32_16x16x32_bf16 v[44:47], v[174:177], v[202:205], v[44:47]
	v_mfma_f32_16x16x32_bf16 v[40:43], v[182:185], v[202:205], v[40:43]
	v_mfma_f32_16x16x32_bf16 v[28:31], v[174:177], v[210:213], v[28:31]
	v_mfma_f32_16x16x32_bf16 v[24:27], v[182:185], v[210:213], v[24:27]
	v_mfma_f32_16x16x32_bf16 v[12:15], v[174:177], v[218:221], v[12:15]
	v_mfma_f32_16x16x32_bf16 v[8:11], v[182:185], v[218:221], v[8:11]
	s_barrier
	s_add_i32 s33, 0, 0x18000
	s_add_i32 s54, 0, 0x1c000
	v_add_u32_e32 v166, s33, v151
	v_add_u32_e32 v182, s54, v151
	ds_read_b128 v[144:147], v166
	ds_read_b128 v[158:161], v166 offset:1024
	ds_read_b128 v[162:165], v166 offset:2048
	ds_read_b128 v[166:169], v166 offset:3072
	ds_read_b128 v[170:173], v182
	ds_read_b128 v[174:177], v182 offset:1024
	ds_read_b128 v[178:181], v182 offset:2048
	ds_read_b128 v[182:185], v182 offset:3072
	s_add_u32 s34, s34, 0x80000
	s_addc_u32 s35, s35, 0
	s_mov_b32 m0, s48
	v_lshl_add_u64 v[226:227], s[34:35], 0, v[134:135]
	ds_read_b128 v[186:189], v155 offset:32768
	ds_read_b128 v[194:197], v155 offset:33792
	ds_read_b128 v[198:201], v155 offset:34816
	ds_read_b128 v[202:205], v155 offset:35840
	ds_read_b128 v[206:209], v155 offset:36864
	ds_read_b128 v[210:213], v155 offset:37888
	ds_read_b128 v[214:217], v155 offset:38912
	ds_read_b128 v[218:221], v155 offset:39936
	global_load_lds_dwordx4 v[226:227], off
	v_lshl_add_u64 v[226:227], s[34:35], 0, v[130:131]
	s_mov_b32 m0, s49
	s_nop 0
	global_load_lds_dwordx4 v[226:227], off
	s_waitcnt vmcnt(8)
	s_waitcnt lgkmcnt(0)
	s_barrier
	s_waitcnt lgkmcnt(0)
	v_mfma_f32_16x16x32_bf16 v[116:119], v[144:147], v[186:189], v[116:119]
	v_mfma_f32_16x16x32_bf16 v[112:115], v[162:165], v[186:189], v[112:115]
	v_mfma_f32_16x16x32_bf16 v[100:103], v[144:147], v[198:201], v[100:103]
	v_mfma_f32_16x16x32_bf16 v[96:99], v[162:165], v[198:201], v[96:99]
	v_mfma_f32_16x16x32_bf16 v[84:87], v[144:147], v[206:209], v[84:87]
	v_mfma_f32_16x16x32_bf16 v[80:83], v[162:165], v[206:209], v[80:83]
	v_mfma_f32_16x16x32_bf16 v[68:71], v[144:147], v[214:217], v[68:71]
	v_mfma_f32_16x16x32_bf16 v[64:67], v[162:165], v[214:217], v[64:67]
	v_mfma_f32_16x16x32_bf16 v[116:119], v[158:161], v[194:197], v[116:119]
	v_mfma_f32_16x16x32_bf16 v[112:115], v[166:169], v[194:197], v[112:115]
	v_mfma_f32_16x16x32_bf16 v[100:103], v[158:161], v[202:205], v[100:103]
	v_mfma_f32_16x16x32_bf16 v[96:99], v[166:169], v[202:205], v[96:99]
	v_mfma_f32_16x16x32_bf16 v[84:87], v[158:161], v[210:213], v[84:87]
	v_mfma_f32_16x16x32_bf16 v[80:83], v[166:169], v[210:213], v[80:83]
	v_mfma_f32_16x16x32_bf16 v[68:71], v[158:161], v[218:221], v[68:71]
	v_mfma_f32_16x16x32_bf16 v[64:67], v[166:169], v[218:221], v[64:67]
	v_mfma_f32_16x16x32_bf16 v[124:127], v[170:173], v[186:189], v[124:127]
	v_mfma_f32_16x16x32_bf16 v[120:123], v[178:181], v[186:189], v[120:123]
	v_mfma_f32_16x16x32_bf16 v[108:111], v[170:173], v[198:201], v[108:111]
	v_mfma_f32_16x16x32_bf16 v[104:107], v[178:181], v[198:201], v[104:107]
	v_mfma_f32_16x16x32_bf16 v[92:95], v[170:173], v[206:209], v[92:95]
	v_mfma_f32_16x16x32_bf16 v[88:91], v[178:181], v[206:209], v[88:91]
	v_mfma_f32_16x16x32_bf16 v[76:79], v[170:173], v[214:217], v[76:79]
	v_mfma_f32_16x16x32_bf16 v[72:75], v[178:181], v[214:217], v[72:75]
	v_mfma_f32_16x16x32_bf16 v[124:127], v[174:177], v[194:197], v[124:127]
	v_mfma_f32_16x16x32_bf16 v[120:123], v[182:185], v[194:197], v[120:123]
	v_mfma_f32_16x16x32_bf16 v[108:111], v[174:177], v[202:205], v[108:111]
	v_mfma_f32_16x16x32_bf16 v[104:107], v[182:185], v[202:205], v[104:107]
	v_mfma_f32_16x16x32_bf16 v[92:95], v[174:177], v[210:213], v[92:95]
	v_mfma_f32_16x16x32_bf16 v[88:91], v[182:185], v[210:213], v[88:91]
	v_mfma_f32_16x16x32_bf16 v[76:79], v[174:177], v[218:221], v[76:79]
	v_mfma_f32_16x16x32_bf16 v[72:75], v[182:185], v[218:221], v[72:75]
	s_barrier
	s_add_i32 s33, s33, s40
	v_lshl_add_u64 v[148:149], v[148:149], 0, s[16:17]
	s_mov_b32 m0, s33
	ds_read_b128 v[186:189], v155 offset:49152
	ds_read_b128 v[194:197], v155 offset:50176
	ds_read_b128 v[198:201], v155 offset:51200
	ds_read_b128 v[202:205], v155 offset:52224
	ds_read_b128 v[206:209], v155 offset:53248
	ds_read_b128 v[210:213], v155 offset:54272
	ds_read_b128 v[214:217], v155 offset:55296
	ds_read_b128 v[218:221], v155 offset:56320
	global_load_lds_dwordx4 v[148:149], off
	s_add_i32 m0, s33, 0x2000
	s_add_u32 s30, s30, 0x80080
	v_lshl_add_u64 v[148:149], v[190:191], 0, s[16:17]
	s_addc_u32 s31, s31, 0
	s_add_i32 s33, s54, s40
	global_load_lds_dwordx4 v[148:149], off
	v_lshl_add_u64 v[148:149], s[30:31], 0, v[132:133]
	s_mov_b32 m0, s33
	s_nop 0
	global_load_lds_dwordx4 v[148:149], off
	v_lshl_add_u64 v[148:149], s[30:31], 0, v[128:129]
	s_add_i32 m0, s33, 0x2000
	s_nop 0
	global_load_lds_dwordx4 v[148:149], off
	v_lshl_add_u64 v[148:149], v[222:223], 0, s[16:17]
	s_mov_b32 m0, s51
	s_nop 0
	global_load_lds_dwordx4 v[148:149], off
	v_lshl_add_u64 v[148:149], v[224:225], 0, s[16:17]
	s_mov_b32 m0, s56
	s_nop 0
	global_load_lds_dwordx4 v[148:149], off
	s_waitcnt vmcnt(8)
	s_waitcnt lgkmcnt(0)
	s_barrier
	s_waitcnt lgkmcnt(0)
	v_mfma_f32_16x16x32_bf16 v[52:55], v[144:147], v[186:189], v[52:55]
	v_mfma_f32_16x16x32_bf16 v[48:51], v[162:165], v[186:189], v[48:51]
	v_mfma_f32_16x16x32_bf16 v[36:39], v[144:147], v[198:201], v[36:39]
	v_mfma_f32_16x16x32_bf16 v[32:35], v[162:165], v[198:201], v[32:35]
	v_mfma_f32_16x16x32_bf16 v[20:23], v[144:147], v[206:209], v[20:23]
	v_mfma_f32_16x16x32_bf16 v[16:19], v[162:165], v[206:209], v[16:19]
	v_mfma_f32_16x16x32_bf16 v[4:7], v[144:147], v[214:217], v[4:7]
	v_mfma_f32_16x16x32_bf16 v[0:3], v[162:165], v[214:217], v[0:3]
	v_mfma_f32_16x16x32_bf16 v[52:55], v[158:161], v[194:197], v[52:55]
	v_mfma_f32_16x16x32_bf16 v[48:51], v[166:169], v[194:197], v[48:51]
	v_mfma_f32_16x16x32_bf16 v[36:39], v[158:161], v[202:205], v[36:39]
	v_mfma_f32_16x16x32_bf16 v[32:35], v[166:169], v[202:205], v[32:35]
	v_mfma_f32_16x16x32_bf16 v[20:23], v[158:161], v[210:213], v[20:23]
	v_mfma_f32_16x16x32_bf16 v[16:19], v[166:169], v[210:213], v[16:19]
	v_mfma_f32_16x16x32_bf16 v[4:7], v[158:161], v[218:221], v[4:7]
	v_mfma_f32_16x16x32_bf16 v[0:3], v[166:169], v[218:221], v[0:3]
	v_mfma_f32_16x16x32_bf16 v[60:63], v[170:173], v[186:189], v[60:63]
	v_mfma_f32_16x16x32_bf16 v[56:59], v[178:181], v[186:189], v[56:59]
	v_mfma_f32_16x16x32_bf16 v[44:47], v[170:173], v[198:201], v[44:47]
	v_mfma_f32_16x16x32_bf16 v[40:43], v[178:181], v[198:201], v[40:43]
	v_mfma_f32_16x16x32_bf16 v[28:31], v[170:173], v[206:209], v[28:31]
	v_mfma_f32_16x16x32_bf16 v[24:27], v[178:181], v[206:209], v[24:27]
	v_mfma_f32_16x16x32_bf16 v[12:15], v[170:173], v[214:217], v[12:15]
	v_mfma_f32_16x16x32_bf16 v[8:11], v[178:181], v[214:217], v[8:11]
	v_mfma_f32_16x16x32_bf16 v[60:63], v[174:177], v[194:197], v[60:63]
	v_mfma_f32_16x16x32_bf16 v[56:59], v[182:185], v[194:197], v[56:59]
	v_mfma_f32_16x16x32_bf16 v[44:47], v[174:177], v[202:205], v[44:47]
	v_mfma_f32_16x16x32_bf16 v[40:43], v[182:185], v[202:205], v[40:43]
	v_mfma_f32_16x16x32_bf16 v[28:31], v[174:177], v[210:213], v[28:31]
	v_mfma_f32_16x16x32_bf16 v[24:27], v[182:185], v[210:213], v[24:27]
	v_mfma_f32_16x16x32_bf16 v[12:15], v[174:177], v[218:221], v[12:15]
	v_mfma_f32_16x16x32_bf16 v[8:11], v[182:185], v[218:221], v[8:11]
	s_barrier
	s_add_i32 s65, s65, 2
	s_add_u32 s28, s28, 0x100
	s_addc_u32 s29, s29, 0
	s_add_u32 s63, s63, 0x100
	s_addc_u32 s64, s64, 0
	s_cmp_gt_u32 s65, 29
	s_cbranch_scc0 .LBB0_1504
	v_lshl_add_u32 v144, s8, 8, v150
	v_ashrrev_i32_e32 v145, 31, v144
	v_lshl_add_u64 v[148:149], v[144:145], 2, s[14:15]
	global_load_dword v172, v[148:149], off
	global_load_dword v173, v[148:149], off offset:64
	global_load_dword v174, v[148:149], off offset:128
	global_load_dword v175, v[148:149], off offset:192
	global_load_dword v176, v[148:149], off offset:512
	global_load_dword v177, v[148:149], off offset:576
	global_load_dword v178, v[148:149], off offset:640
	global_load_dword v179, v[148:149], off offset:704
	s_and_b64 vcc, exec, s[18:19]
	s_cbranch_vccz .LBB0_1507
	s_barrier

.LBB0_2011:
	ds_read_b128 v[144:147], v153
	ds_read_b128 v[158:161], v153 offset:1024
	ds_read_b128 v[162:165], v153 offset:2048
	ds_read_b128 v[166:169], v153 offset:3072
	ds_read_b128 v[170:173], v154
	ds_read_b128 v[174:177], v154 offset:1024
	ds_read_b128 v[178:181], v154 offset:2048
	ds_read_b128 v[182:185], v154 offset:3072
	s_add_u32 s36, s34, 0x100
	s_addc_u32 s37, s35, 0
	s_cmpk_eq_i32 s68, 0x54
	s_cselect_b32 s41, s11, s37
	s_cselect_b32 s40, s10, s36
	s_cselect_b32 s39, s31, s67
	s_cselect_b32 s38, s30, s66
	v_lshl_add_u64 v[148:149], s[34:35], 0, v[136:137]
	s_add_i32 m0, s51, 0xc000
	ds_read_b128 v[186:189], v155
	ds_read_b128 v[194:197], v155 offset:1024
	ds_read_b128 v[198:201], v155 offset:2048
	ds_read_b128 v[202:205], v155 offset:3072
	ds_read_b128 v[206:209], v155 offset:4096
	ds_read_b128 v[210:213], v155 offset:5120
	ds_read_b128 v[214:217], v155 offset:6144
	ds_read_b128 v[218:221], v155 offset:7168
	global_load_lds_dwordx4 v[148:149], off
	v_lshl_add_u64 v[148:149], s[34:35], 0, v[138:139]
	s_add_i32 m0, s51, 0xe000
	s_nop 0
	global_load_lds_dwordx4 v[148:149], off
	s_waitcnt vmcnt(8)
	s_waitcnt lgkmcnt(0)
	s_barrier
	s_waitcnt lgkmcnt(0)
	v_mfma_f32_16x16x32_bf16 v[124:127], v[144:147], v[186:189], v[124:127]
	v_mfma_f32_16x16x32_bf16 v[120:123], v[162:165], v[186:189], v[120:123]
	v_mfma_f32_16x16x32_bf16 v[108:111], v[144:147], v[198:201], v[108:111]
	v_mfma_f32_16x16x32_bf16 v[104:107], v[162:165], v[198:201], v[104:107]
	v_mfma_f32_16x16x32_bf16 v[92:95], v[144:147], v[206:209], v[92:95]
	v_mfma_f32_16x16x32_bf16 v[88:91], v[162:165], v[206:209], v[88:91]
	v_mfma_f32_16x16x32_bf16 v[76:79], v[144:147], v[214:217], v[76:79]
	v_mfma_f32_16x16x32_bf16 v[72:75], v[162:165], v[214:217], v[72:75]
	v_mfma_f32_16x16x32_bf16 v[124:127], v[158:161], v[194:197], v[124:127]
	v_mfma_f32_16x16x32_bf16 v[120:123], v[166:169], v[194:197], v[120:123]
	v_mfma_f32_16x16x32_bf16 v[108:111], v[158:161], v[202:205], v[108:111]
	v_mfma_f32_16x16x32_bf16 v[104:107], v[166:169], v[202:205], v[104:107]
	v_mfma_f32_16x16x32_bf16 v[92:95], v[158:161], v[210:213], v[92:95]
	v_mfma_f32_16x16x32_bf16 v[88:91], v[166:169], v[210:213], v[88:91]
	v_mfma_f32_16x16x32_bf16 v[76:79], v[158:161], v[218:221], v[76:79]
	v_mfma_f32_16x16x32_bf16 v[72:75], v[166:169], v[218:221], v[72:75]
	v_mfma_f32_16x16x32_bf16 v[116:119], v[170:173], v[186:189], v[116:119]
	v_mfma_f32_16x16x32_bf16 v[112:115], v[178:181], v[186:189], v[112:115]
	v_mfma_f32_16x16x32_bf16 v[100:103], v[170:173], v[198:201], v[100:103]
	v_mfma_f32_16x16x32_bf16 v[96:99], v[178:181], v[198:201], v[96:99]
	v_mfma_f32_16x16x32_bf16 v[84:87], v[170:173], v[206:209], v[84:87]
	v_mfma_f32_16x16x32_bf16 v[80:83], v[178:181], v[206:209], v[80:83]
	v_mfma_f32_16x16x32_bf16 v[68:71], v[170:173], v[214:217], v[68:71]
	v_mfma_f32_16x16x32_bf16 v[64:67], v[178:181], v[214:217], v[64:67]
	v_mfma_f32_16x16x32_bf16 v[116:119], v[174:177], v[194:197], v[116:119]
	v_mfma_f32_16x16x32_bf16 v[112:115], v[182:185], v[194:197], v[112:115]
	v_mfma_f32_16x16x32_bf16 v[100:103], v[174:177], v[202:205], v[100:103]
	v_mfma_f32_16x16x32_bf16 v[96:99], v[182:185], v[202:205], v[96:99]
	v_mfma_f32_16x16x32_bf16 v[84:87], v[174:177], v[210:213], v[84:87]
	v_mfma_f32_16x16x32_bf16 v[80:83], v[182:185], v[210:213], v[80:83]
	v_mfma_f32_16x16x32_bf16 v[68:71], v[174:177], v[218:221], v[68:71]
	v_mfma_f32_16x16x32_bf16 v[64:67], v[182:185], v[218:221], v[64:67]
	s_barrier
	s_add_i32 s33, s60, s50
	v_lshl_add_u64 v[148:149], s[38:39], 0, v[130:131]
	s_mov_b32 m0, s33
	ds_read_b128 v[186:189], v155 offset:16384
	ds_read_b128 v[194:197], v155 offset:17408
	ds_read_b128 v[198:201], v155 offset:18432
	ds_read_b128 v[202:205], v155 offset:19456
	ds_read_b128 v[206:209], v155 offset:20480
	ds_read_b128 v[210:213], v155 offset:21504
	ds_read_b128 v[214:217], v155 offset:22528
	ds_read_b128 v[218:221], v155 offset:23552
	global_load_lds_dwordx4 v[148:149], off
	s_add_i32 m0, s33, 0x2000
	s_add_u32 s34, s38, 0x160000
	v_lshl_add_u64 v[190:191], s[38:39], 0, v[134:135]
	s_addc_u32 s35, s39, 0
	s_add_i32 s33, s61, s50
	global_load_lds_dwordx4 v[190:191], off
	v_lshl_add_u64 v[222:223], s[34:35], 0, v[130:131]
	s_mov_b32 m0, s33
	v_lshl_add_u64 v[224:225], s[40:41], 0, v[132:133]
	global_load_lds_dwordx4 v[222:223], off
	v_lshl_add_u64 v[222:223], s[34:35], 0, v[134:135]
	s_add_i32 m0, s33, 0x2000
	s_nop 0
	global_load_lds_dwordx4 v[222:223], off
	v_lshl_add_u64 v[222:223], s[40:41], 0, v[128:129]
	s_mov_b32 m0, s51
	s_nop 0
	global_load_lds_dwordx4 v[222:223], off
	s_mov_b32 m0, s54
	s_nop 0
	global_load_lds_dwordx4 v[224:225], off
	s_waitcnt vmcnt(8)
	s_waitcnt lgkmcnt(0)
	s_barrier
	s_waitcnt lgkmcnt(0)
	v_mfma_f32_16x16x32_bf16 v[60:63], v[144:147], v[186:189], v[60:63]
	v_mfma_f32_16x16x32_bf16 v[56:59], v[162:165], v[186:189], v[56:59]
	v_mfma_f32_16x16x32_bf16 v[44:47], v[144:147], v[198:201], v[44:47]
	v_mfma_f32_16x16x32_bf16 v[40:43], v[162:165], v[198:201], v[40:43]
	v_mfma_f32_16x16x32_bf16 v[28:31], v[144:147], v[206:209], v[28:31]
	v_mfma_f32_16x16x32_bf16 v[24:27], v[162:165], v[206:209], v[24:27]
	v_mfma_f32_16x16x32_bf16 v[12:15], v[144:147], v[214:217], v[12:15]
	v_mfma_f32_16x16x32_bf16 v[8:11], v[162:165], v[214:217], v[8:11]
	v_mfma_f32_16x16x32_bf16 v[60:63], v[158:161], v[194:197], v[60:63]
	v_mfma_f32_16x16x32_bf16 v[56:59], v[166:169], v[194:197], v[56:59]
	v_mfma_f32_16x16x32_bf16 v[44:47], v[158:161], v[202:205], v[44:47]
	v_mfma_f32_16x16x32_bf16 v[40:43], v[166:169], v[202:205], v[40:43]
	v_mfma_f32_16x16x32_bf16 v[28:31], v[158:161], v[210:213], v[28:31]
	v_mfma_f32_16x16x32_bf16 v[24:27], v[166:169], v[210:213], v[24:27]
	v_mfma_f32_16x16x32_bf16 v[12:15], v[158:161], v[218:221], v[12:15]
	v_mfma_f32_16x16x32_bf16 v[8:11], v[166:169], v[218:221], v[8:11]
	v_mfma_f32_16x16x32_bf16 v[52:55], v[170:173], v[186:189], v[52:55]
	v_mfma_f32_16x16x32_bf16 v[48:51], v[178:181], v[186:189], v[48:51]
	v_mfma_f32_16x16x32_bf16 v[36:39], v[170:173], v[198:201], v[36:39]
	v_mfma_f32_16x16x32_bf16 v[32:35], v[178:181], v[198:201], v[32:35]
	v_mfma_f32_16x16x32_bf16 v[20:23], v[170:173], v[206:209], v[20:23]
	v_mfma_f32_16x16x32_bf16 v[16:19], v[178:181], v[206:209], v[16:19]
	v_mfma_f32_16x16x32_bf16 v[4:7], v[170:173], v[214:217], v[4:7]
	v_mfma_f32_16x16x32_bf16 v[0:3], v[178:181], v[214:217], v[0:3]
	v_mfma_f32_16x16x32_bf16 v[52:55], v[174:177], v[194:197], v[52:55]
	v_mfma_f32_16x16x32_bf16 v[48:51], v[182:185], v[194:197], v[48:51]
	v_mfma_f32_16x16x32_bf16 v[36:39], v[174:177], v[202:205], v[36:39]
	v_mfma_f32_16x16x32_bf16 v[32:35], v[182:185], v[202:205], v[32:35]
	v_mfma_f32_16x16x32_bf16 v[20:23], v[174:177], v[210:213], v[20:23]
	v_mfma_f32_16x16x32_bf16 v[16:19], v[182:185], v[210:213], v[16:19]
	v_mfma_f32_16x16x32_bf16 v[4:7], v[174:177], v[218:221], v[4:7]
	v_mfma_f32_16x16x32_bf16 v[0:3], v[182:185], v[218:221], v[0:3]
	s_barrier
	s_add_i32 s33, 0, 0x18000
	v_add_u32_e32 v157, s33, v151
	s_add_i32 s69, 0, 0x1c000
	ds_read_b128 v[144:147], v157
	ds_read_b128 v[158:161], v157 offset:1024
	ds_read_b128 v[162:165], v157 offset:2048
	ds_read_b128 v[166:169], v157 offset:3072
	v_add_u32_e32 v157, s69, v151
	ds_read_b128 v[170:173], v157
	ds_read_b128 v[174:177], v157 offset:1024
	ds_read_b128 v[178:181], v157 offset:2048
	ds_read_b128 v[182:185], v157 offset:3072
	s_add_u32 s34, s40, 0x160000
	s_addc_u32 s35, s41, 0
	s_mov_b32 m0, s55
	v_lshl_add_u64 v[226:227], s[34:35], 0, v[128:129]
	ds_read_b128 v[186:189], v155 offset:32768
	ds_read_b128 v[194:197], v155 offset:33792
	ds_read_b128 v[198:201], v155 offset:34816
	ds_read_b128 v[202:205], v155 offset:35840
	ds_read_b128 v[206:209], v155 offset:36864
	ds_read_b128 v[210:213], v155 offset:37888
	ds_read_b128 v[214:217], v155 offset:38912
	ds_read_b128 v[218:221], v155 offset:39936
	global_load_lds_dwordx4 v[226:227], off
	v_lshl_add_u64 v[226:227], s[34:35], 0, v[132:133]
	s_mov_b32 m0, s56
	s_nop 0
	global_load_lds_dwordx4 v[226:227], off
	s_waitcnt vmcnt(8)
	s_waitcnt lgkmcnt(0)
	s_barrier
	s_waitcnt lgkmcnt(0)
	v_mfma_f32_16x16x32_bf16 v[124:127], v[144:147], v[186:189], v[124:127]
	v_mfma_f32_16x16x32_bf16 v[120:123], v[162:165], v[186:189], v[120:123]
	v_mfma_f32_16x16x32_bf16 v[108:111], v[144:147], v[198:201], v[108:111]
	v_mfma_f32_16x16x32_bf16 v[104:107], v[162:165], v[198:201], v[104:107]
	v_mfma_f32_16x16x32_bf16 v[92:95], v[144:147], v[206:209], v[92:95]
	v_mfma_f32_16x16x32_bf16 v[88:91], v[162:165], v[206:209], v[88:91]
	v_mfma_f32_16x16x32_bf16 v[76:79], v[144:147], v[214:217], v[76:79]
	v_mfma_f32_16x16x32_bf16 v[72:75], v[162:165], v[214:217], v[72:75]
	v_mfma_f32_16x16x32_bf16 v[124:127], v[158:161], v[194:197], v[124:127]
	v_mfma_f32_16x16x32_bf16 v[120:123], v[166:169], v[194:197], v[120:123]
	v_mfma_f32_16x16x32_bf16 v[108:111], v[158:161], v[202:205], v[108:111]
	v_mfma_f32_16x16x32_bf16 v[104:107], v[166:169], v[202:205], v[104:107]
	v_mfma_f32_16x16x32_bf16 v[92:95], v[158:161], v[210:213], v[92:95]
	v_mfma_f32_16x16x32_bf16 v[88:91], v[166:169], v[210:213], v[88:91]
	v_mfma_f32_16x16x32_bf16 v[76:79], v[158:161], v[218:221], v[76:79]
	v_mfma_f32_16x16x32_bf16 v[72:75], v[166:169], v[218:221], v[72:75]
	v_mfma_f32_16x16x32_bf16 v[116:119], v[170:173], v[186:189], v[116:119]
	v_mfma_f32_16x16x32_bf16 v[112:115], v[178:181], v[186:189], v[112:115]
	v_mfma_f32_16x16x32_bf16 v[100:103], v[170:173], v[198:201], v[100:103]
	v_mfma_f32_16x16x32_bf16 v[96:99], v[178:181], v[198:201], v[96:99]
	v_mfma_f32_16x16x32_bf16 v[84:87], v[170:173], v[206:209], v[84:87]
	v_mfma_f32_16x16x32_bf16 v[80:83], v[178:181], v[206:209], v[80:83]
	v_mfma_f32_16x16x32_bf16 v[68:71], v[170:173], v[214:217], v[68:71]
	v_mfma_f32_16x16x32_bf16 v[64:67], v[178:181], v[214:217], v[64:67]
	v_mfma_f32_16x16x32_bf16 v[116:119], v[174:177], v[194:197], v[116:119]
	v_mfma_f32_16x16x32_bf16 v[112:115], v[182:185], v[194:197], v[112:115]
	v_mfma_f32_16x16x32_bf16 v[100:103], v[174:177], v[202:205], v[100:103]
	v_mfma_f32_16x16x32_bf16 v[96:99], v[182:185], v[202:205], v[96:99]
	v_mfma_f32_16x16x32_bf16 v[84:87], v[174:177], v[210:213], v[84:87]
	v_mfma_f32_16x16x32_bf16 v[80:83], v[182:185], v[210:213], v[80:83]
	v_mfma_f32_16x16x32_bf16 v[68:71], v[174:177], v[218:221], v[68:71]
	v_mfma_f32_16x16x32_bf16 v[64:67], v[182:185], v[218:221], v[64:67]
	s_barrier
	s_add_i32 s33, s33, s50
	v_lshl_add_u64 v[148:149], v[148:149], 0, s[18:19]
	s_mov_b32 m0, s33
	ds_read_b128 v[186:189], v155 offset:49152
	ds_read_b128 v[194:197], v155 offset:50176
	ds_read_b128 v[198:201], v155 offset:51200
	ds_read_b128 v[202:205], v155 offset:52224
	ds_read_b128 v[206:209], v155 offset:53248
	ds_read_b128 v[210:213], v155 offset:54272
	ds_read_b128 v[214:217], v155 offset:55296
	ds_read_b128 v[218:221], v155 offset:56320
	global_load_lds_dwordx4 v[148:149], off
	s_add_i32 m0, s33, 0x2000
	s_add_u32 s34, s38, 0x160080
	v_lshl_add_u64 v[148:149], v[190:191], 0, s[18:19]
	s_addc_u32 s35, s39, 0
	s_add_i32 s33, s69, s50
	global_load_lds_dwordx4 v[148:149], off
	v_lshl_add_u64 v[148:149], s[34:35], 0, v[130:131]
	s_mov_b32 m0, s33
	s_nop 0
	global_load_lds_dwordx4 v[148:149], off
	v_lshl_add_u64 v[148:149], s[34:35], 0, v[134:135]
	s_add_i32 m0, s33, 0x2000
	s_nop 0
	global_load_lds_dwordx4 v[148:149], off
	v_lshl_add_u64 v[148:149], v[222:223], 0, s[18:19]
	s_mov_b32 m0, s58
	s_nop 0
	global_load_lds_dwordx4 v[148:149], off
	v_lshl_add_u64 v[148:149], v[224:225], 0, s[18:19]
	s_mov_b32 m0, s59
	s_nop 0
	global_load_lds_dwordx4 v[148:149], off
	s_waitcnt vmcnt(8)
	s_waitcnt lgkmcnt(0)
	s_barrier
	s_waitcnt lgkmcnt(0)
	v_mfma_f32_16x16x32_bf16 v[60:63], v[144:147], v[186:189], v[60:63]
	v_mfma_f32_16x16x32_bf16 v[56:59], v[162:165], v[186:189], v[56:59]
	v_mfma_f32_16x16x32_bf16 v[44:47], v[144:147], v[198:201], v[44:47]
	v_mfma_f32_16x16x32_bf16 v[40:43], v[162:165], v[198:201], v[40:43]
	v_mfma_f32_16x16x32_bf16 v[28:31], v[144:147], v[206:209], v[28:31]
	v_mfma_f32_16x16x32_bf16 v[24:27], v[162:165], v[206:209], v[24:27]
	v_mfma_f32_16x16x32_bf16 v[12:15], v[144:147], v[214:217], v[12:15]
	v_mfma_f32_16x16x32_bf16 v[8:11], v[162:165], v[214:217], v[8:11]
	v_mfma_f32_16x16x32_bf16 v[60:63], v[158:161], v[194:197], v[60:63]
	v_mfma_f32_16x16x32_bf16 v[56:59], v[166:169], v[194:197], v[56:59]
	v_mfma_f32_16x16x32_bf16 v[44:47], v[158:161], v[202:205], v[44:47]
	v_mfma_f32_16x16x32_bf16 v[40:43], v[166:169], v[202:205], v[40:43]
	v_mfma_f32_16x16x32_bf16 v[28:31], v[158:161], v[210:213], v[28:31]
	v_mfma_f32_16x16x32_bf16 v[24:27], v[166:169], v[210:213], v[24:27]
	v_mfma_f32_16x16x32_bf16 v[12:15], v[158:161], v[218:221], v[12:15]
	v_mfma_f32_16x16x32_bf16 v[8:11], v[166:169], v[218:221], v[8:11]
	v_mfma_f32_16x16x32_bf16 v[52:55], v[170:173], v[186:189], v[52:55]
	v_mfma_f32_16x16x32_bf16 v[48:51], v[178:181], v[186:189], v[48:51]
	v_mfma_f32_16x16x32_bf16 v[36:39], v[170:173], v[198:201], v[36:39]
	v_mfma_f32_16x16x32_bf16 v[32:35], v[178:181], v[198:201], v[32:35]
	v_mfma_f32_16x16x32_bf16 v[20:23], v[170:173], v[206:209], v[20:23]
	v_mfma_f32_16x16x32_bf16 v[16:19], v[178:181], v[206:209], v[16:19]
	v_mfma_f32_16x16x32_bf16 v[4:7], v[170:173], v[214:217], v[4:7]
	v_mfma_f32_16x16x32_bf16 v[0:3], v[178:181], v[214:217], v[0:3]
	v_mfma_f32_16x16x32_bf16 v[52:55], v[174:177], v[194:197], v[52:55]
	v_mfma_f32_16x16x32_bf16 v[48:51], v[182:185], v[194:197], v[48:51]
	v_mfma_f32_16x16x32_bf16 v[36:39], v[174:177], v[202:205], v[36:39]
	v_mfma_f32_16x16x32_bf16 v[32:35], v[182:185], v[202:205], v[32:35]
	v_mfma_f32_16x16x32_bf16 v[20:23], v[174:177], v[210:213], v[20:23]
	v_mfma_f32_16x16x32_bf16 v[16:19], v[182:185], v[210:213], v[16:19]
	v_mfma_f32_16x16x32_bf16 v[4:7], v[174:177], v[218:221], v[4:7]
	v_mfma_f32_16x16x32_bf16 v[0:3], v[182:185], v[218:221], v[0:3]
	s_barrier
	s_add_i32 s68, s68, 2
	s_add_u32 s66, s66, 0x100
	s_addc_u32 s67, s67, 0
	s_cmpk_gt_u32 s68, 0x55
	s_mov_b64 s[34:35], s[36:37]
	s_cbranch_scc0 .LBB0_2011
	s_and_b64 vcc, exec, s[20:21]
	s_cbranch_vccz .LBB0_2014
	s_barrier

.LBB0_2113:
	v_add_u32_e32 v151, s48, v149
	ds_read_b128 v[152:155], v151
	ds_read_b128 v[156:159], v151 offset:1024
	ds_read_b128 v[160:163], v151 offset:2048
	ds_read_b128 v[164:167], v151 offset:3072
	v_add_u32_e32 v151, s49, v149
	s_add_u32 s28, s24, s26
	ds_read_b128 v[168:171], v151
	ds_read_b128 v[172:175], v151 offset:1024
	ds_read_b128 v[176:179], v151 offset:2048
	ds_read_b128 v[180:183], v151 offset:3072
	s_addc_u32 s29, s25, s27
	s_add_u32 s28, s28, 0x100
	s_addc_u32 s29, s29, 0
	s_add_u32 s55, s21, s26
	s_addc_u32 s56, s53, s27
	s_cmpk_eq_i32 s26, 0x2b00
	s_cselect_b32 s31, s5, s29
	s_cselect_b32 s30, s4, s28
	s_cselect_b32 s29, s23, s56
	s_cselect_b32 s28, s22, s55
	v_lshl_add_u64 v[218:219], v[144:145], 0, s[26:27]
	s_add_i32 m0, s39, 0xc000
	ds_read_b128 v[184:187], v150
	ds_read_b128 v[188:191], v150 offset:1024
	ds_read_b128 v[194:197], v150 offset:2048
	ds_read_b128 v[198:201], v150 offset:3072
	ds_read_b128 v[202:205], v150 offset:4096
	ds_read_b128 v[206:209], v150 offset:5120
	ds_read_b128 v[210:213], v150 offset:6144
	ds_read_b128 v[214:217], v150 offset:7168
	global_load_lds_dwordx4 v[218:219], off
	v_lshl_add_u64 v[218:219], v[146:147], 0, s[26:27]
	s_add_i32 m0, s39, 0xe000
	s_nop 0
	global_load_lds_dwordx4 v[218:219], off
	s_waitcnt vmcnt(8)
	s_waitcnt lgkmcnt(0)
	s_barrier
	s_waitcnt lgkmcnt(0)
	v_mfma_f32_16x16x32_bf16 v[124:127], v[152:155], v[184:187], v[124:127]
	v_mfma_f32_16x16x32_bf16 v[120:123], v[160:163], v[184:187], v[120:123]
	v_mfma_f32_16x16x32_bf16 v[108:111], v[152:155], v[194:197], v[108:111]
	v_mfma_f32_16x16x32_bf16 v[104:107], v[160:163], v[194:197], v[104:107]
	v_mfma_f32_16x16x32_bf16 v[92:95], v[152:155], v[202:205], v[92:95]
	v_mfma_f32_16x16x32_bf16 v[88:91], v[160:163], v[202:205], v[88:91]
	v_mfma_f32_16x16x32_bf16 v[76:79], v[152:155], v[210:213], v[76:79]
	v_mfma_f32_16x16x32_bf16 v[72:75], v[160:163], v[210:213], v[72:75]
	v_mfma_f32_16x16x32_bf16 v[124:127], v[156:159], v[188:191], v[124:127]
	v_mfma_f32_16x16x32_bf16 v[120:123], v[164:167], v[188:191], v[120:123]
	v_mfma_f32_16x16x32_bf16 v[108:111], v[156:159], v[198:201], v[108:111]
	v_mfma_f32_16x16x32_bf16 v[104:107], v[164:167], v[198:201], v[104:107]
	v_mfma_f32_16x16x32_bf16 v[92:95], v[156:159], v[206:209], v[92:95]
	v_mfma_f32_16x16x32_bf16 v[88:91], v[164:167], v[206:209], v[88:91]
	v_mfma_f32_16x16x32_bf16 v[76:79], v[156:159], v[214:217], v[76:79]
	v_mfma_f32_16x16x32_bf16 v[72:75], v[164:167], v[214:217], v[72:75]
	v_mfma_f32_16x16x32_bf16 v[116:119], v[168:171], v[184:187], v[116:119]
	v_mfma_f32_16x16x32_bf16 v[112:115], v[176:179], v[184:187], v[112:115]
	v_mfma_f32_16x16x32_bf16 v[100:103], v[168:171], v[194:197], v[100:103]
	v_mfma_f32_16x16x32_bf16 v[96:99], v[176:179], v[194:197], v[96:99]
	v_mfma_f32_16x16x32_bf16 v[84:87], v[168:171], v[202:205], v[84:87]
	v_mfma_f32_16x16x32_bf16 v[80:83], v[176:179], v[202:205], v[80:83]
	v_mfma_f32_16x16x32_bf16 v[68:71], v[168:171], v[210:213], v[68:71]
	v_mfma_f32_16x16x32_bf16 v[64:67], v[176:179], v[210:213], v[64:67]
	v_mfma_f32_16x16x32_bf16 v[116:119], v[172:175], v[188:191], v[116:119]
	v_mfma_f32_16x16x32_bf16 v[112:115], v[180:183], v[188:191], v[112:115]
	v_mfma_f32_16x16x32_bf16 v[100:103], v[172:175], v[198:201], v[100:103]
	v_mfma_f32_16x16x32_bf16 v[96:99], v[180:183], v[198:201], v[96:99]
	v_mfma_f32_16x16x32_bf16 v[84:87], v[172:175], v[206:209], v[84:87]
	v_mfma_f32_16x16x32_bf16 v[80:83], v[180:183], v[206:209], v[80:83]
	v_mfma_f32_16x16x32_bf16 v[68:71], v[172:175], v[214:217], v[68:71]
	v_mfma_f32_16x16x32_bf16 v[64:67], v[180:183], v[214:217], v[64:67]
	s_barrier
	s_add_i32 s55, s48, s38
	v_lshl_add_u64 v[218:219], s[28:29], 0, v[130:131]
	s_mov_b32 m0, s55
	ds_read_b128 v[184:187], v150 offset:16384
	ds_read_b128 v[188:191], v150 offset:17408
	ds_read_b128 v[194:197], v150 offset:18432
	ds_read_b128 v[198:201], v150 offset:19456
	ds_read_b128 v[202:205], v150 offset:20480
	ds_read_b128 v[206:209], v150 offset:21504
	ds_read_b128 v[210:213], v150 offset:22528
	ds_read_b128 v[214:217], v150 offset:23552
	global_load_lds_dwordx4 v[218:219], off
	s_add_i32 m0, s55, 0x2000
	s_add_u32 s56, s28, 0x160000
	v_lshl_add_u64 v[220:221], s[28:29], 0, v[134:135]
	s_addc_u32 s57, s29, 0
	s_add_i32 s55, s49, s38
	global_load_lds_dwordx4 v[220:221], off
	v_lshl_add_u64 v[222:223], s[56:57], 0, v[130:131]
	s_mov_b32 m0, s55
	v_lshl_add_u64 v[224:225], s[30:31], 0, v[132:133]
	global_load_lds_dwordx4 v[222:223], off
	v_lshl_add_u64 v[222:223], s[56:57], 0, v[134:135]
	s_add_i32 m0, s55, 0x2000
	s_nop 0
	global_load_lds_dwordx4 v[222:223], off
	v_lshl_add_u64 v[222:223], s[30:31], 0, v[128:129]
	s_mov_b32 m0, s39
	s_nop 0
	global_load_lds_dwordx4 v[222:223], off
	s_mov_b32 m0, s40
	s_nop 0
	global_load_lds_dwordx4 v[224:225], off
	s_waitcnt vmcnt(8)
	s_waitcnt lgkmcnt(0)
	s_barrier
	s_waitcnt lgkmcnt(0)
	v_mfma_f32_16x16x32_bf16 v[60:63], v[152:155], v[184:187], v[60:63]
	v_mfma_f32_16x16x32_bf16 v[56:59], v[160:163], v[184:187], v[56:59]
	v_mfma_f32_16x16x32_bf16 v[44:47], v[152:155], v[194:197], v[44:47]
	v_mfma_f32_16x16x32_bf16 v[40:43], v[160:163], v[194:197], v[40:43]
	v_mfma_f32_16x16x32_bf16 v[28:31], v[152:155], v[202:205], v[28:31]
	v_mfma_f32_16x16x32_bf16 v[24:27], v[160:163], v[202:205], v[24:27]
	v_mfma_f32_16x16x32_bf16 v[12:15], v[152:155], v[210:213], v[12:15]
	v_mfma_f32_16x16x32_bf16 v[8:11], v[160:163], v[210:213], v[8:11]
	v_mfma_f32_16x16x32_bf16 v[60:63], v[156:159], v[188:191], v[60:63]
	v_mfma_f32_16x16x32_bf16 v[56:59], v[164:167], v[188:191], v[56:59]
	v_mfma_f32_16x16x32_bf16 v[44:47], v[156:159], v[198:201], v[44:47]
	v_mfma_f32_16x16x32_bf16 v[40:43], v[164:167], v[198:201], v[40:43]
	v_mfma_f32_16x16x32_bf16 v[28:31], v[156:159], v[206:209], v[28:31]
	v_mfma_f32_16x16x32_bf16 v[24:27], v[164:167], v[206:209], v[24:27]
	v_mfma_f32_16x16x32_bf16 v[12:15], v[156:159], v[214:217], v[12:15]
	v_mfma_f32_16x16x32_bf16 v[8:11], v[164:167], v[214:217], v[8:11]
	v_mfma_f32_16x16x32_bf16 v[52:55], v[168:171], v[184:187], v[52:55]
	v_mfma_f32_16x16x32_bf16 v[48:51], v[176:179], v[184:187], v[48:51]
	v_mfma_f32_16x16x32_bf16 v[36:39], v[168:171], v[194:197], v[36:39]
	v_mfma_f32_16x16x32_bf16 v[32:35], v[176:179], v[194:197], v[32:35]
	v_mfma_f32_16x16x32_bf16 v[20:23], v[168:171], v[202:205], v[20:23]
	v_mfma_f32_16x16x32_bf16 v[16:19], v[176:179], v[202:205], v[16:19]
	v_mfma_f32_16x16x32_bf16 v[4:7], v[168:171], v[210:213], v[4:7]
	v_mfma_f32_16x16x32_bf16 v[0:3], v[176:179], v[210:213], v[0:3]
	v_mfma_f32_16x16x32_bf16 v[52:55], v[172:175], v[188:191], v[52:55]
	v_mfma_f32_16x16x32_bf16 v[48:51], v[180:183], v[188:191], v[48:51]
	v_mfma_f32_16x16x32_bf16 v[36:39], v[172:175], v[198:201], v[36:39]
	v_mfma_f32_16x16x32_bf16 v[32:35], v[180:183], v[198:201], v[32:35]
	v_mfma_f32_16x16x32_bf16 v[20:23], v[172:175], v[206:209], v[20:23]
	v_mfma_f32_16x16x32_bf16 v[16:19], v[180:183], v[206:209], v[16:19]
	v_mfma_f32_16x16x32_bf16 v[4:7], v[172:175], v[214:217], v[4:7]
	v_mfma_f32_16x16x32_bf16 v[0:3], v[180:183], v[214:217], v[0:3]
	s_barrier
	s_add_i32 s55, 0, 0x18000
	v_add_u32_e32 v151, s55, v149
	s_add_i32 s56, 0, 0x1c000
	ds_read_b128 v[152:155], v151
	ds_read_b128 v[156:159], v151 offset:1024
	ds_read_b128 v[160:163], v151 offset:2048
	ds_read_b128 v[164:167], v151 offset:3072
	v_add_u32_e32 v151, s56, v149
	ds_read_b128 v[168:171], v151
	ds_read_b128 v[172:175], v151 offset:1024
	ds_read_b128 v[176:179], v151 offset:2048
	ds_read_b128 v[180:183], v151 offset:3072
	s_add_u32 s30, s30, 0x160000
	s_addc_u32 s31, s31, 0
	s_mov_b32 m0, s41
	v_lshl_add_u64 v[226:227], s[30:31], 0, v[128:129]
	ds_read_b128 v[184:187], v150 offset:32768
	ds_read_b128 v[188:191], v150 offset:33792
	ds_read_b128 v[194:197], v150 offset:34816
	ds_read_b128 v[198:201], v150 offset:35840
	ds_read_b128 v[202:205], v150 offset:36864
	ds_read_b128 v[206:209], v150 offset:37888
	ds_read_b128 v[210:213], v150 offset:38912
	ds_read_b128 v[214:217], v150 offset:39936
	global_load_lds_dwordx4 v[226:227], off
	v_lshl_add_u64 v[226:227], s[30:31], 0, v[132:133]
	s_mov_b32 m0, s42
	s_nop 0
	global_load_lds_dwordx4 v[226:227], off
	s_waitcnt vmcnt(8)
	s_waitcnt lgkmcnt(0)
	s_barrier
	s_waitcnt lgkmcnt(0)
	v_mfma_f32_16x16x32_bf16 v[124:127], v[152:155], v[184:187], v[124:127]
	v_mfma_f32_16x16x32_bf16 v[120:123], v[160:163], v[184:187], v[120:123]
	v_mfma_f32_16x16x32_bf16 v[108:111], v[152:155], v[194:197], v[108:111]
	v_mfma_f32_16x16x32_bf16 v[104:107], v[160:163], v[194:197], v[104:107]
	v_mfma_f32_16x16x32_bf16 v[92:95], v[152:155], v[202:205], v[92:95]
	v_mfma_f32_16x16x32_bf16 v[88:91], v[160:163], v[202:205], v[88:91]
	v_mfma_f32_16x16x32_bf16 v[76:79], v[152:155], v[210:213], v[76:79]
	v_mfma_f32_16x16x32_bf16 v[72:75], v[160:163], v[210:213], v[72:75]
	v_mfma_f32_16x16x32_bf16 v[124:127], v[156:159], v[188:191], v[124:127]
	v_mfma_f32_16x16x32_bf16 v[120:123], v[164:167], v[188:191], v[120:123]
	v_mfma_f32_16x16x32_bf16 v[108:111], v[156:159], v[198:201], v[108:111]
	v_mfma_f32_16x16x32_bf16 v[104:107], v[164:167], v[198:201], v[104:107]
	v_mfma_f32_16x16x32_bf16 v[92:95], v[156:159], v[206:209], v[92:95]
	v_mfma_f32_16x16x32_bf16 v[88:91], v[164:167], v[206:209], v[88:91]
	v_mfma_f32_16x16x32_bf16 v[76:79], v[156:159], v[214:217], v[76:79]
	v_mfma_f32_16x16x32_bf16 v[72:75], v[164:167], v[214:217], v[72:75]
	v_mfma_f32_16x16x32_bf16 v[116:119], v[168:171], v[184:187], v[116:119]
	v_mfma_f32_16x16x32_bf16 v[112:115], v[176:179], v[184:187], v[112:115]
	v_mfma_f32_16x16x32_bf16 v[100:103], v[168:171], v[194:197], v[100:103]
	v_mfma_f32_16x16x32_bf16 v[96:99], v[176:179], v[194:197], v[96:99]
	v_mfma_f32_16x16x32_bf16 v[84:87], v[168:171], v[202:205], v[84:87]
	v_mfma_f32_16x16x32_bf16 v[80:83], v[176:179], v[202:205], v[80:83]
	v_mfma_f32_16x16x32_bf16 v[68:71], v[168:171], v[210:213], v[68:71]
	v_mfma_f32_16x16x32_bf16 v[64:67], v[176:179], v[210:213], v[64:67]
	v_mfma_f32_16x16x32_bf16 v[116:119], v[172:175], v[188:191], v[116:119]
	v_mfma_f32_16x16x32_bf16 v[112:115], v[180:183], v[188:191], v[112:115]
	v_mfma_f32_16x16x32_bf16 v[100:103], v[172:175], v[198:201], v[100:103]
	v_mfma_f32_16x16x32_bf16 v[96:99], v[180:183], v[198:201], v[96:99]
	v_mfma_f32_16x16x32_bf16 v[84:87], v[172:175], v[206:209], v[84:87]
	v_mfma_f32_16x16x32_bf16 v[80:83], v[180:183], v[206:209], v[80:83]
	v_mfma_f32_16x16x32_bf16 v[68:71], v[172:175], v[214:217], v[68:71]
	v_mfma_f32_16x16x32_bf16 v[64:67], v[180:183], v[214:217], v[64:67]
	s_barrier
	s_add_i32 s30, s55, s38
	v_lshl_add_u64 v[218:219], v[218:219], 0, s[16:17]
	s_mov_b32 m0, s30
	ds_read_b128 v[184:187], v150 offset:49152
	ds_read_b128 v[188:191], v150 offset:50176
	ds_read_b128 v[194:197], v150 offset:51200
	ds_read_b128 v[198:201], v150 offset:52224
	ds_read_b128 v[202:205], v150 offset:53248
	ds_read_b128 v[206:209], v150 offset:54272
	ds_read_b128 v[210:213], v150 offset:55296
	ds_read_b128 v[214:217], v150 offset:56320
	global_load_lds_dwordx4 v[218:219], off
	s_add_i32 m0, s30, 0x2000
	s_add_u32 s28, s28, 0x160080
	v_lshl_add_u64 v[218:219], v[220:221], 0, s[16:17]
	s_addc_u32 s29, s29, 0
	s_add_i32 s30, s56, s38
	global_load_lds_dwordx4 v[218:219], off
	v_lshl_add_u64 v[218:219], s[28:29], 0, v[130:131]
	s_mov_b32 m0, s30
	s_nop 0
	global_load_lds_dwordx4 v[218:219], off
	v_lshl_add_u64 v[218:219], s[28:29], 0, v[134:135]
	s_add_i32 m0, s30, 0x2000
	s_nop 0
	global_load_lds_dwordx4 v[218:219], off
	v_lshl_add_u64 v[218:219], v[222:223], 0, s[16:17]
	s_mov_b32 m0, s45
	s_nop 0
	global_load_lds_dwordx4 v[218:219], off
	v_lshl_add_u64 v[218:219], v[224:225], 0, s[16:17]
	s_mov_b32 m0, s46
	s_nop 0
	global_load_lds_dwordx4 v[218:219], off
	s_waitcnt vmcnt(8)
	s_waitcnt lgkmcnt(0)
	s_barrier
	s_waitcnt lgkmcnt(0)
	v_mfma_f32_16x16x32_bf16 v[60:63], v[152:155], v[184:187], v[60:63]
	v_mfma_f32_16x16x32_bf16 v[56:59], v[160:163], v[184:187], v[56:59]
	v_mfma_f32_16x16x32_bf16 v[44:47], v[152:155], v[194:197], v[44:47]
	v_mfma_f32_16x16x32_bf16 v[40:43], v[160:163], v[194:197], v[40:43]
	v_mfma_f32_16x16x32_bf16 v[28:31], v[152:155], v[202:205], v[28:31]
	v_mfma_f32_16x16x32_bf16 v[24:27], v[160:163], v[202:205], v[24:27]
	v_mfma_f32_16x16x32_bf16 v[12:15], v[152:155], v[210:213], v[12:15]
	v_mfma_f32_16x16x32_bf16 v[8:11], v[160:163], v[210:213], v[8:11]
	v_mfma_f32_16x16x32_bf16 v[60:63], v[156:159], v[188:191], v[60:63]
	v_mfma_f32_16x16x32_bf16 v[56:59], v[164:167], v[188:191], v[56:59]
	v_mfma_f32_16x16x32_bf16 v[44:47], v[156:159], v[198:201], v[44:47]
	v_mfma_f32_16x16x32_bf16 v[40:43], v[164:167], v[198:201], v[40:43]
	v_mfma_f32_16x16x32_bf16 v[28:31], v[156:159], v[206:209], v[28:31]
	v_mfma_f32_16x16x32_bf16 v[24:27], v[164:167], v[206:209], v[24:27]
	v_mfma_f32_16x16x32_bf16 v[12:15], v[156:159], v[214:217], v[12:15]
	v_mfma_f32_16x16x32_bf16 v[8:11], v[164:167], v[214:217], v[8:11]
	v_mfma_f32_16x16x32_bf16 v[52:55], v[168:171], v[184:187], v[52:55]
	v_mfma_f32_16x16x32_bf16 v[48:51], v[176:179], v[184:187], v[48:51]
	v_mfma_f32_16x16x32_bf16 v[36:39], v[168:171], v[194:197], v[36:39]
	v_mfma_f32_16x16x32_bf16 v[32:35], v[176:179], v[194:197], v[32:35]
	v_mfma_f32_16x16x32_bf16 v[20:23], v[168:171], v[202:205], v[20:23]
	v_mfma_f32_16x16x32_bf16 v[16:19], v[176:179], v[202:205], v[16:19]
	v_mfma_f32_16x16x32_bf16 v[4:7], v[168:171], v[210:213], v[4:7]
	v_mfma_f32_16x16x32_bf16 v[0:3], v[176:179], v[210:213], v[0:3]
	v_mfma_f32_16x16x32_bf16 v[52:55], v[172:175], v[188:191], v[52:55]
	v_mfma_f32_16x16x32_bf16 v[48:51], v[180:183], v[188:191], v[48:51]
	v_mfma_f32_16x16x32_bf16 v[36:39], v[172:175], v[198:201], v[36:39]
	v_mfma_f32_16x16x32_bf16 v[32:35], v[180:183], v[198:201], v[32:35]
	v_mfma_f32_16x16x32_bf16 v[20:23], v[172:175], v[206:209], v[20:23]
	v_mfma_f32_16x16x32_bf16 v[16:19], v[180:183], v[206:209], v[16:19]
	v_mfma_f32_16x16x32_bf16 v[4:7], v[172:175], v[214:217], v[4:7]
	v_mfma_f32_16x16x32_bf16 v[0:3], v[180:183], v[214:217], v[0:3]
	s_barrier
	s_add_i32 s54, s54, 2
	s_add_u32 s26, s26, 0x100
	s_addc_u32 s27, s27, 0
	s_cmpk_gt_u32 s54, 0x55
	s_cbranch_scc0 .LBB0_2113
	s_and_b64 vcc, exec, s[18:19]
	s_cbranch_vccz .LBB0_2116
	s_barrier

.LBB0_2120:
	s_add_u32 s0, s10, 0x27000000
	s_addc_u32 s1, s11, 0
	s_add_u32 s2, s10, 0x28000
	s_addc_u32 s3, s11, 0
	s_lshl_b32 s4, s34, 8
	v_lshrrev_b32_e32 v128, 1, v192
	s_add_i32 s4, s4, s43
	v_and_b32_e32 v128, 24, v128
	v_or_b32_e32 v138, s4, v148
	v_lshl_or_b32 v128, s47, 8, v128
	v_ashrrev_i32_e32 v139, 31, v138
	v_or_b32_e32 v128, s44, v128
	v_lshlrev_b64 v[130:131], 12, v[138:139]
	v_ashrrev_i32_e32 v129, 31, v128
	v_lshl_add_u64 v[130:131], s[0:1], 0, v[130:131]
	v_lshl_add_u64 v[134:135], v[128:129], 1, v[130:131]
	global_load_dwordx4 v[172:175], v[134:135], off
	global_load_dwordx4 v[176:179], v[134:135], off offset:256
	v_add_co_u32_e32 v240, vcc, 0x10000, v134
	s_nop 1
	v_addc_co_u32_e32 v241, vcc, 0, v135, vcc
	global_load_dwordx4 v[180:183], v[240:241], off
	global_load_dwordx4 v[184:187], v[240:241], off offset:256
	v_add_co_u32_e32 v242, vcc, 0x20000, v134
	s_nop 1
	v_addc_co_u32_e32 v243, vcc, 0, v135, vcc
	global_load_dwordx4 v[188:191], v[242:243], off
	global_load_dwordx4 v[196:199], v[242:243], off offset:256
	v_add_co_u32_e32 v240, vcc, 0x30000, v134
	s_nop 1
	v_addc_co_u32_e32 v241, vcc, 0, v135, vcc
	global_load_dwordx4 v[200:203], v[240:241], off
	global_load_dwordx4 v[204:207], v[240:241], off offset:256
	v_add_co_u32_e32 v242, vcc, 0x80000, v134
	s_nop 1
	v_addc_co_u32_e32 v243, vcc, 0, v135, vcc
	global_load_dwordx4 v[208:211], v[242:243], off
	global_load_dwordx4 v[212:215], v[242:243], off offset:256
	v_add_co_u32_e32 v240, vcc, 0x90000, v134
	s_nop 1
	v_addc_co_u32_e32 v241, vcc, 0, v135, vcc
	global_load_dwordx4 v[216:219], v[240:241], off
	global_load_dwordx4 v[220:223], v[240:241], off offset:256
	v_add_co_u32_e32 v242, vcc, 0xa0000, v134
	s_nop 1
	v_addc_co_u32_e32 v243, vcc, 0, v135, vcc
	global_load_dwordx4 v[224:227], v[242:243], off
	global_load_dwordx4 v[228:231], v[242:243], off offset:256
	v_add_co_u32_e32 v240, vcc, 0xb0000, v134
	s_nop 1
	v_addc_co_u32_e32 v241, vcc, 0, v135, vcc
	global_load_dwordx4 v[232:235], v[240:241], off
	global_load_dwordx4 v[236:239], v[240:241], off offset:256
	s_waitcnt vmcnt(16)
	s_barrier
	s_waitcnt vmcnt(15)
	s_nop 0
	v_mov_b32_e32 v130, v172
	v_mov_b32_e32 v131, v173
	v_mov_b32_e32 v132, v174
	v_mov_b32_e32 v133, v175
	s_nop 0
	s_waitcnt vmcnt(14)
	s_nop 0
	v_mov_b32_e32 v134, v176
	v_mov_b32_e32 v135, v177
	v_mov_b32_e32 v136, v178
	v_mov_b32_e32 v137, v179
	v_mbcnt_lo_u32_b32 v140, -1, 0
	v_mbcnt_hi_u32_b32 v145, -1, v140
	v_and_b32_e32 v141, 64, v145
	v_xor_b32_e32 v140, 16, v145
	v_add_u32_e32 v152, 64, v141
	v_cmp_lt_i32_e32 vcc, v140, v152
	v_and_b32_e32 v141, 0xffff0000, v130
	v_cndmask_b32_e32 v140, v145, v140, vcc
	v_lshlrev_b32_e32 v144, 2, v140
	v_lshlrev_b32_e32 v140, 16, v130
	v_lshlrev_b32_e32 v130, 16, v131
	v_and_b32_e32 v131, 0xffff0000, v131
	v_lshlrev_b32_e32 v148, 16, v134
	v_and_b32_e32 v149, 0xffff0000, v134
	v_lshlrev_b32_e32 v134, 16, v135
	v_and_b32_e32 v135, 0xffff0000, v135
	v_lshlrev_b32_e32 v142, 16, v132
	v_and_b32_e32 v143, 0xffff0000, v132
	v_lshlrev_b32_e32 v146, 16, v133
	v_and_b32_e32 v147, 0xffff0000, v133
	v_lshlrev_b32_e32 v150, 16, v136
	v_and_b32_e32 v151, 0xffff0000, v136
	v_pk_add_f32 v[126:127], v[126:127], v[130:131]
	v_pk_add_f32 v[132:133], v[124:125], v[140:141]
	v_pk_add_f32 v[118:119], v[118:119], v[134:135]
	v_pk_add_f32 v[116:117], v[116:117], v[148:149]
	v_lshlrev_b32_e32 v136, 16, v137
	v_and_b32_e32 v137, 0xffff0000, v137
	v_pk_add_f32 v[124:125], v[120:121], v[142:143]
	v_pk_add_f32 v[120:121], v[112:113], v[150:151]
	v_mul_f32_e32 v112, v133, v133
	v_mul_f32_e32 v113, v127, v127
	v_mul_f32_e32 v134, v117, v117
	v_mul_f32_e32 v135, v119, v119
	v_pk_add_f32 v[122:123], v[122:123], v[146:147]
	v_pk_add_f32 v[114:115], v[114:115], v[136:137]
	v_mul_f32_e32 v130, v125, v125
	v_mul_f32_e32 v136, v121, v121
	v_fmac_f32_e32 v112, v132, v132
	v_fmac_f32_e32 v113, v126, v126
	v_fmac_f32_e32 v134, v116, v116
	v_fmac_f32_e32 v135, v118, v118
	v_mul_f32_e32 v131, v123, v123
	v_mul_f32_e32 v137, v115, v115
	v_fmac_f32_e32 v130, v124, v124
	v_fmac_f32_e32 v136, v120, v120
	v_add_f32_e32 v112, v112, v113
	v_add_f32_e32 v113, v134, v135
	v_fmac_f32_e32 v131, v122, v122
	v_fmac_f32_e32 v137, v114, v114
	v_add_f32_e32 v112, v130, v112
	v_add_f32_e32 v113, v136, v113
	v_add_f32_e32 v112, v131, v112
	v_add_f32_e32 v113, v137, v113
	v_add_f32_e32 v112, v112, v113
	ds_bpermute_b32 v113, v144, v112
	v_xor_b32_e32 v130, 32, v145
	v_cmp_lt_i32_e32 vcc, v130, v152
	s_nop 1
	v_cndmask_b32_e32 v130, v145, v130, vcc
	v_lshlrev_b32_e32 v146, 2, v130
	s_waitcnt lgkmcnt(0)
	v_add_f32_e32 v130, v112, v113
	ds_bpermute_b32 v131, v146, v130
	v_and_b32_e32 v145, 63, v192
	v_cmp_gt_u32_e32 vcc, 16, v145
	v_lshl_add_u64 v[112:113], v[138:139], 2, s[2:3]
	s_and_saveexec_b64 s[4:5], vcc
	s_cbranch_execz .LBB0_2122
	s_waitcnt lgkmcnt(0)
	v_add_f32_e32 v130, v130, v131
	global_atomic_add_f32 v[112:113], v130, off
.LBB0_2122:
	s_or_b64 exec, exec, s[4:5]
	v_or_b32_e32 v136, 16, v138
	v_ashrrev_i32_e32 v137, 31, v136
	s_waitcnt lgkmcnt(0)
	v_lshlrev_b64 v[130:131], 12, v[136:137]
	v_lshl_add_u64 v[130:131], s[0:1], 0, v[130:131]
	v_lshl_add_u64 v[130:131], v[128:129], 1, v[130:131]
	s_waitcnt vmcnt(13)
	s_nop 0
	v_mov_b32_e32 v140, v180
	v_mov_b32_e32 v141, v181
	v_mov_b32_e32 v142, v182
	v_mov_b32_e32 v143, v183
	s_waitcnt vmcnt(12)
	s_nop 0
	v_mov_b32_e32 v148, v184
	v_mov_b32_e32 v149, v185
	v_mov_b32_e32 v150, v186
	v_mov_b32_e32 v151, v187
	v_lshlrev_b32_e32 v130, 16, v140
	v_and_b32_e32 v131, 0xffff0000, v140
	v_lshlrev_b32_e32 v134, 16, v141
	v_and_b32_e32 v135, 0xffff0000, v141
	v_lshlrev_b32_e32 v152, 16, v148
	v_and_b32_e32 v153, 0xffff0000, v148
	v_lshlrev_b32_e32 v148, 16, v149
	v_and_b32_e32 v149, 0xffff0000, v149
	v_lshlrev_b32_e32 v140, 16, v142
	v_and_b32_e32 v141, 0xffff0000, v142
	v_lshlrev_b32_e32 v154, 16, v150
	v_and_b32_e32 v155, 0xffff0000, v150
	v_pk_add_f32 v[110:111], v[110:111], v[134:135]
	v_pk_add_f32 v[130:131], v[108:109], v[130:131]
	v_pk_add_f32 v[102:103], v[102:103], v[148:149]
	v_pk_add_f32 v[100:101], v[100:101], v[152:153]
	v_lshlrev_b32_e32 v142, 16, v143
	v_and_b32_e32 v143, 0xffff0000, v143
	v_lshlrev_b32_e32 v150, 16, v151
	v_and_b32_e32 v151, 0xffff0000, v151
	v_pk_add_f32 v[104:105], v[104:105], v[140:141]
	v_pk_add_f32 v[96:97], v[96:97], v[154:155]
	v_mul_f32_e32 v108, v131, v131
	v_mul_f32_e32 v109, v111, v111
	v_mul_f32_e32 v140, v101, v101
	v_mul_f32_e32 v141, v103, v103
	v_pk_add_f32 v[106:107], v[106:107], v[142:143]
	v_pk_add_f32 v[98:99], v[98:99], v[150:151]
	v_mul_f32_e32 v134, v105, v105
	v_mul_f32_e32 v142, v97, v97
	v_fmac_f32_e32 v108, v130, v130
	v_fmac_f32_e32 v109, v110, v110
	v_fmac_f32_e32 v140, v100, v100
	v_fmac_f32_e32 v141, v102, v102
	v_mul_f32_e32 v135, v107, v107
	v_mul_f32_e32 v143, v99, v99
	v_fmac_f32_e32 v134, v104, v104
	v_fmac_f32_e32 v142, v96, v96
	v_add_f32_e32 v108, v108, v109
	v_add_f32_e32 v109, v140, v141
	v_fmac_f32_e32 v135, v106, v106
	v_fmac_f32_e32 v143, v98, v98
	v_add_f32_e32 v108, v134, v108
	v_add_f32_e32 v109, v142, v109
	v_add_f32_e32 v108, v135, v108
	v_add_f32_e32 v109, v143, v109
	v_add_f32_e32 v108, v108, v109
	ds_bpermute_b32 v109, v144, v108
	s_waitcnt lgkmcnt(0)
	v_add_f32_e32 v108, v108, v109
	ds_bpermute_b32 v109, v146, v108
	s_and_saveexec_b64 s[4:5], vcc
	s_cbranch_execz .LBB0_2124
	s_waitcnt lgkmcnt(0)
	v_add_f32_e32 v108, v108, v109
	global_atomic_add_f32 v[112:113], v108, off offset:64
.LBB0_2124:
	s_or_b64 exec, exec, s[4:5]
	v_or_b32_e32 v134, 32, v138
	v_ashrrev_i32_e32 v135, 31, v134
	s_waitcnt lgkmcnt(0)
	v_lshlrev_b64 v[108:109], 12, v[134:135]
	v_lshl_add_u64 v[108:109], s[0:1], 0, v[108:109]
	v_lshl_add_u64 v[108:109], v[128:129], 1, v[108:109]
	s_waitcnt vmcnt(11)
	s_nop 0
	v_mov_b32_e32 v140, v188
	v_mov_b32_e32 v141, v189
	v_mov_b32_e32 v142, v190
	v_mov_b32_e32 v143, v191
	s_waitcnt vmcnt(10)
	s_nop 0
	v_mov_b32_e32 v148, v196
	v_mov_b32_e32 v149, v197
	v_mov_b32_e32 v150, v198
	v_mov_b32_e32 v151, v199
	v_lshlrev_b32_e32 v108, 16, v140
	v_and_b32_e32 v109, 0xffff0000, v140
	v_lshlrev_b32_e32 v140, 16, v141
	v_and_b32_e32 v141, 0xffff0000, v141
	v_lshlrev_b32_e32 v154, 16, v148
	v_and_b32_e32 v155, 0xffff0000, v148
	v_lshlrev_b32_e32 v148, 16, v149
	v_and_b32_e32 v149, 0xffff0000, v149
	v_lshlrev_b32_e32 v152, 16, v142
	v_and_b32_e32 v153, 0xffff0000, v142
	v_lshlrev_b32_e32 v142, 16, v143
	v_and_b32_e32 v143, 0xffff0000, v143
	v_lshlrev_b32_e32 v156, 16, v150
	v_and_b32_e32 v157, 0xffff0000, v150
	v_pk_add_f32 v[94:95], v[94:95], v[140:141]
	v_pk_add_f32 v[92:93], v[92:93], v[108:109]
	v_pk_add_f32 v[86:87], v[86:87], v[148:149]
	v_pk_add_f32 v[84:85], v[84:85], v[154:155]
	v_lshlrev_b32_e32 v150, 16, v151
	v_and_b32_e32 v151, 0xffff0000, v151
	v_pk_add_f32 v[90:91], v[90:91], v[142:143]
	v_pk_add_f32 v[88:89], v[88:89], v[152:153]
	v_pk_add_f32 v[80:81], v[80:81], v[156:157]
	v_mul_f32_e32 v108, v93, v93
	v_mul_f32_e32 v109, v95, v95
	v_mul_f32_e32 v142, v85, v85
	v_mul_f32_e32 v143, v87, v87
	v_pk_add_f32 v[82:83], v[82:83], v[150:151]
	v_mul_f32_e32 v140, v89, v89
	v_mul_f32_e32 v147, v81, v81
	v_fmac_f32_e32 v108, v92, v92
	v_fmac_f32_e32 v109, v94, v94
	v_fmac_f32_e32 v142, v84, v84
	v_fmac_f32_e32 v143, v86, v86
	v_mul_f32_e32 v141, v91, v91
	v_mul_f32_e32 v148, v83, v83
	v_fmac_f32_e32 v140, v88, v88
	v_fmac_f32_e32 v147, v80, v80
	v_add_f32_e32 v108, v108, v109
	v_add_f32_e32 v109, v142, v143
	v_fmac_f32_e32 v141, v90, v90
	v_fmac_f32_e32 v148, v82, v82
	v_add_f32_e32 v108, v140, v108
	v_add_f32_e32 v109, v147, v109
	v_add_f32_e32 v108, v141, v108
	v_add_f32_e32 v109, v148, v109
	v_add_f32_e32 v108, v108, v109
	ds_bpermute_b32 v109, v144, v108
	s_waitcnt lgkmcnt(0)
	v_add_f32_e32 v108, v108, v109
	ds_bpermute_b32 v109, v146, v108
	s_and_saveexec_b64 s[4:5], vcc
	s_cbranch_execz .LBB0_2126
	s_waitcnt lgkmcnt(0)
	v_add_f32_e32 v108, v108, v109
	global_atomic_add_f32 v[112:113], v108, off offset:128
.LBB0_2126:
	s_or_b64 exec, exec, s[4:5]
	v_or_b32_e32 v108, 48, v138
	s_waitcnt lgkmcnt(0)
	v_ashrrev_i32_e32 v109, 31, v108
	v_lshlrev_b64 v[140:141], 12, v[108:109]
	v_lshl_add_u64 v[140:141], s[0:1], 0, v[140:141]
	v_lshl_add_u64 v[148:149], v[128:129], 1, v[140:141]
	s_waitcnt vmcnt(9)
	s_nop 0
	v_mov_b32_e32 v140, v200
	v_mov_b32_e32 v141, v201
	v_mov_b32_e32 v142, v202
	v_mov_b32_e32 v143, v203
	s_nop 0
	s_waitcnt vmcnt(8)
	s_nop 0
	v_mov_b32_e32 v148, v204
	v_mov_b32_e32 v149, v205
	v_mov_b32_e32 v150, v206
	v_mov_b32_e32 v151, v207
	v_lshlrev_b32_e32 v152, 16, v140
	v_and_b32_e32 v153, 0xffff0000, v140
	v_lshlrev_b32_e32 v140, 16, v141
	v_and_b32_e32 v141, 0xffff0000, v141
	v_lshlrev_b32_e32 v156, 16, v148
	v_and_b32_e32 v157, 0xffff0000, v148
	v_lshlrev_b32_e32 v148, 16, v149
	v_and_b32_e32 v149, 0xffff0000, v149
	v_lshlrev_b32_e32 v154, 16, v142
	v_and_b32_e32 v155, 0xffff0000, v142
	v_lshlrev_b32_e32 v158, 16, v150
	v_and_b32_e32 v159, 0xffff0000, v150
	v_pk_add_f32 v[78:79], v[78:79], v[140:141]
	v_pk_add_f32 v[76:77], v[76:77], v[152:153]
	v_pk_add_f32 v[70:71], v[70:71], v[148:149]
	v_pk_add_f32 v[68:69], v[68:69], v[156:157]
	v_lshlrev_b32_e32 v142, 16, v143
	v_and_b32_e32 v143, 0xffff0000, v143
	v_lshlrev_b32_e32 v150, 16, v151
	v_and_b32_e32 v151, 0xffff0000, v151
	v_pk_add_f32 v[72:73], v[72:73], v[154:155]
	v_pk_add_f32 v[64:65], v[64:65], v[158:159]
	v_mul_f32_e32 v140, v77, v77
	v_mul_f32_e32 v141, v79, v79
	v_mul_f32_e32 v147, v69, v69
	v_mul_f32_e32 v148, v71, v71
	v_pk_add_f32 v[74:75], v[74:75], v[142:143]
	v_pk_add_f32 v[66:67], v[66:67], v[150:151]
	v_mul_f32_e32 v142, v73, v73
	v_mul_f32_e32 v149, v65, v65
	v_fmac_f32_e32 v140, v76, v76
	v_fmac_f32_e32 v141, v78, v78
	v_fmac_f32_e32 v147, v68, v68
	v_fmac_f32_e32 v148, v70, v70
	v_mul_f32_e32 v143, v75, v75
	v_mul_f32_e32 v150, v67, v67
	v_fmac_f32_e32 v142, v72, v72
	v_fmac_f32_e32 v149, v64, v64
	v_add_f32_e32 v140, v140, v141
	v_add_f32_e32 v141, v147, v148
	v_fmac_f32_e32 v143, v74, v74
	v_fmac_f32_e32 v150, v66, v66
	v_add_f32_e32 v140, v142, v140
	v_add_f32_e32 v141, v149, v141
	v_add_f32_e32 v140, v143, v140
	v_add_f32_e32 v141, v150, v141
	v_add_f32_e32 v140, v140, v141
	ds_bpermute_b32 v141, v144, v140
	s_waitcnt lgkmcnt(0)
	v_add_f32_e32 v140, v140, v141
	ds_bpermute_b32 v141, v146, v140
	s_and_saveexec_b64 s[4:5], vcc
	s_cbranch_execz .LBB0_2128
	s_waitcnt lgkmcnt(0)
	v_add_f32_e32 v140, v140, v141
	global_atomic_add_f32 v[112:113], v140, off offset:192
.LBB0_2128:
	s_or_b64 exec, exec, s[4:5]
	v_add_u32_e32 v140, 0x80, v138
	s_waitcnt lgkmcnt(0)
	v_ashrrev_i32_e32 v141, 31, v140
	v_lshlrev_b64 v[142:143], 12, v[140:141]
	v_lshl_add_u64 v[142:143], s[0:1], 0, v[142:143]
	v_lshl_add_u64 v[142:143], v[128:129], 1, v[142:143]
	s_waitcnt vmcnt(7)
	s_nop 0
	v_mov_b32_e32 v148, v208
	v_mov_b32_e32 v149, v209
	v_mov_b32_e32 v150, v210
	v_mov_b32_e32 v151, v211
	s_waitcnt vmcnt(6)
	s_nop 0
	v_mov_b32_e32 v152, v212
	v_mov_b32_e32 v153, v213
	v_mov_b32_e32 v154, v214
	v_mov_b32_e32 v155, v215
	v_lshlrev_b32_e32 v142, 16, v148
	v_and_b32_e32 v143, 0xffff0000, v148
	v_lshlrev_b32_e32 v148, 16, v149
	v_and_b32_e32 v149, 0xffff0000, v149
	v_lshlrev_b32_e32 v158, 16, v152
	v_and_b32_e32 v159, 0xffff0000, v152
	v_lshlrev_b32_e32 v152, 16, v153
	v_and_b32_e32 v153, 0xffff0000, v153
	v_lshlrev_b32_e32 v156, 16, v150
	v_and_b32_e32 v157, 0xffff0000, v150
	v_lshlrev_b32_e32 v150, 16, v151
	v_and_b32_e32 v151, 0xffff0000, v151
	v_lshlrev_b32_e32 v160, 16, v154
	v_and_b32_e32 v161, 0xffff0000, v154
	v_pk_add_f32 v[62:63], v[62:63], v[148:149]
	v_pk_add_f32 v[60:61], v[60:61], v[142:143]
	v_pk_add_f32 v[54:55], v[54:55], v[152:153]
	v_pk_add_f32 v[52:53], v[52:53], v[158:159]
	v_lshlrev_b32_e32 v154, 16, v155
	v_and_b32_e32 v155, 0xffff0000, v155
	v_pk_add_f32 v[58:59], v[58:59], v[150:151]
	v_pk_add_f32 v[56:57], v[56:57], v[156:157]
	v_pk_add_f32 v[48:49], v[48:49], v[160:161]
	v_mul_f32_e32 v142, v61, v61
	v_mul_f32_e32 v143, v63, v63
	v_mul_f32_e32 v149, v53, v53
	v_mul_f32_e32 v150, v55, v55
	v_pk_add_f32 v[50:51], v[50:51], v[154:155]
	v_mul_f32_e32 v147, v57, v57
	v_mul_f32_e32 v151, v49, v49
	v_fmac_f32_e32 v142, v60, v60
	v_fmac_f32_e32 v143, v62, v62
	v_fmac_f32_e32 v149, v52, v52
	v_fmac_f32_e32 v150, v54, v54
	v_mul_f32_e32 v148, v59, v59
	v_mul_f32_e32 v152, v51, v51
	v_fmac_f32_e32 v147, v56, v56
	v_fmac_f32_e32 v151, v48, v48
	v_add_f32_e32 v142, v142, v143
	v_add_f32_e32 v143, v149, v150
	v_fmac_f32_e32 v148, v58, v58
	v_fmac_f32_e32 v152, v50, v50
	v_add_f32_e32 v142, v147, v142
	v_add_f32_e32 v143, v151, v143
	v_add_f32_e32 v142, v148, v142
	v_add_f32_e32 v143, v152, v143
	v_add_f32_e32 v142, v142, v143
	ds_bpermute_b32 v143, v144, v142
	s_waitcnt lgkmcnt(0)
	v_add_f32_e32 v142, v142, v143
	ds_bpermute_b32 v143, v146, v142
	s_and_saveexec_b64 s[4:5], vcc
	s_cbranch_execz .LBB0_2130
	s_waitcnt lgkmcnt(0)
	v_add_f32_e32 v142, v142, v143
	global_atomic_add_f32 v[112:113], v142, off offset:512
.LBB0_2130:
	s_or_b64 exec, exec, s[4:5]
	v_add_u32_e32 v142, 0x90, v138
	s_waitcnt lgkmcnt(0)
	v_ashrrev_i32_e32 v143, 31, v142
	v_lshlrev_b64 v[148:149], 12, v[142:143]
	v_lshl_add_u64 v[148:149], s[0:1], 0, v[148:149]
	v_lshl_add_u64 v[152:153], v[128:129], 1, v[148:149]
	s_waitcnt vmcnt(5)
	s_nop 0
	v_mov_b32_e32 v148, v216
	v_mov_b32_e32 v149, v217
	v_mov_b32_e32 v150, v218
	v_mov_b32_e32 v151, v219
	s_nop 0
	s_waitcnt vmcnt(4)
	s_nop 0
	v_mov_b32_e32 v152, v220
	v_mov_b32_e32 v153, v221
	v_mov_b32_e32 v154, v222
	v_mov_b32_e32 v155, v223
	v_lshlrev_b32_e32 v156, 16, v148
	v_and_b32_e32 v157, 0xffff0000, v148
	v_lshlrev_b32_e32 v148, 16, v149
	v_and_b32_e32 v149, 0xffff0000, v149
	v_lshlrev_b32_e32 v160, 16, v152
	v_and_b32_e32 v161, 0xffff0000, v152
	v_lshlrev_b32_e32 v152, 16, v153
	v_and_b32_e32 v153, 0xffff0000, v153
	v_lshlrev_b32_e32 v158, 16, v150
	v_and_b32_e32 v159, 0xffff0000, v150
	v_lshlrev_b32_e32 v150, 16, v151
	v_and_b32_e32 v151, 0xffff0000, v151
	v_lshlrev_b32_e32 v162, 16, v154
	v_and_b32_e32 v163, 0xffff0000, v154
	v_pk_add_f32 v[46:47], v[46:47], v[148:149]
	v_pk_add_f32 v[44:45], v[44:45], v[156:157]
	v_pk_add_f32 v[38:39], v[38:39], v[152:153]
	v_pk_add_f32 v[36:37], v[36:37], v[160:161]
	v_lshlrev_b32_e32 v154, 16, v155
	v_and_b32_e32 v155, 0xffff0000, v155
	v_pk_add_f32 v[42:43], v[42:43], v[150:151]
	v_pk_add_f32 v[40:41], v[40:41], v[158:159]
	v_pk_add_f32 v[32:33], v[32:33], v[162:163]
	v_mul_f32_e32 v147, v45, v45
	v_mul_f32_e32 v148, v47, v47
	v_mul_f32_e32 v151, v37, v37
	v_mul_f32_e32 v152, v39, v39
	v_pk_add_f32 v[34:35], v[34:35], v[154:155]
	v_mul_f32_e32 v149, v41, v41
	v_mul_f32_e32 v153, v33, v33
	v_fmac_f32_e32 v147, v44, v44
	v_fmac_f32_e32 v148, v46, v46
	v_fmac_f32_e32 v151, v36, v36
	v_fmac_f32_e32 v152, v38, v38
	v_mul_f32_e32 v150, v43, v43
	v_mul_f32_e32 v154, v35, v35
	v_fmac_f32_e32 v149, v40, v40
	v_fmac_f32_e32 v153, v32, v32
	v_add_f32_e32 v147, v147, v148
	v_add_f32_e32 v148, v151, v152
	v_fmac_f32_e32 v150, v42, v42
	v_fmac_f32_e32 v154, v34, v34
	v_add_f32_e32 v147, v149, v147
	v_add_f32_e32 v148, v153, v148
	v_add_f32_e32 v147, v150, v147
	v_add_f32_e32 v148, v154, v148
	v_add_f32_e32 v147, v147, v148
	ds_bpermute_b32 v148, v144, v147
	s_waitcnt lgkmcnt(0)
	v_add_f32_e32 v147, v147, v148
	ds_bpermute_b32 v148, v146, v147
	s_and_saveexec_b64 s[4:5], vcc
	s_cbranch_execz .LBB0_2132
	s_waitcnt lgkmcnt(0)
	v_add_f32_e32 v147, v147, v148
	global_atomic_add_f32 v[112:113], v147, off offset:576
.LBB0_2132:
	s_or_b64 exec, exec, s[4:5]
	v_add_u32_e32 v152, 0xa0, v138
	v_ashrrev_i32_e32 v153, 31, v152
	s_waitcnt lgkmcnt(0)
	v_lshlrev_b64 v[148:149], 12, v[152:153]
	v_lshl_add_u64 v[148:149], s[0:1], 0, v[148:149]
	v_lshl_add_u64 v[154:155], v[128:129], 1, v[148:149]
	s_waitcnt vmcnt(3)
	s_nop 0
	v_mov_b32_e32 v148, v224
	v_mov_b32_e32 v149, v225
	v_mov_b32_e32 v150, v226
	v_mov_b32_e32 v151, v227
	s_nop 0
	s_waitcnt vmcnt(2)
	s_nop 0
	v_mov_b32_e32 v154, v228
	v_mov_b32_e32 v155, v229
	v_mov_b32_e32 v156, v230
	v_mov_b32_e32 v157, v231
	v_lshlrev_b32_e32 v158, 16, v148
	v_and_b32_e32 v159, 0xffff0000, v148
	v_lshlrev_b32_e32 v148, 16, v149
	v_and_b32_e32 v149, 0xffff0000, v149
	v_lshlrev_b32_e32 v162, 16, v154
	v_and_b32_e32 v163, 0xffff0000, v154
	v_lshlrev_b32_e32 v154, 16, v155
	v_and_b32_e32 v155, 0xffff0000, v155
	v_lshlrev_b32_e32 v160, 16, v150
	v_and_b32_e32 v161, 0xffff0000, v150
	v_lshlrev_b32_e32 v150, 16, v151
	v_and_b32_e32 v151, 0xffff0000, v151
	v_lshlrev_b32_e32 v164, 16, v156
	v_and_b32_e32 v165, 0xffff0000, v156
	v_pk_add_f32 v[30:31], v[30:31], v[148:149]
	v_pk_add_f32 v[28:29], v[28:29], v[158:159]
	v_pk_add_f32 v[22:23], v[22:23], v[154:155]
	v_pk_add_f32 v[20:21], v[20:21], v[162:163]
	v_lshlrev_b32_e32 v156, 16, v157
	v_and_b32_e32 v157, 0xffff0000, v157
	v_pk_add_f32 v[26:27], v[26:27], v[150:151]
	v_pk_add_f32 v[24:25], v[24:25], v[160:161]
	v_pk_add_f32 v[16:17], v[16:17], v[164:165]
	v_mul_f32_e32 v147, v29, v29
	v_mul_f32_e32 v148, v31, v31
	v_mul_f32_e32 v151, v21, v21
	v_mul_f32_e32 v154, v23, v23
	v_pk_add_f32 v[18:19], v[18:19], v[156:157]
	v_mul_f32_e32 v149, v25, v25
	v_mul_f32_e32 v155, v17, v17
	v_fmac_f32_e32 v147, v28, v28
	v_fmac_f32_e32 v148, v30, v30
	v_fmac_f32_e32 v151, v20, v20
	v_fmac_f32_e32 v154, v22, v22
	v_mul_f32_e32 v150, v27, v27
	v_mul_f32_e32 v156, v19, v19
	v_fmac_f32_e32 v149, v24, v24
	v_fmac_f32_e32 v155, v16, v16
	v_add_f32_e32 v147, v147, v148
	v_add_f32_e32 v148, v151, v154
	v_fmac_f32_e32 v150, v26, v26
	v_fmac_f32_e32 v156, v18, v18
	v_add_f32_e32 v147, v149, v147
	v_add_f32_e32 v148, v155, v148
	v_add_f32_e32 v147, v150, v147
	v_add_f32_e32 v148, v156, v148
	v_add_f32_e32 v147, v147, v148
	ds_bpermute_b32 v148, v144, v147
	s_waitcnt lgkmcnt(0)
	v_add_f32_e32 v147, v147, v148
	ds_bpermute_b32 v148, v146, v147
	s_and_saveexec_b64 s[4:5], vcc
	s_cbranch_execz .LBB0_2134
	s_waitcnt lgkmcnt(0)
	v_add_f32_e32 v147, v147, v148
	global_atomic_add_f32 v[112:113], v147, off offset:640
.LBB0_2134:
	s_or_b64 exec, exec, s[4:5]
	v_add_u32_e32 v156, 0xb0, v138
	v_ashrrev_i32_e32 v157, 31, v156
	s_waitcnt lgkmcnt(0)
	v_lshlrev_b64 v[148:149], 12, v[156:157]
	v_lshl_add_u64 v[148:149], s[0:1], 0, v[148:149]
	v_lshl_add_u64 v[154:155], v[128:129], 1, v[148:149]
	s_waitcnt vmcnt(1)
	s_nop 0
	v_mov_b32_e32 v148, v232
	v_mov_b32_e32 v149, v233
	v_mov_b32_e32 v150, v234
	v_mov_b32_e32 v151, v235
	s_waitcnt vmcnt(0)
	s_nop 0
	v_mov_b32_e32 v158, v236
	v_mov_b32_e32 v159, v237
	v_mov_b32_e32 v160, v238
	v_mov_b32_e32 v161, v239
	v_lshlrev_b32_e32 v154, 16, v148
	v_and_b32_e32 v155, 0xffff0000, v148
	v_lshlrev_b32_e32 v148, 16, v149
	v_and_b32_e32 v149, 0xffff0000, v149
	v_lshlrev_b32_e32 v164, 16, v158
	v_and_b32_e32 v165, 0xffff0000, v158
	v_lshlrev_b32_e32 v158, 16, v159
	v_and_b32_e32 v159, 0xffff0000, v159
	v_lshlrev_b32_e32 v162, 16, v150
	v_and_b32_e32 v163, 0xffff0000, v150
	v_lshlrev_b32_e32 v150, 16, v151
	v_and_b32_e32 v151, 0xffff0000, v151
	v_lshlrev_b32_e32 v166, 16, v160
	v_and_b32_e32 v167, 0xffff0000, v160
	v_pk_add_f32 v[14:15], v[14:15], v[148:149]
	v_pk_add_f32 v[12:13], v[12:13], v[154:155]
	v_pk_add_f32 v[6:7], v[6:7], v[158:159]
	v_pk_add_f32 v[4:5], v[4:5], v[164:165]
	v_lshlrev_b32_e32 v160, 16, v161
	v_and_b32_e32 v161, 0xffff0000, v161
	v_pk_add_f32 v[10:11], v[10:11], v[150:151]
	v_pk_add_f32 v[8:9], v[8:9], v[162:163]
	v_pk_add_f32 v[0:1], v[0:1], v[166:167]
	v_mul_f32_e32 v147, v13, v13
	v_mul_f32_e32 v148, v15, v15
	v_mul_f32_e32 v151, v5, v5
	v_mul_f32_e32 v154, v7, v7
	v_pk_add_f32 v[2:3], v[2:3], v[160:161]
	v_mul_f32_e32 v149, v9, v9
	v_mul_f32_e32 v155, v1, v1
	v_fmac_f32_e32 v147, v12, v12
	v_fmac_f32_e32 v148, v14, v14
	v_fmac_f32_e32 v151, v4, v4
	v_fmac_f32_e32 v154, v6, v6
	v_mul_f32_e32 v150, v11, v11
	v_mul_f32_e32 v158, v3, v3
	v_fmac_f32_e32 v149, v8, v8
	v_fmac_f32_e32 v155, v0, v0
	v_add_f32_e32 v147, v147, v148
	v_add_f32_e32 v148, v151, v154
	v_fmac_f32_e32 v150, v10, v10
	v_fmac_f32_e32 v158, v2, v2
	v_add_f32_e32 v147, v149, v147
	v_add_f32_e32 v148, v155, v148
	v_add_f32_e32 v147, v150, v147
	v_add_f32_e32 v148, v158, v148
	v_add_f32_e32 v147, v147, v148
	ds_bpermute_b32 v144, v144, v147
	s_waitcnt lgkmcnt(0)
	v_add_f32_e32 v144, v147, v144
	ds_bpermute_b32 v146, v146, v144
	s_and_saveexec_b64 s[0:1], vcc
	s_cbranch_execz .LBB0_2136
	s_waitcnt lgkmcnt(0)
	v_add_f32_e32 v144, v144, v146
	global_atomic_add_f32 v[112:113], v144, off offset:704

.LBB0_2145:
	s_waitcnt vmcnt(0) lgkmcnt(0)
	s_barrier
	v_lshlrev_b64 v[140:141], 2, v[128:129]
	v_lshl_add_u64 v[128:129], s[12:13], 0, v[140:141]
	global_load_dwordx4 v[180:183], v[128:129], off
	global_load_dwordx4 v[184:187], v[128:129], off offset:16
	global_load_dwordx4 v[188:191], v[128:129], off offset:512
	global_load_dwordx4 v[196:199], v[128:129], off offset:528
	global_load_dword v172, v[112:113], off sc1
	global_load_dword v173, v[112:113], off offset:64 sc1
	global_load_dword v174, v[112:113], off offset:128 sc1
	global_load_dword v175, v[112:113], off offset:192 sc1
	global_load_dword v176, v[112:113], off offset:512 sc1
	global_load_dword v177, v[112:113], off offset:576 sc1
	global_load_dword v178, v[112:113], off offset:640 sc1
	global_load_dword v179, v[112:113], off offset:704 sc1
	s_nop 0
	s_nop 0
	v_mov_b32_e32 v153, 0x358637bd
	s_mov_b32 s4, 0xf800000
	s_waitcnt vmcnt(7)
	v_mov_b32_e32 v152, v172
	v_fmamk_f32 v152, v152, 0x3a000000, v153
	v_mul_f32_e32 v156, 0x4f800000, v152
	v_cmp_gt_f32_e32 vcc, s4, v152
	s_nop 1
	v_cndmask_b32_e32 v168, v152, v156, vcc
	v_sqrt_f32_e32 v169, v168
	v_lshl_add_u64 v[156:157], v[158:159], 2, s[8:9]
	v_mov_b32_e32 v152, 0x260
	v_add_u32_e32 v158, -1, v169
	v_add_u32_e32 v159, 1, v169
	v_fma_f32 v170, -v158, v169, v168
	v_fma_f32 v171, -v159, v169, v168
	v_cmp_ge_f32_e64 s[0:1], 0, v170
	s_nop 1
	v_cndmask_b32_e64 v158, v169, v158, s[0:1]
	v_cmp_lt_f32_e64 s[0:1], 0, v171
	s_nop 1
	v_cndmask_b32_e64 v158, v158, v159, s[0:1]
	v_mul_f32_e32 v159, 0x37800000, v158
	v_cndmask_b32_e32 v158, v158, v159, vcc
	v_cmp_class_f32_e32 vcc, v168, v152
	s_nop 1
	v_cndmask_b32_e32 v158, v158, v168, vcc
	v_div_scale_f32 v159, s[0:1], v158, v158, 1.0
	v_rcp_f32_e32 v170, v159
	v_lshl_add_u64 v[168:169], v[156:157], 0, v[140:141]
	v_div_scale_f32 v156, vcc, 1.0, v158, 1.0
	v_fma_f32 v157, -v159, v170, 1.0
	v_fmac_f32_e32 v170, v157, v170
	v_mul_f32_e32 v157, v156, v170
	v_fma_f32 v171, -v159, v157, v156
	v_fmac_f32_e32 v157, v171, v170
	v_fma_f32 v156, -v159, v157, v156
	v_div_fmas_f32 v156, v156, v170, v157
	v_div_fixup_f32 v170, v156, v158, 1.0
	v_pk_mul_f32 v[132:133], v[132:133], v[170:171] op_sel_hi:[1,0]
	v_pk_mul_f32 v[126:127], v[126:127], v[170:171] op_sel_hi:[1,0]
	v_pk_mul_f32 v[156:157], v[124:125], v[170:171] op_sel_hi:[1,0]
	v_pk_mul_f32 v[158:159], v[122:123], v[170:171] op_sel_hi:[1,0]
	v_mov_b32_e32 v160, v180
	v_mov_b32_e32 v161, v181
	v_mov_b32_e32 v162, v182
	v_mov_b32_e32 v163, v183
	v_pk_mul_f32 v[124:125], v[162:163], v[126:127]
	v_pk_mul_f32 v[122:123], v[160:161], v[132:133]
	v_mov_b32_e32 v164, v184
	v_mov_b32_e32 v165, v185
	v_mov_b32_e32 v166, v186
	v_mov_b32_e32 v167, v187
	v_pk_mul_f32 v[158:159], v[166:167], v[158:159]
	v_pk_mul_f32 v[156:157], v[164:165], v[156:157]
	global_store_dwordx4 v[168:169], v[122:125], off
	global_store_dwordx4 v[168:169], v[156:159], off offset:16
	s_nop 0
	s_nop 0
	s_nop 0
	v_pk_mul_f32 v[118:119], v[118:119], v[170:171] op_sel_hi:[1,0]
	v_pk_mul_f32 v[116:117], v[116:117], v[170:171] op_sel_hi:[1,0]
	v_pk_mul_f32 v[132:133], v[114:115], v[170:171] op_sel_hi:[1,0]
	v_pk_mul_f32 v[120:121], v[120:121], v[170:171] op_sel_hi:[1,0]
	v_lshl_add_u64 v[126:127], v[136:137], 2, s[2:3]
	v_mov_b32_e32 v122, v188
	v_mov_b32_e32 v123, v189
	v_mov_b32_e32 v124, v190
	v_mov_b32_e32 v125, v191
	v_pk_mul_f32 v[114:115], v[122:123], v[116:117]
	v_pk_mul_f32 v[116:117], v[124:125], v[118:119]
	v_mov_b32_e32 v156, v196
	v_mov_b32_e32 v157, v197
	v_mov_b32_e32 v158, v198
	v_mov_b32_e32 v159, v199
	v_pk_mul_f32 v[118:119], v[156:157], v[120:121]
	v_pk_mul_f32 v[120:121], v[158:159], v[132:133]
	global_store_dwordx4 v[168:169], v[114:117], off offset:512
	global_store_dwordx4 v[168:169], v[118:121], off offset:528
	s_nop 0
	s_nop 0
	s_nop 0
	s_nop 0
	s_waitcnt vmcnt(6)
	v_mov_b32_e32 v122, v173
	v_fmamk_f32 v122, v122, 0x3a000000, v153
	v_mul_f32_e32 v123, 0x4f800000, v122
	v_cmp_gt_f32_e32 vcc, s4, v122
	s_nop 1
	v_cndmask_b32_e32 v124, v122, v123, vcc
	v_sqrt_f32_e32 v125, v124
	v_lshl_add_u64 v[122:123], v[154:155], 2, s[8:9]
	v_lshl_add_u64 v[122:123], v[122:123], 0, v[140:141]
	v_add_u32_e32 v126, -1, v125
	v_add_u32_e32 v127, 1, v125
	v_fma_f32 v132, -v126, v125, v124
	v_fma_f32 v133, -v127, v125, v124
	v_cmp_ge_f32_e64 s[0:1], 0, v132
	s_nop 1
	v_cndmask_b32_e64 v125, v125, v126, s[0:1]
	v_cmp_lt_f32_e64 s[0:1], 0, v133
	s_nop 1
	v_cndmask_b32_e64 v125, v125, v127, s[0:1]
	v_mul_f32_e32 v126, 0x37800000, v125
	v_cndmask_b32_e32 v125, v125, v126, vcc
	v_cmp_class_f32_e32 vcc, v124, v152
	s_nop 1
	v_cndmask_b32_e32 v124, v125, v124, vcc
	v_div_scale_f32 v125, s[0:1], v124, v124, 1.0
	v_rcp_f32_e32 v126, v125
	v_div_scale_f32 v127, vcc, 1.0, v124, 1.0
	v_fma_f32 v132, -v125, v126, 1.0
	v_fmac_f32_e32 v126, v132, v126
	v_mul_f32_e32 v132, v127, v126
	v_fma_f32 v133, -v125, v132, v127
	v_fmac_f32_e32 v132, v133, v126
	v_fma_f32 v125, -v125, v132, v127
	v_div_fmas_f32 v125, v125, v126, v132
	v_div_fixup_f32 v124, v125, v124, 1.0
	v_pk_mul_f32 v[126:127], v[130:131], v[124:125] op_sel_hi:[1,0]
	v_pk_mul_f32 v[110:111], v[110:111], v[124:125] op_sel_hi:[1,0]
	v_pk_mul_f32 v[130:131], v[104:105], v[124:125] op_sel_hi:[1,0]
	v_pk_mul_f32 v[132:133], v[106:107], v[124:125] op_sel_hi:[1,0]
	v_mov_b32_e32 v114, v180
	v_mov_b32_e32 v115, v181
	v_mov_b32_e32 v116, v182
	v_mov_b32_e32 v117, v183
	v_pk_mul_f32 v[106:107], v[116:117], v[110:111]
	v_pk_mul_f32 v[104:105], v[114:115], v[126:127]
	v_mov_b32_e32 v118, v184
	v_mov_b32_e32 v119, v185
	v_mov_b32_e32 v120, v186
	v_mov_b32_e32 v121, v187
	v_pk_mul_f32 v[116:117], v[120:121], v[132:133]
	v_pk_mul_f32 v[114:115], v[118:119], v[130:131]
	global_store_dwordx4 v[122:123], v[104:107], off
	global_store_dwordx4 v[122:123], v[114:117], off offset:16
	s_nop 0
	s_nop 0
	s_nop 0
	v_pk_mul_f32 v[102:103], v[102:103], v[124:125] op_sel_hi:[1,0]
	v_pk_mul_f32 v[100:101], v[100:101], v[124:125] op_sel_hi:[1,0]
	v_pk_mul_f32 v[118:119], v[98:99], v[124:125] op_sel_hi:[1,0]
	v_pk_mul_f32 v[120:121], v[96:97], v[124:125] op_sel_hi:[1,0]
	v_lshl_add_u64 v[110:111], v[134:135], 2, s[2:3]
	v_mov_b32_e32 v104, v188
	v_mov_b32_e32 v105, v189
	v_mov_b32_e32 v106, v190
	v_mov_b32_e32 v107, v191
	v_pk_mul_f32 v[96:97], v[104:105], v[100:101]
	v_pk_mul_f32 v[98:99], v[106:107], v[102:103]
	v_mov_b32_e32 v114, v196
	v_mov_b32_e32 v115, v197
	v_mov_b32_e32 v116, v198
	v_mov_b32_e32 v117, v199
	v_pk_mul_f32 v[100:101], v[114:115], v[120:121]
	v_pk_mul_f32 v[102:103], v[116:117], v[118:119]
	global_store_dwordx4 v[122:123], v[96:99], off offset:512
	global_store_dwordx4 v[122:123], v[100:103], off offset:528
	s_nop 0
	s_nop 0
	s_nop 0
	s_nop 0
	s_waitcnt vmcnt(5)
	v_mov_b32_e32 v104, v174
	v_fmamk_f32 v104, v104, 0x3a000000, v153
	v_mul_f32_e32 v105, 0x4f800000, v104
	v_cmp_gt_f32_e32 vcc, s4, v104
	s_nop 1
	v_cndmask_b32_e32 v106, v104, v105, vcc
	v_sqrt_f32_e32 v107, v106
	v_lshl_add_u64 v[104:105], v[150:151], 2, s[8:9]
	v_lshl_add_u64 v[104:105], v[104:105], 0, v[140:141]
	v_add_u32_e32 v110, -1, v107
	v_add_u32_e32 v111, 1, v107
	v_fma_f32 v114, -v110, v107, v106
	v_fma_f32 v115, -v111, v107, v106
	v_cmp_ge_f32_e64 s[0:1], 0, v114
	s_nop 1
	v_cndmask_b32_e64 v107, v107, v110, s[0:1]
	v_cmp_lt_f32_e64 s[0:1], 0, v115
	s_nop 1
	v_cndmask_b32_e64 v107, v107, v111, s[0:1]
	v_mul_f32_e32 v110, 0x37800000, v107
	v_cndmask_b32_e32 v107, v107, v110, vcc
	v_cmp_class_f32_e32 vcc, v106, v152
	s_nop 1
	v_cndmask_b32_e32 v106, v107, v106, vcc
	v_div_scale_f32 v107, s[0:1], v106, v106, 1.0
	v_rcp_f32_e32 v110, v107
	v_div_scale_f32 v111, vcc, 1.0, v106, 1.0
	v_fma_f32 v114, -v107, v110, 1.0
	v_fmac_f32_e32 v110, v114, v110
	v_mul_f32_e32 v114, v111, v110
	v_fma_f32 v115, -v107, v114, v111
	v_fmac_f32_e32 v114, v115, v110
	v_fma_f32 v107, -v107, v114, v111
	v_div_fmas_f32 v107, v107, v110, v114
	v_div_fixup_f32 v106, v107, v106, 1.0
	v_pk_mul_f32 v[92:93], v[92:93], v[106:107] op_sel_hi:[1,0]
	v_pk_mul_f32 v[94:95], v[94:95], v[106:107] op_sel_hi:[1,0]
	v_pk_mul_f32 v[110:111], v[88:89], v[106:107] op_sel_hi:[1,0]
	v_pk_mul_f32 v[114:115], v[90:91], v[106:107] op_sel_hi:[1,0]
	v_mov_b32_e32 v96, v180
	v_mov_b32_e32 v97, v181
	v_mov_b32_e32 v98, v182
	v_mov_b32_e32 v99, v183
	v_pk_mul_f32 v[90:91], v[98:99], v[94:95]
	v_pk_mul_f32 v[88:89], v[96:97], v[92:93]
	v_mov_b32_e32 v100, v184
	v_mov_b32_e32 v101, v185
	v_mov_b32_e32 v102, v186
	v_mov_b32_e32 v103, v187
	v_pk_mul_f32 v[94:95], v[102:103], v[114:115]
	v_pk_mul_f32 v[92:93], v[100:101], v[110:111]
	global_store_dwordx4 v[104:105], v[88:91], off
	global_store_dwordx4 v[104:105], v[92:95], off offset:16
	s_nop 0
	s_nop 0
	s_nop 0
	v_pk_mul_f32 v[86:87], v[86:87], v[106:107] op_sel_hi:[1,0]
	v_pk_mul_f32 v[84:85], v[84:85], v[106:107] op_sel_hi:[1,0]
	v_pk_mul_f32 v[98:99], v[82:83], v[106:107] op_sel_hi:[1,0]
	v_pk_mul_f32 v[100:101], v[80:81], v[106:107] op_sel_hi:[1,0]
	v_lshl_add_u64 v[96:97], v[108:109], 2, s[2:3]
	v_mov_b32_e32 v88, v188
	v_mov_b32_e32 v89, v189
	v_mov_b32_e32 v90, v190
	v_mov_b32_e32 v91, v191
	v_pk_mul_f32 v[80:81], v[88:89], v[84:85]
	v_pk_mul_f32 v[82:83], v[90:91], v[86:87]
	v_mov_b32_e32 v92, v196
	v_mov_b32_e32 v93, v197
	v_mov_b32_e32 v94, v198
	v_mov_b32_e32 v95, v199
	v_pk_mul_f32 v[84:85], v[92:93], v[100:101]
	v_pk_mul_f32 v[86:87], v[94:95], v[98:99]
	global_store_dwordx4 v[104:105], v[80:83], off offset:512
	global_store_dwordx4 v[104:105], v[84:87], off offset:528
	s_nop 0
	s_nop 0
	s_nop 0
	s_nop 0
	s_waitcnt vmcnt(4)
	v_mov_b32_e32 v88, v175
	v_fmamk_f32 v88, v88, 0x3a000000, v153
	v_mul_f32_e32 v89, 0x4f800000, v88
	v_cmp_gt_f32_e32 vcc, s4, v88
	s_nop 1
	v_cndmask_b32_e32 v90, v88, v89, vcc
	v_sqrt_f32_e32 v91, v90
	v_lshl_add_u64 v[88:89], v[148:149], 2, s[8:9]
	v_lshl_add_u64 v[88:89], v[88:89], 0, v[140:141]
	v_add_u32_e32 v92, -1, v91
	v_add_u32_e32 v93, 1, v91
	v_fma_f32 v94, -v92, v91, v90
	v_fma_f32 v95, -v93, v91, v90
	v_cmp_ge_f32_e64 s[0:1], 0, v94
	s_nop 1
	v_cndmask_b32_e64 v91, v91, v92, s[0:1]
	v_cmp_lt_f32_e64 s[0:1], 0, v95
	s_nop 1
	v_cndmask_b32_e64 v91, v91, v93, s[0:1]
	v_mul_f32_e32 v92, 0x37800000, v91
	v_cndmask_b32_e32 v91, v91, v92, vcc
	v_cmp_class_f32_e32 vcc, v90, v152
	s_nop 1
	v_cndmask_b32_e32 v90, v91, v90, vcc
	v_div_scale_f32 v91, s[0:1], v90, v90, 1.0
	v_rcp_f32_e32 v92, v91
	v_div_scale_f32 v93, vcc, 1.0, v90, 1.0
	v_fma_f32 v94, -v91, v92, 1.0
	v_fmac_f32_e32 v92, v94, v92
	v_mul_f32_e32 v94, v93, v92
	v_fma_f32 v95, -v91, v94, v93
	v_fmac_f32_e32 v94, v95, v92
	v_fma_f32 v91, -v91, v94, v93
	v_div_fmas_f32 v91, v91, v92, v94
	v_div_fixup_f32 v90, v91, v90, 1.0
	v_pk_mul_f32 v[76:77], v[76:77], v[90:91] op_sel_hi:[1,0]
	v_pk_mul_f32 v[78:79], v[78:79], v[90:91] op_sel_hi:[1,0]
	v_pk_mul_f32 v[92:93], v[72:73], v[90:91] op_sel_hi:[1,0]
	v_pk_mul_f32 v[94:95], v[74:75], v[90:91] op_sel_hi:[1,0]
	v_mov_b32_e32 v80, v180
	v_mov_b32_e32 v81, v181
	v_mov_b32_e32 v82, v182
	v_mov_b32_e32 v83, v183
	v_pk_mul_f32 v[74:75], v[82:83], v[78:79]
	v_pk_mul_f32 v[72:73], v[80:81], v[76:77]
	v_mov_b32_e32 v84, v184
	v_mov_b32_e32 v85, v185
	v_mov_b32_e32 v86, v186
	v_mov_b32_e32 v87, v187
	v_pk_mul_f32 v[78:79], v[86:87], v[94:95]
	v_pk_mul_f32 v[76:77], v[84:85], v[92:93]
	global_store_dwordx4 v[88:89], v[72:75], off
	global_store_dwordx4 v[88:89], v[76:79], off offset:16
	s_nop 0
	s_nop 0
	s_nop 0
	v_pk_mul_f32 v[70:71], v[70:71], v[90:91] op_sel_hi:[1,0]
	v_pk_mul_f32 v[68:69], v[68:69], v[90:91] op_sel_hi:[1,0]
	v_pk_mul_f32 v[80:81], v[66:67], v[90:91] op_sel_hi:[1,0]
	v_pk_mul_f32 v[82:83], v[64:65], v[90:91] op_sel_hi:[1,0]
	v_mov_b32_e32 v72, v188
	v_mov_b32_e32 v73, v189
	v_mov_b32_e32 v74, v190
	v_mov_b32_e32 v75, v191
	v_pk_mul_f32 v[64:65], v[72:73], v[68:69]
	v_pk_mul_f32 v[66:67], v[74:75], v[70:71]
	v_mov_b32_e32 v76, v196
	v_mov_b32_e32 v77, v197
	v_mov_b32_e32 v78, v198
	v_mov_b32_e32 v79, v199
	v_pk_mul_f32 v[68:69], v[76:77], v[82:83]
	v_pk_mul_f32 v[70:71], v[78:79], v[80:81]
	global_store_dwordx4 v[88:89], v[64:67], off offset:512
	global_store_dwordx4 v[88:89], v[68:71], off offset:528
	s_nop 0
	s_nop 0
	s_nop 0
	s_nop 0
	s_waitcnt vmcnt(3)
	v_mov_b32_e32 v72, v176
	v_fmamk_f32 v72, v72, 0x3a000000, v153
	v_mul_f32_e32 v73, 0x4f800000, v72
	v_cmp_gt_f32_e32 vcc, s4, v72
	s_nop 1
	v_cndmask_b32_e32 v74, v72, v73, vcc
	v_sqrt_f32_e32 v75, v74
	v_lshl_add_u64 v[72:73], v[146:147], 2, s[8:9]
	v_lshl_add_u64 v[72:73], v[72:73], 0, v[140:141]
	v_add_u32_e32 v76, -1, v75
	v_add_u32_e32 v77, 1, v75
	v_fma_f32 v78, -v76, v75, v74
	v_fma_f32 v79, -v77, v75, v74
	v_cmp_ge_f32_e64 s[0:1], 0, v78
	s_nop 1
	v_cndmask_b32_e64 v75, v75, v76, s[0:1]
	v_cmp_lt_f32_e64 s[0:1], 0, v79
	s_nop 1
	v_cndmask_b32_e64 v75, v75, v77, s[0:1]
	v_mul_f32_e32 v76, 0x37800000, v75
	v_cndmask_b32_e32 v75, v75, v76, vcc
	v_cmp_class_f32_e32 vcc, v74, v152
	s_nop 1
	v_cndmask_b32_e32 v74, v75, v74, vcc
	v_div_scale_f32 v75, s[0:1], v74, v74, 1.0
	v_rcp_f32_e32 v76, v75
	v_div_scale_f32 v77, vcc, 1.0, v74, 1.0
	v_fma_f32 v78, -v75, v76, 1.0
	v_fmac_f32_e32 v76, v78, v76
	v_mul_f32_e32 v78, v77, v76
	v_fma_f32 v79, -v75, v78, v77
	v_fmac_f32_e32 v78, v79, v76
	v_fma_f32 v75, -v75, v78, v77
	v_div_fmas_f32 v75, v75, v76, v78
	v_div_fixup_f32 v74, v75, v74, 1.0
	v_pk_mul_f32 v[60:61], v[60:61], v[74:75] op_sel_hi:[1,0]
	v_pk_mul_f32 v[62:63], v[62:63], v[74:75] op_sel_hi:[1,0]
	v_pk_mul_f32 v[76:77], v[56:57], v[74:75] op_sel_hi:[1,0]
	v_pk_mul_f32 v[78:79], v[58:59], v[74:75] op_sel_hi:[1,0]
	v_mov_b32_e32 v64, v180
	v_mov_b32_e32 v65, v181
	v_mov_b32_e32 v66, v182
	v_mov_b32_e32 v67, v183
	v_pk_mul_f32 v[58:59], v[66:67], v[62:63]
	v_pk_mul_f32 v[56:57], v[64:65], v[60:61]
	v_mov_b32_e32 v68, v184
	v_mov_b32_e32 v69, v185
	v_mov_b32_e32 v70, v186
	v_mov_b32_e32 v71, v187
	v_pk_mul_f32 v[62:63], v[70:71], v[78:79]
	v_pk_mul_f32 v[60:61], v[68:69], v[76:77]
	global_store_dwordx4 v[72:73], v[56:59], off
	global_store_dwordx4 v[72:73], v[60:63], off offset:16
	s_nop 0
	s_nop 0
	s_nop 0
	v_pk_mul_f32 v[54:55], v[54:55], v[74:75] op_sel_hi:[1,0]
	v_pk_mul_f32 v[52:53], v[52:53], v[74:75] op_sel_hi:[1,0]
	v_pk_mul_f32 v[64:65], v[50:51], v[74:75] op_sel_hi:[1,0]
	v_pk_mul_f32 v[66:67], v[48:49], v[74:75] op_sel_hi:[1,0]
	v_mov_b32_e32 v56, v188
	v_mov_b32_e32 v57, v189
	v_mov_b32_e32 v58, v190
	v_mov_b32_e32 v59, v191
	v_pk_mul_f32 v[48:49], v[56:57], v[52:53]
	v_pk_mul_f32 v[50:51], v[58:59], v[54:55]
	v_mov_b32_e32 v60, v196
	v_mov_b32_e32 v61, v197
	v_mov_b32_e32 v62, v198
	v_mov_b32_e32 v63, v199
	v_pk_mul_f32 v[52:53], v[60:61], v[66:67]
	v_pk_mul_f32 v[54:55], v[62:63], v[64:65]
	global_store_dwordx4 v[72:73], v[48:51], off offset:512
	global_store_dwordx4 v[72:73], v[52:55], off offset:528
	s_nop 0
	s_nop 0
	s_nop 0
	s_nop 0
	s_waitcnt vmcnt(2)
	v_mov_b32_e32 v56, v177
	v_fmamk_f32 v56, v56, 0x3a000000, v153
	v_mul_f32_e32 v57, 0x4f800000, v56
	v_cmp_gt_f32_e32 vcc, s4, v56
	s_nop 1
	v_cndmask_b32_e32 v58, v56, v57, vcc
	v_sqrt_f32_e32 v59, v58
	v_lshl_add_u64 v[56:57], v[144:145], 2, s[8:9]
	v_lshl_add_u64 v[56:57], v[56:57], 0, v[140:141]
	v_add_u32_e32 v60, -1, v59
	v_add_u32_e32 v61, 1, v59
	v_fma_f32 v62, -v60, v59, v58
	v_fma_f32 v63, -v61, v59, v58
	v_cmp_ge_f32_e64 s[0:1], 0, v62
	s_nop 1
	v_cndmask_b32_e64 v59, v59, v60, s[0:1]
	v_cmp_lt_f32_e64 s[0:1], 0, v63
	s_nop 1
	v_cndmask_b32_e64 v59, v59, v61, s[0:1]
	v_mul_f32_e32 v60, 0x37800000, v59
	v_cndmask_b32_e32 v59, v59, v60, vcc
	v_cmp_class_f32_e32 vcc, v58, v152
	s_nop 1
	v_cndmask_b32_e32 v58, v59, v58, vcc
	v_div_scale_f32 v59, s[0:1], v58, v58, 1.0
	v_rcp_f32_e32 v60, v59
	v_div_scale_f32 v61, vcc, 1.0, v58, 1.0
	v_fma_f32 v62, -v59, v60, 1.0
	v_fmac_f32_e32 v60, v62, v60
	v_mul_f32_e32 v62, v61, v60
	v_fma_f32 v63, -v59, v62, v61
	v_fmac_f32_e32 v62, v63, v60
	v_fma_f32 v59, -v59, v62, v61
	v_div_fmas_f32 v59, v59, v60, v62
	v_div_fixup_f32 v58, v59, v58, 1.0
	v_pk_mul_f32 v[44:45], v[44:45], v[58:59] op_sel_hi:[1,0]
	v_pk_mul_f32 v[46:47], v[46:47], v[58:59] op_sel_hi:[1,0]
	v_pk_mul_f32 v[60:61], v[40:41], v[58:59] op_sel_hi:[1,0]
	v_pk_mul_f32 v[62:63], v[42:43], v[58:59] op_sel_hi:[1,0]
	v_mov_b32_e32 v48, v180
	v_mov_b32_e32 v49, v181
	v_mov_b32_e32 v50, v182
	v_mov_b32_e32 v51, v183
	v_pk_mul_f32 v[42:43], v[50:51], v[46:47]
	v_pk_mul_f32 v[40:41], v[48:49], v[44:45]
	v_mov_b32_e32 v52, v184
	v_mov_b32_e32 v53, v185
	v_mov_b32_e32 v54, v186
	v_mov_b32_e32 v55, v187
	v_pk_mul_f32 v[46:47], v[54:55], v[62:63]
	v_pk_mul_f32 v[44:45], v[52:53], v[60:61]
	global_store_dwordx4 v[56:57], v[40:43], off
	global_store_dwordx4 v[56:57], v[44:47], off offset:16
	s_nop 0
	s_nop 0
	s_nop 0
	v_pk_mul_f32 v[38:39], v[38:39], v[58:59] op_sel_hi:[1,0]
	v_pk_mul_f32 v[36:37], v[36:37], v[58:59] op_sel_hi:[1,0]
	v_pk_mul_f32 v[48:49], v[34:35], v[58:59] op_sel_hi:[1,0]
	v_pk_mul_f32 v[50:51], v[32:33], v[58:59] op_sel_hi:[1,0]
	v_mov_b32_e32 v40, v188
	v_mov_b32_e32 v41, v189
	v_mov_b32_e32 v42, v190
	v_mov_b32_e32 v43, v191
	v_pk_mul_f32 v[32:33], v[40:41], v[36:37]
	v_pk_mul_f32 v[34:35], v[42:43], v[38:39]
	v_mov_b32_e32 v44, v196
	v_mov_b32_e32 v45, v197
	v_mov_b32_e32 v46, v198
	v_mov_b32_e32 v47, v199
	v_pk_mul_f32 v[36:37], v[44:45], v[50:51]
	v_pk_mul_f32 v[38:39], v[46:47], v[48:49]
	global_store_dwordx4 v[56:57], v[32:35], off offset:512
	global_store_dwordx4 v[56:57], v[36:39], off offset:528
	s_nop 0
	s_nop 0
	s_nop 0
	s_nop 0
	s_waitcnt vmcnt(1)
	v_mov_b32_e32 v40, v178
	v_fmamk_f32 v40, v40, 0x3a000000, v153
	v_mul_f32_e32 v41, 0x4f800000, v40
	v_cmp_gt_f32_e32 vcc, s4, v40
	s_nop 1
	v_cndmask_b32_e32 v42, v40, v41, vcc
	v_sqrt_f32_e32 v43, v42
	v_lshl_add_u64 v[40:41], v[142:143], 2, s[8:9]
	v_lshl_add_u64 v[40:41], v[40:41], 0, v[140:141]
	v_add_u32_e32 v44, -1, v43
	v_add_u32_e32 v45, 1, v43
	v_fma_f32 v46, -v44, v43, v42
	v_fma_f32 v47, -v45, v43, v42
	v_cmp_ge_f32_e64 s[0:1], 0, v46
	s_nop 1
	v_cndmask_b32_e64 v43, v43, v44, s[0:1]
	v_cmp_lt_f32_e64 s[0:1], 0, v47
	s_nop 1
	v_cndmask_b32_e64 v43, v43, v45, s[0:1]
	v_mul_f32_e32 v44, 0x37800000, v43
	v_cndmask_b32_e32 v43, v43, v44, vcc
	v_cmp_class_f32_e32 vcc, v42, v152
	s_nop 1
	v_cndmask_b32_e32 v42, v43, v42, vcc
	v_div_scale_f32 v43, s[0:1], v42, v42, 1.0
	v_rcp_f32_e32 v44, v43
	v_div_scale_f32 v45, vcc, 1.0, v42, 1.0
	v_fma_f32 v46, -v43, v44, 1.0
	v_fmac_f32_e32 v44, v46, v44
	v_mul_f32_e32 v46, v45, v44
	v_fma_f32 v47, -v43, v46, v45
	v_fmac_f32_e32 v46, v47, v44
	v_fma_f32 v43, -v43, v46, v45
	v_div_fmas_f32 v43, v43, v44, v46
	v_div_fixup_f32 v42, v43, v42, 1.0
	v_pk_mul_f32 v[28:29], v[28:29], v[42:43] op_sel_hi:[1,0]
	v_pk_mul_f32 v[30:31], v[30:31], v[42:43] op_sel_hi:[1,0]
	v_pk_mul_f32 v[44:45], v[24:25], v[42:43] op_sel_hi:[1,0]
	v_pk_mul_f32 v[46:47], v[26:27], v[42:43] op_sel_hi:[1,0]
	v_mov_b32_e32 v32, v180
	v_mov_b32_e32 v33, v181
	v_mov_b32_e32 v34, v182
	v_mov_b32_e32 v35, v183
	v_pk_mul_f32 v[26:27], v[34:35], v[30:31]
	v_pk_mul_f32 v[24:25], v[32:33], v[28:29]
	v_mov_b32_e32 v36, v184
	v_mov_b32_e32 v37, v185
	v_mov_b32_e32 v38, v186
	v_mov_b32_e32 v39, v187
	v_pk_mul_f32 v[30:31], v[38:39], v[46:47]
	v_pk_mul_f32 v[28:29], v[36:37], v[44:45]
	global_store_dwordx4 v[40:41], v[24:27], off
	global_store_dwordx4 v[40:41], v[28:31], off offset:16
	s_nop 0
	s_nop 0
	s_nop 0
	v_pk_mul_f32 v[22:23], v[22:23], v[42:43] op_sel_hi:[1,0]
	v_pk_mul_f32 v[20:21], v[20:21], v[42:43] op_sel_hi:[1,0]
	v_pk_mul_f32 v[32:33], v[18:19], v[42:43] op_sel_hi:[1,0]
	v_pk_mul_f32 v[34:35], v[16:17], v[42:43] op_sel_hi:[1,0]
	v_mov_b32_e32 v24, v188
	v_mov_b32_e32 v25, v189
	v_mov_b32_e32 v26, v190
	v_mov_b32_e32 v27, v191
	v_pk_mul_f32 v[16:17], v[24:25], v[20:21]
	v_pk_mul_f32 v[18:19], v[26:27], v[22:23]
	v_mov_b32_e32 v28, v196
	v_mov_b32_e32 v29, v197
	v_mov_b32_e32 v30, v198
	v_mov_b32_e32 v31, v199
	v_pk_mul_f32 v[20:21], v[28:29], v[34:35]
	v_pk_mul_f32 v[22:23], v[30:31], v[32:33]
	global_store_dwordx4 v[40:41], v[16:19], off offset:512
	global_store_dwordx4 v[40:41], v[20:23], off offset:528
	s_nop 0
	s_nop 0
	s_nop 0
	s_nop 0
	s_waitcnt vmcnt(0)
	v_mov_b32_e32 v24, v179
	v_fmac_f32_e32 v153, 0x3a000000, v24
	v_mul_f32_e32 v24, 0x4f800000, v153
	v_cmp_gt_f32_e32 vcc, s4, v153
	s_nop 1
	v_cndmask_b32_e32 v26, v153, v24, vcc
	v_sqrt_f32_e32 v27, v26
	v_lshl_add_u64 v[24:25], v[138:139], 2, s[8:9]
	v_lshl_add_u64 v[24:25], v[24:25], 0, v[140:141]
	v_add_u32_e32 v28, -1, v27
	v_add_u32_e32 v29, 1, v27
	v_fma_f32 v30, -v28, v27, v26
	v_fma_f32 v31, -v29, v27, v26
	v_cmp_ge_f32_e64 s[0:1], 0, v30
	s_nop 1
	v_cndmask_b32_e64 v27, v27, v28, s[0:1]
	v_cmp_lt_f32_e64 s[0:1], 0, v31
	s_nop 1
	v_cndmask_b32_e64 v27, v27, v29, s[0:1]
	v_mul_f32_e32 v28, 0x37800000, v27
	v_cndmask_b32_e32 v27, v27, v28, vcc
	v_cmp_class_f32_e32 vcc, v26, v152
	s_nop 1
	v_cndmask_b32_e32 v26, v27, v26, vcc
	v_div_scale_f32 v27, s[0:1], v26, v26, 1.0
	v_rcp_f32_e32 v28, v27
	v_div_scale_f32 v29, vcc, 1.0, v26, 1.0
	v_fma_f32 v30, -v27, v28, 1.0
	v_fmac_f32_e32 v28, v30, v28
	v_mul_f32_e32 v30, v29, v28
	v_fma_f32 v31, -v27, v30, v29
	v_fmac_f32_e32 v30, v31, v28
	v_fma_f32 v27, -v27, v30, v29
	v_div_fmas_f32 v27, v27, v28, v30
	v_div_fixup_f32 v26, v27, v26, 1.0
	v_pk_mul_f32 v[12:13], v[12:13], v[26:27] op_sel_hi:[1,0]
	v_pk_mul_f32 v[14:15], v[14:15], v[26:27] op_sel_hi:[1,0]
	v_pk_mul_f32 v[28:29], v[8:9], v[26:27] op_sel_hi:[1,0]
	v_pk_mul_f32 v[30:31], v[10:11], v[26:27] op_sel_hi:[1,0]
	v_mov_b32_e32 v16, v180
	v_mov_b32_e32 v17, v181
	v_mov_b32_e32 v18, v182
	v_mov_b32_e32 v19, v183
	v_pk_mul_f32 v[10:11], v[18:19], v[14:15]
	v_pk_mul_f32 v[8:9], v[16:17], v[12:13]
	v_mov_b32_e32 v20, v184
	v_mov_b32_e32 v21, v185
	v_mov_b32_e32 v22, v186
	v_mov_b32_e32 v23, v187
	v_pk_mul_f32 v[14:15], v[22:23], v[30:31]
	v_pk_mul_f32 v[12:13], v[20:21], v[28:29]
	global_store_dwordx4 v[24:25], v[8:11], off
	global_store_dwordx4 v[24:25], v[12:15], off offset:16
	s_nop 0
	s_nop 0
	s_nop 0
	v_pk_mul_f32 v[6:7], v[6:7], v[26:27] op_sel_hi:[1,0]
	v_pk_mul_f32 v[4:5], v[4:5], v[26:27] op_sel_hi:[1,0]
	v_pk_mul_f32 v[16:17], v[2:3], v[26:27] op_sel_hi:[1,0]
	v_pk_mul_f32 v[18:19], v[0:1], v[26:27] op_sel_hi:[1,0]
	v_mov_b32_e32 v8, v188
	v_mov_b32_e32 v9, v189
	v_mov_b32_e32 v10, v190
	v_mov_b32_e32 v11, v191
	v_pk_mul_f32 v[0:1], v[8:9], v[4:5]
	v_pk_mul_f32 v[2:3], v[10:11], v[6:7]
	v_mov_b32_e32 v12, v196
	v_mov_b32_e32 v13, v197
	v_mov_b32_e32 v14, v198
	v_mov_b32_e32 v15, v199
	v_pk_mul_f32 v[4:5], v[12:13], v[18:19]
	v_pk_mul_f32 v[6:7], v[14:15], v[16:17]
	global_store_dwordx4 v[24:25], v[0:3], off offset:512
	global_store_dwordx4 v[24:25], v[4:7], off offset:528
	s_endpgm
